# v22 plus non-temporal (nt) policy on the once-read f32 weight loads of the conversion phase
# speedup vs baseline: 1.0076x; 1.0028x over previous
; __device__ __forceinline__ void cvt_item(gfp W, int N, bf16* WT, int Kd, int k0, int n0, int drow0, LAS float* scr, int lane, gfp gk) {
; #pragma unroll 8
;     for (int i = 0; i < 32; ++i) { const int kk = 2 * i + (lane >> 5); scr[kk * 33 + (lane & 31)] = W[(size_t)(k0 + kk) * N + n0 + (lane & 31)]; }
.LBB0_123:
	v_mov_b32_e32 v103, v1
	s_lshl_b32 s30, s25, 1
	s_lshl_b32 s27, s23, 1
	v_or_b32_e32 v136, s30, v10
	s_add_i32 s33, s30, 4
	s_add_i32 s31, s27, 4
	s_add_i32 s34, s27, 8
	s_add_i32 s35, s30, 8
	v_add_u32_e32 v102, s0, v136
	v_or_b32_e32 v127, s33, v10
	v_or_b32_e32 v101, s27, v11
	s_add_i32 s36, s27, 12
	s_add_i32 s37, s30, 12
	s_add_i32 s38, s27, 16
	s_add_i32 s40, s27, 20
	s_add_i32 s42, s27, 24
	s_add_i32 s27, s27, 28
	v_or_b32_e32 v126, s31, v11
	v_or_b32_e32 v128, s34, v11
	v_or_b32_e32 v129, s35, v10
	v_lshlrev_b64 v[120:121], 13, v[102:103]
	v_add_u32_e32 v102, s0, v127
	v_mov_b32_e32 v105, v103
	v_mov_b32_e32 v107, v103
	v_mov_b32_e32 v109, v103
	s_add_i32 s39, s30, 16
	v_add_u32_e32 v104, s22, v101
	v_or_b32_e32 v130, s36, v11
	v_or_b32_e32 v131, s37, v10
	v_or_b32_e32 v132, s38, v11
	v_or_b32_e32 v134, s40, v11
	v_or_b32_e32 v137, s42, v11
	v_or_b32_e32 v139, s27, v11
	v_add_u32_e32 v106, s22, v126
	v_add_u32_e32 v108, s22, v128
	v_lshlrev_b64 v[122:123], 13, v[102:103]
	v_add_u32_e32 v102, s0, v129
	v_mov_b32_e32 v111, v103
	v_mov_b32_e32 v113, v103
	v_mov_b32_e32 v115, v103
	v_mov_b32_e32 v117, v103
	v_mov_b32_e32 v119, v103
	s_add_i32 s41, s30, 20
	v_or_b32_e32 v133, s39, v10
	v_lshlrev_b64 v[104:105], 13, v[104:105]
	v_add_u32_e32 v110, s22, v130
	v_add_u32_e32 v112, s22, v132
	v_add_u32_e32 v114, s22, v134
	v_add_u32_e32 v116, s22, v137
	v_add_u32_e32 v118, s22, v139
	v_lshl_add_u64 v[120:121], v[2:3], 0, v[120:121]
	v_lshlrev_b64 v[106:107], 13, v[106:107]
	v_lshlrev_b64 v[108:109], 13, v[108:109]
	v_lshlrev_b64 v[124:125], 13, v[102:103]
	v_add_u32_e32 v102, s0, v131
	s_add_i32 s43, s30, 24
	v_or_b32_e32 v135, s41, v10
	v_lshl_add_u64 v[104:105], v[2:3], 0, v[104:105]
	v_lshlrev_b64 v[110:111], 13, v[110:111]
	v_lshlrev_b64 v[112:113], 13, v[112:113]
	v_lshlrev_b64 v[114:115], 13, v[114:115]
	v_lshlrev_b64 v[116:117], 13, v[116:117]
	v_lshlrev_b64 v[118:119], 13, v[118:119]
	v_lshl_add_u64 v[122:123], v[2:3], 0, v[122:123]
	v_lshl_add_u64 v[106:107], v[2:3], 0, v[106:107]
	v_lshl_add_u64 v[108:109], v[2:3], 0, v[108:109]
	global_load_dword v141, v[120:121], off nt
	global_load_dword v142, v[104:105], off nt
	v_lshlrev_b64 v[120:121], 13, v[102:103]
	v_add_u32_e32 v102, s0, v133
	s_add_i32 s30, s30, 28
	v_or_b32_e32 v138, s43, v10
	v_lshl_add_u64 v[110:111], v[2:3], 0, v[110:111]
	v_lshl_add_u64 v[112:113], v[2:3], 0, v[112:113]
	v_lshl_add_u64 v[114:115], v[2:3], 0, v[114:115]
	v_lshl_add_u64 v[116:117], v[2:3], 0, v[116:117]
	v_lshl_add_u64 v[118:119], v[2:3], 0, v[118:119]
	global_load_dword v143, v[122:123], off nt
	global_load_dword v144, v[106:107], off nt
	global_load_dword v145, v[108:109], off nt
	global_load_dword v146, v[110:111], off nt
	global_load_dword v147, v[112:113], off nt
	global_load_dword v148, v[114:115], off nt
	global_load_dword v149, v[116:117], off nt
	global_load_dword v150, v[118:119], off nt
	v_lshl_add_u64 v[106:107], v[2:3], 0, v[120:121]
	v_lshlrev_b64 v[108:109], 13, v[102:103]
	v_add_u32_e32 v102, s0, v135
	v_or_b32_e32 v140, s30, v10
	v_lshl_add_u64 v[104:105], v[2:3], 0, v[124:125]
	global_load_dword v151, v[106:107], off nt
	global_load_dword v152, v[104:105], off nt
	v_lshlrev_b64 v[106:107], 13, v[102:103]
	v_add_u32_e32 v102, s0, v138
	v_lshl_add_u64 v[104:105], v[2:3], 0, v[108:109]
	v_lshlrev_b64 v[108:109], 13, v[102:103]
	v_add_u32_e32 v102, s0, v140
	v_lshlrev_b64 v[110:111], 13, v[102:103]
	v_lshl_add_u64 v[110:111], v[2:3], 0, v[110:111]
	v_lshl_add_u64 v[106:107], v[2:3], 0, v[106:107]
	v_lshl_add_u64 v[108:109], v[2:3], 0, v[108:109]
	global_load_dword v102, v[110:111], off nt
	global_load_dword v153, v[108:109], off nt
	global_load_dword v154, v[106:107], off nt
	global_load_dword v155, v[104:105], off nt
	s_add_i32 s25, s25, 16
	s_add_i32 s23, s23, 16
	s_add_i32 s26, s26, -16
	s_cmp_lg_u32 s26, 0
	s_lshl_b32 s30, s25, 1
	s_lshl_b32 s27, s23, 1
	v_or_b32_e32 v45, s30, v10
	s_add_i32 s33, s30, 4
	s_add_i32 s31, s27, 4
	s_add_i32 s34, s27, 8
	s_add_i32 s35, s30, 8
	v_add_u32_e32 v0, s0, v45
	v_or_b32_e32 v63, s33, v10
	v_or_b32_e32 v39, s27, v11
	s_add_i32 s36, s27, 12
	s_add_i32 s37, s30, 12
	s_add_i32 s38, s27, 16
	s_add_i32 s40, s27, 20
	s_add_i32 s42, s27, 24
	s_add_i32 s27, s27, 28
	v_or_b32_e32 v62, s31, v11
	v_or_b32_e32 v64, s34, v11
	v_or_b32_e32 v65, s35, v10
	v_lshlrev_b64 v[56:57], 13, v[0:1]
	v_add_u32_e32 v0, s0, v63
	v_mov_b32_e32 v5, v1
	v_mov_b32_e32 v7, v1
	v_mov_b32_e32 v9, v1
	s_add_i32 s39, s30, 16
	v_add_u32_e32 v4, s22, v39
	v_or_b32_e32 v66, s36, v11
	v_or_b32_e32 v67, s37, v10
	v_or_b32_e32 v68, s38, v11
	v_or_b32_e32 v70, s40, v11
	v_or_b32_e32 v72, s42, v11
	v_or_b32_e32 v74, s27, v11
	v_add_u32_e32 v6, s22, v62
	v_add_u32_e32 v8, s22, v64
	v_lshlrev_b64 v[58:59], 13, v[0:1]
	v_add_u32_e32 v0, s0, v65
	v_mov_b32_e32 v47, v1
	v_mov_b32_e32 v49, v1
	v_mov_b32_e32 v51, v1
	v_mov_b32_e32 v53, v1
	v_mov_b32_e32 v55, v1
	s_add_i32 s41, s30, 20
	v_or_b32_e32 v69, s39, v10
	v_lshlrev_b64 v[4:5], 13, v[4:5]
	v_add_u32_e32 v46, s22, v66
	v_add_u32_e32 v48, s22, v68
	v_add_u32_e32 v50, s22, v70
	v_add_u32_e32 v52, s22, v72
	v_add_u32_e32 v54, s22, v74
	v_lshl_add_u64 v[56:57], v[2:3], 0, v[56:57]
	v_lshlrev_b64 v[6:7], 13, v[6:7]
	v_lshlrev_b64 v[8:9], 13, v[8:9]
	v_lshlrev_b64 v[60:61], 13, v[0:1]
	v_add_u32_e32 v0, s0, v67
	s_add_i32 s43, s30, 24
	v_or_b32_e32 v71, s41, v10
	v_lshl_add_u64 v[4:5], v[2:3], 0, v[4:5]
	v_lshlrev_b64 v[46:47], 13, v[46:47]
	v_lshlrev_b64 v[48:49], 13, v[48:49]
	v_lshlrev_b64 v[50:51], 13, v[50:51]
	v_lshlrev_b64 v[52:53], 13, v[52:53]
	v_lshlrev_b64 v[54:55], 13, v[54:55]
	v_lshl_add_u64 v[58:59], v[2:3], 0, v[58:59]
; #define GAS __attribute__((address_space(1)))
; #define LAS __attribute__((address_space(3)))
; #define LDS_WAIT() asm volatile("s_waitcnt lgkmcnt(0)" ::: "memory")
; __device__ __forceinline__ unsigned pk2(float lo, float hi) { unsigned r; asm("v_cvt_pk_bf16_f32 %0, %1, %2" : "=v"(r) : "v"(lo), "v"(hi)); return r; }
; __device__ __forceinline__ void cvt_item(gfp W, int N, bf16* WT, int Kd, int k0, int n0, int drow0, LAS float* scr, int lane, gfp gk) {
;     ...
;     for (int i = 0; i < 32; ++i) { const int kk = 2 * i + (lane >> 5); scr[kk * 33 + (lane & 31)] = W[(size_t)(k0 + kk) * N + n0 + (lane & 31)]; }
;     const int c = lane & 7;
;     f32x4 ga = (f32x4){1.f, 1.f, 1.f, 1.f}, gb = ga;
;     if (gk != nullptr) { ga = *(const GAS f32x4*)(gk + k0 + 8 * c); gb = *(const GAS f32x4*)(gk + k0 + 8 * c + 4); }
;     LDS_WAIT(); asm volatile("" ::: "memory");
; #pragma unroll
;     for (int j = 0; j < 4; ++j) { const int n = (lane >> 3) + 8 * j; const LAS float* s = scr + (8 * c) * 33 + n;
;         v4u o; o.x = pk2(s[0 * 33] * ga[0], s[1 * 33] * ga[1]); o.y = pk2(s[2 * 33] * ga[2], s[3 * 33] * ga[3]); o.z = pk2(s[4 * 33] * gb[0], s[5 * 33] * gb[1]); o.w = pk2(s[6 * 33] * gb[2], s[7 * 33] * gb[3]);
;         *(GAS v4u*)(WT + (size_t)(drow0 + n) * Kd + k0 + 8 * c) = o; }
;     LDS_WAIT(); asm volatile("" ::: "memory");
	v_lshl_add_u64 v[6:7], v[2:3], 0, v[6:7]
	v_lshl_add_u64 v[8:9], v[2:3], 0, v[8:9]
	global_load_dword v76, v[56:57], off nt
	global_load_dword v77, v[4:5], off nt
	v_lshlrev_b64 v[56:57], 13, v[0:1]
	v_add_u32_e32 v0, s0, v69
	s_add_i32 s30, s30, 28
	v_or_b32_e32 v73, s43, v10
	v_lshl_add_u64 v[46:47], v[2:3], 0, v[46:47]
	v_lshl_add_u64 v[48:49], v[2:3], 0, v[48:49]
	v_lshl_add_u64 v[50:51], v[2:3], 0, v[50:51]
	v_lshl_add_u64 v[52:53], v[2:3], 0, v[52:53]
	v_lshl_add_u64 v[54:55], v[2:3], 0, v[54:55]
	global_load_dword v78, v[58:59], off nt
	global_load_dword v79, v[6:7], off nt
	global_load_dword v80, v[8:9], off nt
	global_load_dword v81, v[46:47], off nt
	global_load_dword v82, v[48:49], off nt
	global_load_dword v83, v[50:51], off nt
	global_load_dword v84, v[52:53], off nt
	global_load_dword v85, v[54:55], off nt
	v_lshl_add_u64 v[6:7], v[2:3], 0, v[56:57]
	v_lshlrev_b64 v[8:9], 13, v[0:1]
	v_add_u32_e32 v0, s0, v71
	v_or_b32_e32 v75, s30, v10
	v_lshl_add_u64 v[4:5], v[2:3], 0, v[60:61]
	global_load_dword v86, v[6:7], off nt
	global_load_dword v87, v[4:5], off nt
	v_lshlrev_b64 v[6:7], 13, v[0:1]
	v_add_u32_e32 v0, s0, v73
	v_lshl_add_u64 v[4:5], v[2:3], 0, v[8:9]
	v_lshlrev_b64 v[8:9], 13, v[0:1]
	v_add_u32_e32 v0, s0, v75
	v_lshlrev_b64 v[46:47], 13, v[0:1]
	v_lshl_add_u64 v[46:47], v[2:3], 0, v[46:47]
	v_lshl_add_u64 v[6:7], v[2:3], 0, v[6:7]
	v_lshl_add_u64 v[8:9], v[2:3], 0, v[8:9]
	global_load_dword v0, v[46:47], off nt
	global_load_dword v88, v[8:9], off nt
	global_load_dword v89, v[6:7], off nt
	global_load_dword v90, v[4:5], off nt
	v_mad_u64_u32 v[104:105], s[30:31], v136, s81, v[12:13]
	v_mad_u64_u32 v[106:107], s[30:31], v101, s81, v[12:13]
	v_mad_u64_u32 v[108:109], s[30:31], v127, s81, v[12:13]
	v_mad_u64_u32 v[110:111], s[30:31], v126, s81, v[12:13]
	v_mad_u64_u32 v[112:113], s[30:31], v129, s81, v[12:13]
	v_mad_u64_u32 v[114:115], s[30:31], v128, s81, v[12:13]
	v_mad_u64_u32 v[116:117], s[30:31], v131, s81, v[12:13]
	v_mad_u64_u32 v[118:119], s[30:31], v130, s81, v[12:13]
	v_mad_u64_u32 v[120:121], s[30:31], v133, s81, v[12:13]
	v_mad_u64_u32 v[122:123], s[30:31], v132, s81, v[12:13]
	v_mad_u64_u32 v[124:125], s[30:31], v135, s81, v[12:13]
	v_mad_u64_u32 v[126:127], s[30:31], v134, s81, v[12:13]
	v_mad_u64_u32 v[128:129], s[30:31], v138, s81, v[12:13]
	v_mad_u64_u32 v[130:131], s[30:31], v137, s81, v[12:13]
	v_mad_u64_u32 v[132:133], s[30:31], v140, s81, v[12:13]
	v_mad_u64_u32 v[134:135], s[30:31], v139, s81, v[12:13]
	s_waitcnt vmcnt(31)
	ds_write_b32 v104, v141
	s_waitcnt vmcnt(30)
	ds_write_b32 v106, v142
	s_waitcnt vmcnt(29)
	ds_write_b32 v108, v143
	s_waitcnt vmcnt(28)
	ds_write_b32 v110, v144
	s_waitcnt vmcnt(20)
	ds_write_b32 v112, v152
	ds_write_b32 v114, v145
	ds_write_b32 v116, v151
	ds_write_b32 v118, v146
	s_waitcnt vmcnt(16)
	ds_write_b32 v120, v155
	ds_write_b32 v122, v147
	ds_write_b32 v124, v154
	ds_write_b32 v126, v148
	ds_write_b32 v128, v153
	ds_write_b32 v130, v149
	ds_write_b32 v132, v102
	ds_write_b32 v134, v150
	v_mad_u64_u32 v[4:5], s[30:31], v45, s81, v[12:13]
	v_mad_u64_u32 v[6:7], s[30:31], v39, s81, v[12:13]
	v_mad_u64_u32 v[8:9], s[30:31], v63, s81, v[12:13]
	v_mad_u64_u32 v[46:47], s[30:31], v62, s81, v[12:13]
	v_mad_u64_u32 v[48:49], s[30:31], v65, s81, v[12:13]
	v_mad_u64_u32 v[50:51], s[30:31], v64, s81, v[12:13]
	v_mad_u64_u32 v[52:53], s[30:31], v67, s81, v[12:13]
	v_mad_u64_u32 v[54:55], s[30:31], v66, s81, v[12:13]
	v_mad_u64_u32 v[56:57], s[30:31], v69, s81, v[12:13]
	v_mad_u64_u32 v[58:59], s[30:31], v68, s81, v[12:13]
	v_mad_u64_u32 v[60:61], s[30:31], v71, s81, v[12:13]
	v_mad_u64_u32 v[62:63], s[30:31], v70, s81, v[12:13]
	v_mad_u64_u32 v[64:65], s[30:31], v73, s81, v[12:13]
	v_mad_u64_u32 v[66:67], s[30:31], v72, s81, v[12:13]
	v_mad_u64_u32 v[68:69], s[30:31], v75, s81, v[12:13]
	v_mad_u64_u32 v[70:71], s[30:31], v74, s81, v[12:13]
	s_waitcnt vmcnt(15)
	ds_write_b32 v4, v76
	s_waitcnt vmcnt(14)
	ds_write_b32 v6, v77
	s_waitcnt vmcnt(13)
	ds_write_b32 v8, v78
	s_waitcnt vmcnt(12)
	ds_write_b32 v46, v79
	s_waitcnt vmcnt(4)
	ds_write_b32 v48, v87
	ds_write_b32 v50, v80
	ds_write_b32 v52, v86
	ds_write_b32 v54, v81
	s_waitcnt vmcnt(0)
	ds_write_b32 v56, v90
	ds_write_b32 v58, v82
	ds_write_b32 v60, v89
	ds_write_b32 v62, v83
	ds_write_b32 v64, v88
	ds_write_b32 v66, v84
	ds_write_b32 v68, v0
	ds_write_b32 v70, v85
	s_add_i32 s25, s25, 16
	s_add_i32 s23, s23, 16
	s_add_i32 s26, s26, -16
	s_cmp_lg_u32 s26, 0
	s_waitcnt lgkmcnt(0)
	ds_read2_b32 v[6:7], v41 offset0:33 offset1:41
	ds_read2_b32 v[8:9], v41 offset1:8
	ds_read2_b32 v[46:47], v41 offset0:66 offset1:74
	ds_read2_b32 v[48:49], v41 offset0:99 offset1:107
	ds_read2_b32 v[50:51], v41 offset0:132 offset1:140
	ds_read2_b32 v[52:53], v41 offset0:165 offset1:173
	ds_read2_b32 v[54:55], v41 offset0:198 offset1:206
	ds_read2_b32 v[56:57], v41 offset0:231 offset1:239
	s_lshl_b32 s0, s0, 1
	v_or_b32_e32 v0, s24, v40
	v_lshl_add_u64 v[58:59], v[16:17], 0, s[0:1]
	v_lshlrev_b32_e32 v0, 12, v0
	v_lshl_add_u64 v[60:61], v[58:59], 0, v[0:1]
	s_waitcnt lgkmcnt(6)
	v_cvt_pk_bf16_f32 v2, v8, v6
	s_waitcnt lgkmcnt(4)
	v_cvt_pk_bf16_f32 v3, v46, v48
	s_waitcnt lgkmcnt(2)
	v_cvt_pk_bf16_f32 v4, v50, v52
	s_waitcnt lgkmcnt(0)
	v_cvt_pk_bf16_f32 v5, v54, v56
	global_store_dwordx4 v[60:61], v[2:5], off
	v_or_b32_e32 v0, s24, v42
	v_lshlrev_b32_e32 v0, 12, v0
	v_cvt_pk_bf16_f32 v2, v9, v7
	v_cvt_pk_bf16_f32 v3, v47, v49
	v_cvt_pk_bf16_f32 v4, v51, v53
	v_cvt_pk_bf16_f32 v5, v55, v57
	ds_read2_b32 v[8:9], v41 offset0:16 offset1:24
	ds_read2_b32 v[46:47], v41 offset0:49 offset1:57
	ds_read2_b32 v[48:49], v41 offset0:82 offset1:90
	ds_read2_b32 v[50:51], v41 offset0:115 offset1:123
	ds_read2_b32 v[52:53], v41 offset0:148 offset1:156
	ds_read2_b32 v[54:55], v41 offset0:181 offset1:189
	ds_read2_b32 v[56:57], v41 offset0:214 offset1:222
	ds_read2_b32 v[60:61], v41 offset0:247 offset1:255
	v_lshl_add_u64 v[6:7], v[58:59], 0, v[0:1]
	v_or_b32_e32 v0, s24, v43
	v_lshlrev_b32_e32 v0, 12, v0
	global_store_dwordx4 v[6:7], v[2:5], off
	v_lshl_add_u64 v[6:7], v[58:59], 0, v[0:1]
	v_or_b32_e32 v0, s24, v44
	v_lshlrev_b32_e32 v0, 12, v0
	s_waitcnt lgkmcnt(6)
	v_cvt_pk_bf16_f32 v2, v8, v46
	s_waitcnt lgkmcnt(4)
	v_cvt_pk_bf16_f32 v3, v48, v50
	s_waitcnt lgkmcnt(2)
	v_cvt_pk_bf16_f32 v4, v52, v54
	s_waitcnt lgkmcnt(0)
	v_cvt_pk_bf16_f32 v5, v56, v60
	global_store_dwordx4 v[6:7], v[2:5], off
	v_lshl_add_u64 v[6:7], v[58:59], 0, v[0:1]
	s_mov_b64 s[22:23], 0
	v_cvt_pk_bf16_f32 v2, v9, v47
	v_cvt_pk_bf16_f32 v3, v49, v51
	v_cvt_pk_bf16_f32 v4, v53, v55
	v_cvt_pk_bf16_f32 v5, v57, v61
	global_store_dwordx4 v[6:7], v[2:5], off
	s_waitcnt lgkmcnt(0)

; __device__ __forceinline__ void cvt_item(gfp W, int N, bf16* WT, int Kd, int k0, int n0, int drow0, LAS float* scr, int lane, gfp gk) {
; #pragma unroll 8
;     for (int i = 0; i < 32; ++i) { const int kk = 2 * i + (lane >> 5); scr[kk * 33 + (lane & 31)] = W[(size_t)(k0 + kk) * N + n0 + (lane & 31)]; }
.LBB0_127:
	v_mov_b32_e32 v103, v1
	s_lshl_b32 s30, s25, 1
	s_lshl_b32 s27, s23, 1
	v_or_b32_e32 v136, s30, v10
	s_add_i32 s33, s30, 4
	s_add_i32 s31, s27, 4
	s_add_i32 s34, s27, 8
	s_add_i32 s35, s30, 8
	v_add_u32_e32 v102, s0, v136
	v_or_b32_e32 v127, s33, v10
	v_or_b32_e32 v101, s27, v11
	s_add_i32 s36, s27, 12
	s_add_i32 s37, s30, 12
	s_add_i32 s38, s27, 16
	s_add_i32 s40, s27, 20
	s_add_i32 s42, s27, 24
	s_add_i32 s27, s27, 28
	v_or_b32_e32 v126, s31, v11
	v_or_b32_e32 v128, s34, v11
	v_or_b32_e32 v129, s35, v10
	v_lshlrev_b64 v[120:121], 13, v[102:103]
	v_add_u32_e32 v102, s0, v127
	v_mov_b32_e32 v105, v103
	v_mov_b32_e32 v107, v103
	v_mov_b32_e32 v109, v103
	s_add_i32 s39, s30, 16
	v_add_u32_e32 v104, s22, v101
	v_or_b32_e32 v130, s36, v11
	v_or_b32_e32 v131, s37, v10
	v_or_b32_e32 v132, s38, v11
	v_or_b32_e32 v134, s40, v11
	v_or_b32_e32 v137, s42, v11
	v_or_b32_e32 v139, s27, v11
	v_add_u32_e32 v106, s22, v126
	v_add_u32_e32 v108, s22, v128
	v_lshlrev_b64 v[122:123], 13, v[102:103]
	v_add_u32_e32 v102, s0, v129
	v_mov_b32_e32 v111, v103
	v_mov_b32_e32 v113, v103
	v_mov_b32_e32 v115, v103
	v_mov_b32_e32 v117, v103
	v_mov_b32_e32 v119, v103
	s_add_i32 s41, s30, 20
	v_or_b32_e32 v133, s39, v10
	v_lshlrev_b64 v[104:105], 13, v[104:105]
	v_add_u32_e32 v110, s22, v130
	v_add_u32_e32 v112, s22, v132
	v_add_u32_e32 v114, s22, v134
	v_add_u32_e32 v116, s22, v137
	v_add_u32_e32 v118, s22, v139
	v_lshl_add_u64 v[120:121], v[2:3], 0, v[120:121]
	v_lshlrev_b64 v[106:107], 13, v[106:107]
	v_lshlrev_b64 v[108:109], 13, v[108:109]
	v_lshlrev_b64 v[124:125], 13, v[102:103]
	v_add_u32_e32 v102, s0, v131
	s_add_i32 s43, s30, 24
	v_or_b32_e32 v135, s41, v10
	v_lshl_add_u64 v[104:105], v[2:3], 0, v[104:105]
	v_lshlrev_b64 v[110:111], 13, v[110:111]
	v_lshlrev_b64 v[112:113], 13, v[112:113]
	v_lshlrev_b64 v[114:115], 13, v[114:115]
	v_lshlrev_b64 v[116:117], 13, v[116:117]
	v_lshlrev_b64 v[118:119], 13, v[118:119]
	v_lshl_add_u64 v[122:123], v[2:3], 0, v[122:123]
	v_lshl_add_u64 v[106:107], v[2:3], 0, v[106:107]
	v_lshl_add_u64 v[108:109], v[2:3], 0, v[108:109]
	global_load_dword v141, v[120:121], off nt
	global_load_dword v142, v[104:105], off nt
	v_lshlrev_b64 v[120:121], 13, v[102:103]
	v_add_u32_e32 v102, s0, v133
	s_add_i32 s30, s30, 28
	v_or_b32_e32 v138, s43, v10
	v_lshl_add_u64 v[110:111], v[2:3], 0, v[110:111]
	v_lshl_add_u64 v[112:113], v[2:3], 0, v[112:113]
	v_lshl_add_u64 v[114:115], v[2:3], 0, v[114:115]
	v_lshl_add_u64 v[116:117], v[2:3], 0, v[116:117]
	v_lshl_add_u64 v[118:119], v[2:3], 0, v[118:119]
	global_load_dword v143, v[122:123], off nt
	global_load_dword v144, v[106:107], off nt
	global_load_dword v145, v[108:109], off nt
	global_load_dword v146, v[110:111], off nt
	global_load_dword v147, v[112:113], off nt
	global_load_dword v148, v[114:115], off nt
	global_load_dword v149, v[116:117], off nt
	global_load_dword v150, v[118:119], off nt
	v_lshl_add_u64 v[106:107], v[2:3], 0, v[120:121]
	v_lshlrev_b64 v[108:109], 13, v[102:103]
	v_add_u32_e32 v102, s0, v135
	v_or_b32_e32 v140, s30, v10
	v_lshl_add_u64 v[104:105], v[2:3], 0, v[124:125]
	global_load_dword v151, v[106:107], off nt
	global_load_dword v152, v[104:105], off nt
	v_lshlrev_b64 v[106:107], 13, v[102:103]
	v_add_u32_e32 v102, s0, v138
	v_lshl_add_u64 v[104:105], v[2:3], 0, v[108:109]
	v_lshlrev_b64 v[108:109], 13, v[102:103]
	v_add_u32_e32 v102, s0, v140
	v_lshlrev_b64 v[110:111], 13, v[102:103]
	v_lshl_add_u64 v[110:111], v[2:3], 0, v[110:111]
	v_lshl_add_u64 v[106:107], v[2:3], 0, v[106:107]
	v_lshl_add_u64 v[108:109], v[2:3], 0, v[108:109]
	global_load_dword v102, v[110:111], off nt
	global_load_dword v153, v[108:109], off nt
	global_load_dword v154, v[106:107], off nt
	global_load_dword v155, v[104:105], off nt
	s_add_i32 s25, s25, 16
	s_add_i32 s23, s23, 16
	s_add_i32 s26, s26, -16
	s_cmp_lg_u32 s26, 0
	s_lshl_b32 s30, s25, 1
	s_lshl_b32 s27, s23, 1
	v_or_b32_e32 v45, s30, v10
	s_add_i32 s33, s30, 4
	s_add_i32 s31, s27, 4
	s_add_i32 s34, s27, 8
	s_add_i32 s35, s30, 8
	v_add_u32_e32 v0, s0, v45
	v_or_b32_e32 v63, s33, v10
	v_or_b32_e32 v39, s27, v11
	s_add_i32 s36, s27, 12
	s_add_i32 s37, s30, 12
	s_add_i32 s38, s27, 16
	s_add_i32 s40, s27, 20
	s_add_i32 s42, s27, 24
	s_add_i32 s27, s27, 28
	v_or_b32_e32 v62, s31, v11
	v_or_b32_e32 v64, s34, v11
	v_or_b32_e32 v65, s35, v10
	v_lshlrev_b64 v[56:57], 13, v[0:1]
	v_add_u32_e32 v0, s0, v63
	v_mov_b32_e32 v5, v1
	v_mov_b32_e32 v7, v1
	v_mov_b32_e32 v9, v1
	s_add_i32 s39, s30, 16
	v_add_u32_e32 v4, s22, v39
	v_or_b32_e32 v66, s36, v11
	v_or_b32_e32 v67, s37, v10
	v_or_b32_e32 v68, s38, v11
	v_or_b32_e32 v70, s40, v11
	v_or_b32_e32 v72, s42, v11
	v_or_b32_e32 v74, s27, v11
	v_add_u32_e32 v6, s22, v62
	v_add_u32_e32 v8, s22, v64
	v_lshlrev_b64 v[58:59], 13, v[0:1]
	v_add_u32_e32 v0, s0, v65
	v_mov_b32_e32 v47, v1
	v_mov_b32_e32 v49, v1
	v_mov_b32_e32 v51, v1
	v_mov_b32_e32 v53, v1
	v_mov_b32_e32 v55, v1
	s_add_i32 s41, s30, 20
	v_or_b32_e32 v69, s39, v10
	v_lshlrev_b64 v[4:5], 13, v[4:5]
	v_add_u32_e32 v46, s22, v66
	v_add_u32_e32 v48, s22, v68
	v_add_u32_e32 v50, s22, v70
	v_add_u32_e32 v52, s22, v72
	v_add_u32_e32 v54, s22, v74
	v_lshl_add_u64 v[56:57], v[2:3], 0, v[56:57]
	v_lshlrev_b64 v[6:7], 13, v[6:7]
	v_lshlrev_b64 v[8:9], 13, v[8:9]
	v_lshlrev_b64 v[60:61], 13, v[0:1]
	v_add_u32_e32 v0, s0, v67
	s_add_i32 s43, s30, 24
	v_or_b32_e32 v71, s41, v10
	v_lshl_add_u64 v[4:5], v[2:3], 0, v[4:5]
	v_lshlrev_b64 v[46:47], 13, v[46:47]
	v_lshlrev_b64 v[48:49], 13, v[48:49]
	v_lshlrev_b64 v[50:51], 13, v[50:51]
	v_lshlrev_b64 v[52:53], 13, v[52:53]
	v_lshlrev_b64 v[54:55], 13, v[54:55]
	v_lshl_add_u64 v[58:59], v[2:3], 0, v[58:59]
; #define GAS __attribute__((address_space(1)))
; #define LAS __attribute__((address_space(3)))
; #define LDS_WAIT() asm volatile("s_waitcnt lgkmcnt(0)" ::: "memory")
; __device__ __forceinline__ unsigned pk2(float lo, float hi) { unsigned r; asm("v_cvt_pk_bf16_f32 %0, %1, %2" : "=v"(r) : "v"(lo), "v"(hi)); return r; }
; __device__ __forceinline__ void cvt_item(gfp W, int N, bf16* WT, int Kd, int k0, int n0, int drow0, LAS float* scr, int lane, gfp gk) {
;     ...
;     for (int i = 0; i < 32; ++i) { const int kk = 2 * i + (lane >> 5); scr[kk * 33 + (lane & 31)] = W[(size_t)(k0 + kk) * N + n0 + (lane & 31)]; }
;     const int c = lane & 7;
;     f32x4 ga = (f32x4){1.f, 1.f, 1.f, 1.f}, gb = ga;
;     if (gk != nullptr) { ga = *(const GAS f32x4*)(gk + k0 + 8 * c); gb = *(const GAS f32x4*)(gk + k0 + 8 * c + 4); }
;     LDS_WAIT(); asm volatile("" ::: "memory");
; #pragma unroll
;     for (int j = 0; j < 4; ++j) { const int n = (lane >> 3) + 8 * j; const LAS float* s = scr + (8 * c) * 33 + n;
;         v4u o; o.x = pk2(s[0 * 33] * ga[0], s[1 * 33] * ga[1]); o.y = pk2(s[2 * 33] * ga[2], s[3 * 33] * ga[3]); o.z = pk2(s[4 * 33] * gb[0], s[5 * 33] * gb[1]); o.w = pk2(s[6 * 33] * gb[2], s[7 * 33] * gb[3]);
;         *(GAS v4u*)(WT + (size_t)(drow0 + n) * Kd + k0 + 8 * c) = o; }
;     LDS_WAIT(); asm volatile("" ::: "memory");
	v_lshl_add_u64 v[6:7], v[2:3], 0, v[6:7]
	v_lshl_add_u64 v[8:9], v[2:3], 0, v[8:9]
	global_load_dword v76, v[56:57], off nt
	global_load_dword v77, v[4:5], off nt
	v_lshlrev_b64 v[56:57], 13, v[0:1]
	v_add_u32_e32 v0, s0, v69
	s_add_i32 s30, s30, 28
	v_or_b32_e32 v73, s43, v10
	v_lshl_add_u64 v[46:47], v[2:3], 0, v[46:47]
	v_lshl_add_u64 v[48:49], v[2:3], 0, v[48:49]
	v_lshl_add_u64 v[50:51], v[2:3], 0, v[50:51]
	v_lshl_add_u64 v[52:53], v[2:3], 0, v[52:53]
	v_lshl_add_u64 v[54:55], v[2:3], 0, v[54:55]
	global_load_dword v78, v[58:59], off nt
	global_load_dword v79, v[6:7], off nt
	global_load_dword v80, v[8:9], off nt
	global_load_dword v81, v[46:47], off nt
	global_load_dword v82, v[48:49], off nt
	global_load_dword v83, v[50:51], off nt
	global_load_dword v84, v[52:53], off nt
	global_load_dword v85, v[54:55], off nt
	v_lshl_add_u64 v[6:7], v[2:3], 0, v[56:57]
	v_lshlrev_b64 v[8:9], 13, v[0:1]
	v_add_u32_e32 v0, s0, v71
	v_or_b32_e32 v75, s30, v10
	v_lshl_add_u64 v[4:5], v[2:3], 0, v[60:61]
	global_load_dword v86, v[6:7], off nt
	global_load_dword v87, v[4:5], off nt
	v_lshlrev_b64 v[6:7], 13, v[0:1]
	v_add_u32_e32 v0, s0, v73
	v_lshl_add_u64 v[4:5], v[2:3], 0, v[8:9]
	v_lshlrev_b64 v[8:9], 13, v[0:1]
	v_add_u32_e32 v0, s0, v75
	v_lshlrev_b64 v[46:47], 13, v[0:1]
	v_lshl_add_u64 v[46:47], v[2:3], 0, v[46:47]
	v_lshl_add_u64 v[6:7], v[2:3], 0, v[6:7]
	v_lshl_add_u64 v[8:9], v[2:3], 0, v[8:9]
	global_load_dword v0, v[46:47], off nt
	global_load_dword v88, v[8:9], off nt
	global_load_dword v89, v[6:7], off nt
	global_load_dword v90, v[4:5], off nt
	v_mad_u64_u32 v[104:105], s[30:31], v136, s81, v[12:13]
	v_mad_u64_u32 v[106:107], s[30:31], v101, s81, v[12:13]
	v_mad_u64_u32 v[108:109], s[30:31], v127, s81, v[12:13]
	v_mad_u64_u32 v[110:111], s[30:31], v126, s81, v[12:13]
	v_mad_u64_u32 v[112:113], s[30:31], v129, s81, v[12:13]
	v_mad_u64_u32 v[114:115], s[30:31], v128, s81, v[12:13]
	v_mad_u64_u32 v[116:117], s[30:31], v131, s81, v[12:13]
	v_mad_u64_u32 v[118:119], s[30:31], v130, s81, v[12:13]
	v_mad_u64_u32 v[120:121], s[30:31], v133, s81, v[12:13]
	v_mad_u64_u32 v[122:123], s[30:31], v132, s81, v[12:13]
	v_mad_u64_u32 v[124:125], s[30:31], v135, s81, v[12:13]
	v_mad_u64_u32 v[126:127], s[30:31], v134, s81, v[12:13]
	v_mad_u64_u32 v[128:129], s[30:31], v138, s81, v[12:13]
	v_mad_u64_u32 v[130:131], s[30:31], v137, s81, v[12:13]
	v_mad_u64_u32 v[132:133], s[30:31], v140, s81, v[12:13]
	v_mad_u64_u32 v[134:135], s[30:31], v139, s81, v[12:13]
	s_waitcnt vmcnt(31)
	ds_write_b32 v104, v141
	s_waitcnt vmcnt(30)
	ds_write_b32 v106, v142
	s_waitcnt vmcnt(29)
	ds_write_b32 v108, v143
	s_waitcnt vmcnt(28)
	ds_write_b32 v110, v144
	s_waitcnt vmcnt(20)
	ds_write_b32 v112, v152
	ds_write_b32 v114, v145
	ds_write_b32 v116, v151
	ds_write_b32 v118, v146
	s_waitcnt vmcnt(16)
	ds_write_b32 v120, v155
	ds_write_b32 v122, v147
	ds_write_b32 v124, v154
	ds_write_b32 v126, v148
	ds_write_b32 v128, v153
	ds_write_b32 v130, v149
	ds_write_b32 v132, v102
	ds_write_b32 v134, v150
	v_mad_u64_u32 v[4:5], s[30:31], v45, s81, v[12:13]
	v_mad_u64_u32 v[6:7], s[30:31], v39, s81, v[12:13]
	v_mad_u64_u32 v[8:9], s[30:31], v63, s81, v[12:13]
	v_mad_u64_u32 v[46:47], s[30:31], v62, s81, v[12:13]
	v_mad_u64_u32 v[48:49], s[30:31], v65, s81, v[12:13]
	v_mad_u64_u32 v[50:51], s[30:31], v64, s81, v[12:13]
	v_mad_u64_u32 v[52:53], s[30:31], v67, s81, v[12:13]
	v_mad_u64_u32 v[54:55], s[30:31], v66, s81, v[12:13]
	v_mad_u64_u32 v[56:57], s[30:31], v69, s81, v[12:13]
	v_mad_u64_u32 v[58:59], s[30:31], v68, s81, v[12:13]
	v_mad_u64_u32 v[60:61], s[30:31], v71, s81, v[12:13]
	v_mad_u64_u32 v[62:63], s[30:31], v70, s81, v[12:13]
	v_mad_u64_u32 v[64:65], s[30:31], v73, s81, v[12:13]
	v_mad_u64_u32 v[66:67], s[30:31], v72, s81, v[12:13]
	v_mad_u64_u32 v[68:69], s[30:31], v75, s81, v[12:13]
	v_mad_u64_u32 v[70:71], s[30:31], v74, s81, v[12:13]
	s_waitcnt vmcnt(15)
	ds_write_b32 v4, v76
	s_waitcnt vmcnt(14)
	ds_write_b32 v6, v77
	s_waitcnt vmcnt(13)
	ds_write_b32 v8, v78
	s_waitcnt vmcnt(12)
	ds_write_b32 v46, v79
	s_waitcnt vmcnt(4)
	ds_write_b32 v48, v87
	ds_write_b32 v50, v80
	ds_write_b32 v52, v86
	ds_write_b32 v54, v81
	s_waitcnt vmcnt(0)
	ds_write_b32 v56, v90
	ds_write_b32 v58, v82
	ds_write_b32 v60, v89
	ds_write_b32 v62, v83
	ds_write_b32 v64, v88
	ds_write_b32 v66, v84
	ds_write_b32 v68, v0
	ds_write_b32 v70, v85
	s_add_i32 s25, s25, 16
	s_add_i32 s23, s23, 16
	s_add_i32 s26, s26, -16
	s_cmp_lg_u32 s26, 0
	s_waitcnt lgkmcnt(0)
	ds_read2_b32 v[6:7], v41 offset0:33 offset1:41
	ds_read2_b32 v[8:9], v41 offset1:8
	ds_read2_b32 v[46:47], v41 offset0:66 offset1:74
	ds_read2_b32 v[48:49], v41 offset0:99 offset1:107
	ds_read2_b32 v[50:51], v41 offset0:132 offset1:140
	ds_read2_b32 v[52:53], v41 offset0:165 offset1:173
	ds_read2_b32 v[54:55], v41 offset0:198 offset1:206
	ds_read2_b32 v[56:57], v41 offset0:231 offset1:239
	s_lshl_b32 s0, s0, 1
	v_or_b32_e32 v0, s24, v40
	v_lshl_add_u64 v[58:59], v[18:19], 0, s[0:1]
	v_lshlrev_b32_e32 v0, 11, v0
	v_lshl_add_u64 v[60:61], v[58:59], 0, v[0:1]
	s_waitcnt lgkmcnt(6)
	v_cvt_pk_bf16_f32 v2, v8, v6
	s_waitcnt lgkmcnt(4)
	v_cvt_pk_bf16_f32 v3, v46, v48
	s_waitcnt lgkmcnt(2)
	v_cvt_pk_bf16_f32 v4, v50, v52
	s_waitcnt lgkmcnt(0)
	v_cvt_pk_bf16_f32 v5, v54, v56
	global_store_dwordx4 v[60:61], v[2:5], off
	v_or_b32_e32 v0, s24, v42
	v_lshlrev_b32_e32 v0, 11, v0
	v_cvt_pk_bf16_f32 v2, v9, v7
	v_cvt_pk_bf16_f32 v3, v47, v49
	v_cvt_pk_bf16_f32 v4, v51, v53
	v_cvt_pk_bf16_f32 v5, v55, v57
	ds_read2_b32 v[8:9], v41 offset0:16 offset1:24
	ds_read2_b32 v[46:47], v41 offset0:49 offset1:57
	ds_read2_b32 v[48:49], v41 offset0:82 offset1:90
	ds_read2_b32 v[50:51], v41 offset0:115 offset1:123
	ds_read2_b32 v[52:53], v41 offset0:148 offset1:156
	ds_read2_b32 v[54:55], v41 offset0:181 offset1:189
	ds_read2_b32 v[56:57], v41 offset0:214 offset1:222
	ds_read2_b32 v[60:61], v41 offset0:247 offset1:255
	v_lshl_add_u64 v[6:7], v[58:59], 0, v[0:1]
	v_or_b32_e32 v0, s24, v43
	v_lshlrev_b32_e32 v0, 11, v0
	global_store_dwordx4 v[6:7], v[2:5], off
	v_lshl_add_u64 v[6:7], v[58:59], 0, v[0:1]
	v_or_b32_e32 v0, s24, v44
	v_lshlrev_b32_e32 v0, 11, v0
	s_waitcnt lgkmcnt(6)
	v_cvt_pk_bf16_f32 v2, v8, v46
	s_waitcnt lgkmcnt(4)
	v_cvt_pk_bf16_f32 v3, v48, v50
	s_waitcnt lgkmcnt(2)
	v_cvt_pk_bf16_f32 v4, v52, v54
	s_waitcnt lgkmcnt(0)
	v_cvt_pk_bf16_f32 v5, v56, v60
	global_store_dwordx4 v[6:7], v[2:5], off
	v_lshl_add_u64 v[6:7], v[58:59], 0, v[0:1]
	s_nop 0
	v_cvt_pk_bf16_f32 v2, v9, v47
	v_cvt_pk_bf16_f32 v3, v49, v51
	v_cvt_pk_bf16_f32 v4, v53, v55
	v_cvt_pk_bf16_f32 v5, v57, v61
	global_store_dwordx4 v[6:7], v[2:5], off
	s_waitcnt lgkmcnt(0)

; __device__ __forceinline__ void cvt_item(gfp W, int N, bf16* WT, int Kd, int k0, int n0, int drow0, LAS float* scr, int lane, gfp gk) {
; #pragma unroll 8
;     for (int i = 0; i < 32; ++i) { const int kk = 2 * i + (lane >> 5); scr[kk * 33 + (lane & 31)] = W[(size_t)(k0 + kk) * N + n0 + (lane & 31)]; }
.LBB0_132:
	v_mov_b32_e32 v103, v1
	s_lshl_b32 s30, s25, 1
	s_lshl_b32 s27, s24, 1
	v_or_b32_e32 v136, s30, v10
	s_add_i32 s33, s30, 4
	s_add_i32 s31, s27, 4
	s_add_i32 s34, s27, 8
	s_add_i32 s35, s30, 8
	v_add_u32_e32 v102, s0, v136
	v_or_b32_e32 v127, s33, v10
	v_or_b32_e32 v101, s27, v11
	s_add_i32 s36, s27, 12
	s_add_i32 s37, s30, 12
	s_add_i32 s38, s27, 16
	s_add_i32 s40, s27, 20
	s_add_i32 s42, s27, 24
	s_add_i32 s27, s27, 28
	v_or_b32_e32 v126, s31, v11
	v_or_b32_e32 v128, s34, v11
	v_or_b32_e32 v129, s35, v10
	v_lshlrev_b64 v[120:121], 13, v[102:103]
	v_add_u32_e32 v102, s0, v127
	v_mov_b32_e32 v105, v103
	v_mov_b32_e32 v107, v103
	v_mov_b32_e32 v109, v103
	s_add_i32 s39, s30, 16
	v_add_u32_e32 v104, s23, v101
	v_or_b32_e32 v130, s36, v11
	v_or_b32_e32 v131, s37, v10
	v_or_b32_e32 v132, s38, v11
	v_or_b32_e32 v134, s40, v11
	v_or_b32_e32 v137, s42, v11
	v_or_b32_e32 v139, s27, v11
	v_add_u32_e32 v106, s23, v126
	v_add_u32_e32 v108, s23, v128
	v_lshlrev_b64 v[122:123], 13, v[102:103]
	v_add_u32_e32 v102, s0, v129
	v_mov_b32_e32 v111, v103
	v_mov_b32_e32 v113, v103
	v_mov_b32_e32 v115, v103
	v_mov_b32_e32 v117, v103
	v_mov_b32_e32 v119, v103
	s_add_i32 s41, s30, 20
	v_or_b32_e32 v133, s39, v10
	v_lshlrev_b64 v[104:105], 13, v[104:105]
	v_add_u32_e32 v110, s23, v130
	v_add_u32_e32 v112, s23, v132
	v_add_u32_e32 v114, s23, v134
	v_add_u32_e32 v116, s23, v137
	v_add_u32_e32 v118, s23, v139
	v_lshl_add_u64 v[120:121], v[2:3], 0, v[120:121]
	v_lshlrev_b64 v[106:107], 13, v[106:107]
	v_lshlrev_b64 v[108:109], 13, v[108:109]
	v_lshlrev_b64 v[124:125], 13, v[102:103]
	v_add_u32_e32 v102, s0, v131
	s_add_i32 s43, s30, 24
	v_or_b32_e32 v135, s41, v10
	v_lshl_add_u64 v[104:105], v[2:3], 0, v[104:105]
	v_lshlrev_b64 v[110:111], 13, v[110:111]
	v_lshlrev_b64 v[112:113], 13, v[112:113]
	v_lshlrev_b64 v[114:115], 13, v[114:115]
	v_lshlrev_b64 v[116:117], 13, v[116:117]
	v_lshlrev_b64 v[118:119], 13, v[118:119]
	v_lshl_add_u64 v[122:123], v[2:3], 0, v[122:123]
	v_lshl_add_u64 v[106:107], v[2:3], 0, v[106:107]
	v_lshl_add_u64 v[108:109], v[2:3], 0, v[108:109]
	global_load_dword v141, v[120:121], off nt
	global_load_dword v142, v[104:105], off nt
	v_lshlrev_b64 v[120:121], 13, v[102:103]
	v_add_u32_e32 v102, s0, v133
	s_add_i32 s30, s30, 28
	v_or_b32_e32 v138, s43, v10
	v_lshl_add_u64 v[110:111], v[2:3], 0, v[110:111]
	v_lshl_add_u64 v[112:113], v[2:3], 0, v[112:113]
	v_lshl_add_u64 v[114:115], v[2:3], 0, v[114:115]
	v_lshl_add_u64 v[116:117], v[2:3], 0, v[116:117]
	v_lshl_add_u64 v[118:119], v[2:3], 0, v[118:119]
	global_load_dword v143, v[122:123], off nt
	global_load_dword v144, v[106:107], off nt
	global_load_dword v145, v[108:109], off nt
	global_load_dword v146, v[110:111], off nt
	global_load_dword v147, v[112:113], off nt
	global_load_dword v148, v[114:115], off nt
	global_load_dword v149, v[116:117], off nt
	global_load_dword v150, v[118:119], off nt
	v_lshl_add_u64 v[106:107], v[2:3], 0, v[120:121]
	v_lshlrev_b64 v[108:109], 13, v[102:103]
	v_add_u32_e32 v102, s0, v135
	v_or_b32_e32 v140, s30, v10
	v_lshl_add_u64 v[104:105], v[2:3], 0, v[124:125]
	global_load_dword v151, v[106:107], off nt
	global_load_dword v152, v[104:105], off nt
	v_lshlrev_b64 v[106:107], 13, v[102:103]
	v_add_u32_e32 v102, s0, v138
	v_lshl_add_u64 v[104:105], v[2:3], 0, v[108:109]
	v_lshlrev_b64 v[108:109], 13, v[102:103]
	v_add_u32_e32 v102, s0, v140
	v_lshlrev_b64 v[110:111], 13, v[102:103]
	v_lshl_add_u64 v[110:111], v[2:3], 0, v[110:111]
	v_lshl_add_u64 v[106:107], v[2:3], 0, v[106:107]
	v_lshl_add_u64 v[108:109], v[2:3], 0, v[108:109]
	global_load_dword v102, v[110:111], off nt
	global_load_dword v153, v[108:109], off nt
	global_load_dword v154, v[106:107], off nt
	global_load_dword v155, v[104:105], off nt
	s_add_i32 s25, s25, 16
	s_add_i32 s24, s24, 16
	s_add_i32 s26, s26, -16
	s_cmp_lg_u32 s26, 0
	s_lshl_b32 s30, s25, 1
	s_lshl_b32 s27, s24, 1
	v_or_b32_e32 v45, s30, v10
	s_add_i32 s33, s30, 4
	s_add_i32 s31, s27, 4
	s_add_i32 s34, s27, 8
	s_add_i32 s35, s30, 8
	v_add_u32_e32 v0, s0, v45
	v_or_b32_e32 v63, s33, v10
	v_or_b32_e32 v39, s27, v11
	s_add_i32 s36, s27, 12
	s_add_i32 s37, s30, 12
	s_add_i32 s38, s27, 16
	s_add_i32 s40, s27, 20
	s_add_i32 s42, s27, 24
	s_add_i32 s27, s27, 28
	v_or_b32_e32 v62, s31, v11
	v_or_b32_e32 v64, s34, v11
	v_or_b32_e32 v65, s35, v10
	v_lshlrev_b64 v[56:57], 13, v[0:1]
	v_add_u32_e32 v0, s0, v63
	v_mov_b32_e32 v5, v1
	v_mov_b32_e32 v7, v1
	v_mov_b32_e32 v9, v1
	s_add_i32 s39, s30, 16
	v_add_u32_e32 v4, s23, v39
	v_or_b32_e32 v66, s36, v11
	v_or_b32_e32 v67, s37, v10
	v_or_b32_e32 v68, s38, v11
	v_or_b32_e32 v70, s40, v11
	v_or_b32_e32 v72, s42, v11
	v_or_b32_e32 v74, s27, v11
	v_add_u32_e32 v6, s23, v62
	v_add_u32_e32 v8, s23, v64
	v_lshlrev_b64 v[58:59], 13, v[0:1]
	v_add_u32_e32 v0, s0, v65
	v_mov_b32_e32 v47, v1
	v_mov_b32_e32 v49, v1
	v_mov_b32_e32 v51, v1
	v_mov_b32_e32 v53, v1
	v_mov_b32_e32 v55, v1
	s_add_i32 s41, s30, 20
	v_or_b32_e32 v69, s39, v10
	v_lshlrev_b64 v[4:5], 13, v[4:5]
	v_add_u32_e32 v46, s23, v66
	v_add_u32_e32 v48, s23, v68
	v_add_u32_e32 v50, s23, v70
	v_add_u32_e32 v52, s23, v72
	v_add_u32_e32 v54, s23, v74
	v_lshl_add_u64 v[56:57], v[2:3], 0, v[56:57]
	v_lshlrev_b64 v[6:7], 13, v[6:7]
	v_lshlrev_b64 v[8:9], 13, v[8:9]
	v_lshlrev_b64 v[60:61], 13, v[0:1]
	v_add_u32_e32 v0, s0, v67
	s_add_i32 s43, s30, 24
	v_or_b32_e32 v71, s41, v10
	v_lshl_add_u64 v[4:5], v[2:3], 0, v[4:5]
	v_lshlrev_b64 v[46:47], 13, v[46:47]
	v_lshlrev_b64 v[48:49], 13, v[48:49]
	v_lshlrev_b64 v[50:51], 13, v[50:51]
	v_lshlrev_b64 v[52:53], 13, v[52:53]
	v_lshlrev_b64 v[54:55], 13, v[54:55]
	v_lshl_add_u64 v[58:59], v[2:3], 0, v[58:59]
; #define GAS __attribute__((address_space(1)))
; #define LAS __attribute__((address_space(3)))
; #define LDS_WAIT() asm volatile("s_waitcnt lgkmcnt(0)" ::: "memory")
; __device__ __forceinline__ unsigned pk2(float lo, float hi) { unsigned r; asm("v_cvt_pk_bf16_f32 %0, %1, %2" : "=v"(r) : "v"(lo), "v"(hi)); return r; }
; __device__ __forceinline__ void cvt_item(gfp W, int N, bf16* WT, int Kd, int k0, int n0, int drow0, LAS float* scr, int lane, gfp gk) {
; #pragma unroll 8
;     for (int i = 0; i < 32; ++i) { const int kk = 2 * i + (lane >> 5); scr[kk * 33 + (lane & 31)] = W[(size_t)(k0 + kk) * N + n0 + (lane & 31)]; }
;     const int c = lane & 7;
;     f32x4 ga = (f32x4){1.f, 1.f, 1.f, 1.f}, gb = ga;
;     if (gk != nullptr) { ga = *(const GAS f32x4*)(gk + k0 + 8 * c); gb = *(const GAS f32x4*)(gk + k0 + 8 * c + 4); }
;     LDS_WAIT(); asm volatile("" ::: "memory");
; #pragma unroll
;     for (int j = 0; j < 4; ++j) { const int n = (lane >> 3) + 8 * j; const LAS float* s = scr + (8 * c) * 33 + n;
;         v4u o; o.x = pk2(s[0 * 33] * ga[0], s[1 * 33] * ga[1]); o.y = pk2(s[2 * 33] * ga[2], s[3 * 33] * ga[3]); o.z = pk2(s[4 * 33] * gb[0], s[5 * 33] * gb[1]); o.w = pk2(s[6 * 33] * gb[2], s[7 * 33] * gb[3]);
;         *(GAS v4u*)(WT + (size_t)(drow0 + n) * Kd + k0 + 8 * c) = o; }
;     LDS_WAIT(); asm volatile("" ::: "memory");
	v_lshl_add_u64 v[6:7], v[2:3], 0, v[6:7]
	v_lshl_add_u64 v[8:9], v[2:3], 0, v[8:9]
	global_load_dword v76, v[56:57], off nt
	global_load_dword v77, v[4:5], off nt
	v_lshlrev_b64 v[56:57], 13, v[0:1]
	v_add_u32_e32 v0, s0, v69
	s_add_i32 s30, s30, 28
	v_or_b32_e32 v73, s43, v10
	v_lshl_add_u64 v[46:47], v[2:3], 0, v[46:47]
	v_lshl_add_u64 v[48:49], v[2:3], 0, v[48:49]
	v_lshl_add_u64 v[50:51], v[2:3], 0, v[50:51]
	v_lshl_add_u64 v[52:53], v[2:3], 0, v[52:53]
	v_lshl_add_u64 v[54:55], v[2:3], 0, v[54:55]
	global_load_dword v78, v[58:59], off nt
	global_load_dword v79, v[6:7], off nt
	global_load_dword v80, v[8:9], off nt
	global_load_dword v81, v[46:47], off nt
	global_load_dword v82, v[48:49], off nt
	global_load_dword v83, v[50:51], off nt
	global_load_dword v84, v[52:53], off nt
	global_load_dword v85, v[54:55], off nt
	v_lshl_add_u64 v[6:7], v[2:3], 0, v[56:57]
	v_lshlrev_b64 v[8:9], 13, v[0:1]
	v_add_u32_e32 v0, s0, v71
	v_or_b32_e32 v75, s30, v10
	v_lshl_add_u64 v[4:5], v[2:3], 0, v[60:61]
	global_load_dword v86, v[6:7], off nt
	global_load_dword v87, v[4:5], off nt
	v_lshlrev_b64 v[6:7], 13, v[0:1]
	v_add_u32_e32 v0, s0, v73
	v_lshl_add_u64 v[4:5], v[2:3], 0, v[8:9]
	v_lshlrev_b64 v[8:9], 13, v[0:1]
	v_add_u32_e32 v0, s0, v75
	v_lshlrev_b64 v[46:47], 13, v[0:1]
	v_lshl_add_u64 v[46:47], v[2:3], 0, v[46:47]
	v_lshl_add_u64 v[6:7], v[2:3], 0, v[6:7]
	v_lshl_add_u64 v[8:9], v[2:3], 0, v[8:9]
	global_load_dword v0, v[46:47], off nt
	global_load_dword v88, v[8:9], off nt
	global_load_dword v89, v[6:7], off nt
	global_load_dword v90, v[4:5], off nt
	v_mad_u64_u32 v[104:105], s[30:31], v136, s81, v[12:13]
	v_mad_u64_u32 v[106:107], s[30:31], v101, s81, v[12:13]
	v_mad_u64_u32 v[108:109], s[30:31], v127, s81, v[12:13]
	v_mad_u64_u32 v[110:111], s[30:31], v126, s81, v[12:13]
	v_mad_u64_u32 v[112:113], s[30:31], v129, s81, v[12:13]
	v_mad_u64_u32 v[114:115], s[30:31], v128, s81, v[12:13]
	v_mad_u64_u32 v[116:117], s[30:31], v131, s81, v[12:13]
	v_mad_u64_u32 v[118:119], s[30:31], v130, s81, v[12:13]
	v_mad_u64_u32 v[120:121], s[30:31], v133, s81, v[12:13]
	v_mad_u64_u32 v[122:123], s[30:31], v132, s81, v[12:13]
	v_mad_u64_u32 v[124:125], s[30:31], v135, s81, v[12:13]
	v_mad_u64_u32 v[126:127], s[30:31], v134, s81, v[12:13]
	v_mad_u64_u32 v[128:129], s[30:31], v138, s81, v[12:13]
	v_mad_u64_u32 v[130:131], s[30:31], v137, s81, v[12:13]
	v_mad_u64_u32 v[132:133], s[30:31], v140, s81, v[12:13]
	v_mad_u64_u32 v[134:135], s[30:31], v139, s81, v[12:13]
	s_waitcnt vmcnt(31)
	ds_write_b32 v104, v141
	s_waitcnt vmcnt(30)
	ds_write_b32 v106, v142
	s_waitcnt vmcnt(29)
	ds_write_b32 v108, v143
	s_waitcnt vmcnt(28)
	ds_write_b32 v110, v144
	s_waitcnt vmcnt(20)
	ds_write_b32 v112, v152
	ds_write_b32 v114, v145
	ds_write_b32 v116, v151
	ds_write_b32 v118, v146
	s_waitcnt vmcnt(16)
	ds_write_b32 v120, v155
	ds_write_b32 v122, v147
	ds_write_b32 v124, v154
	ds_write_b32 v126, v148
	ds_write_b32 v128, v153
	ds_write_b32 v130, v149
	ds_write_b32 v132, v102
	ds_write_b32 v134, v150
	v_mad_u64_u32 v[4:5], s[30:31], v45, s81, v[12:13]
	v_mad_u64_u32 v[6:7], s[30:31], v39, s81, v[12:13]
	v_mad_u64_u32 v[8:9], s[30:31], v63, s81, v[12:13]
	v_mad_u64_u32 v[46:47], s[30:31], v62, s81, v[12:13]
	v_mad_u64_u32 v[48:49], s[30:31], v65, s81, v[12:13]
	v_mad_u64_u32 v[50:51], s[30:31], v64, s81, v[12:13]
	v_mad_u64_u32 v[52:53], s[30:31], v67, s81, v[12:13]
	v_mad_u64_u32 v[54:55], s[30:31], v66, s81, v[12:13]
	v_mad_u64_u32 v[56:57], s[30:31], v69, s81, v[12:13]
	v_mad_u64_u32 v[58:59], s[30:31], v68, s81, v[12:13]
	v_mad_u64_u32 v[60:61], s[30:31], v71, s81, v[12:13]
	v_mad_u64_u32 v[62:63], s[30:31], v70, s81, v[12:13]
	v_mad_u64_u32 v[64:65], s[30:31], v73, s81, v[12:13]
	v_mad_u64_u32 v[66:67], s[30:31], v72, s81, v[12:13]
	v_mad_u64_u32 v[68:69], s[30:31], v75, s81, v[12:13]
	v_mad_u64_u32 v[70:71], s[30:31], v74, s81, v[12:13]
	s_waitcnt vmcnt(15)
	ds_write_b32 v4, v76
	s_waitcnt vmcnt(14)
	ds_write_b32 v6, v77
	s_waitcnt vmcnt(13)
	ds_write_b32 v8, v78
	s_waitcnt vmcnt(12)
	ds_write_b32 v46, v79
	s_waitcnt vmcnt(4)
	ds_write_b32 v48, v87
	ds_write_b32 v50, v80
	ds_write_b32 v52, v86
	ds_write_b32 v54, v81
	s_waitcnt vmcnt(0)
	ds_write_b32 v56, v90
	ds_write_b32 v58, v82
	ds_write_b32 v60, v89
	ds_write_b32 v62, v83
	ds_write_b32 v64, v88
	ds_write_b32 v66, v84
	ds_write_b32 v68, v0
	ds_write_b32 v70, v85
	s_add_i32 s25, s25, 16
	s_add_i32 s24, s24, 16
	s_add_i32 s26, s26, -16
	s_cmp_lg_u32 s26, 0
	s_waitcnt lgkmcnt(0)
	ds_read2_b32 v[6:7], v41 offset0:33 offset1:41
	ds_read2_b32 v[8:9], v41 offset1:8
	ds_read2_b32 v[46:47], v41 offset0:66 offset1:74
	ds_read2_b32 v[48:49], v41 offset0:99 offset1:107
	ds_read2_b32 v[50:51], v41 offset0:132 offset1:140
	ds_read2_b32 v[52:53], v41 offset0:165 offset1:173
	ds_read2_b32 v[54:55], v41 offset0:198 offset1:206
	ds_read2_b32 v[56:57], v41 offset0:231 offset1:239
	s_and_b32 s22, 0xffff, s22
	s_lshl_b32 s0, s0, 1
	v_or_b32_e32 v0, s22, v40
	v_lshl_add_u64 v[58:59], v[20:21], 0, s[0:1]
	v_lshlrev_b32_e32 v0, 11, v0
	v_lshl_add_u64 v[60:61], v[58:59], 0, v[0:1]
	s_waitcnt lgkmcnt(6)
	v_cvt_pk_bf16_f32 v2, v8, v6
	s_waitcnt lgkmcnt(4)
	v_cvt_pk_bf16_f32 v3, v46, v48
	s_waitcnt lgkmcnt(2)
	v_cvt_pk_bf16_f32 v4, v50, v52
	s_waitcnt lgkmcnt(0)
	v_cvt_pk_bf16_f32 v5, v54, v56
	global_store_dwordx4 v[60:61], v[2:5], off
	v_or_b32_e32 v0, s22, v42
	v_lshlrev_b32_e32 v0, 11, v0
	v_cvt_pk_bf16_f32 v2, v9, v7
	v_cvt_pk_bf16_f32 v3, v47, v49
	v_cvt_pk_bf16_f32 v4, v51, v53
	v_cvt_pk_bf16_f32 v5, v55, v57
	ds_read2_b32 v[8:9], v41 offset0:16 offset1:24
	ds_read2_b32 v[46:47], v41 offset0:49 offset1:57
	ds_read2_b32 v[48:49], v41 offset0:82 offset1:90
	ds_read2_b32 v[50:51], v41 offset0:115 offset1:123
	ds_read2_b32 v[52:53], v41 offset0:148 offset1:156
	ds_read2_b32 v[54:55], v41 offset0:181 offset1:189
	ds_read2_b32 v[56:57], v41 offset0:214 offset1:222
	ds_read2_b32 v[60:61], v41 offset0:247 offset1:255
	v_lshl_add_u64 v[6:7], v[58:59], 0, v[0:1]
	v_or_b32_e32 v0, s22, v43
	v_lshlrev_b32_e32 v0, 11, v0
	global_store_dwordx4 v[6:7], v[2:5], off
	v_lshl_add_u64 v[6:7], v[58:59], 0, v[0:1]
	v_or_b32_e32 v0, s22, v44
	v_lshlrev_b32_e32 v0, 11, v0
	s_waitcnt lgkmcnt(6)
	v_cvt_pk_bf16_f32 v2, v8, v46
	s_waitcnt lgkmcnt(4)
	v_cvt_pk_bf16_f32 v3, v48, v50
	s_waitcnt lgkmcnt(2)
	v_cvt_pk_bf16_f32 v4, v52, v54
	s_waitcnt lgkmcnt(0)
	v_cvt_pk_bf16_f32 v5, v56, v60
	global_store_dwordx4 v[6:7], v[2:5], off
	v_lshl_add_u64 v[6:7], v[58:59], 0, v[0:1]
	s_nop 0
	v_cvt_pk_bf16_f32 v2, v9, v47
	v_cvt_pk_bf16_f32 v3, v49, v51
	v_cvt_pk_bf16_f32 v4, v53, v55
	v_cvt_pk_bf16_f32 v5, v57, v61
	global_store_dwordx4 v[6:7], v[2:5], off
	s_waitcnt lgkmcnt(0)

; __device__ __forceinline__ void cvt_item(gfp W, int N, bf16* WT, int Kd, int k0, int n0, int drow0, LAS float* scr, int lane, gfp gk) {
; #pragma unroll 8
;     for (int i = 0; i < 32; ++i) { const int kk = 2 * i + (lane >> 5); scr[kk * 33 + (lane & 31)] = W[(size_t)(k0 + kk) * N + n0 + (lane & 31)]; }
.LBB0_137:
	v_mov_b32_e32 v103, v1
	s_lshl_b32 s30, s25, 1
	s_lshl_b32 s27, s24, 1
	v_or_b32_e32 v136, s30, v10
	s_add_i32 s33, s30, 4
	s_add_i32 s31, s27, 4
	s_add_i32 s34, s27, 8
	s_add_i32 s35, s30, 8
	v_add_u32_e32 v102, s0, v136
	v_or_b32_e32 v127, s33, v10
	v_or_b32_e32 v101, s27, v11
	s_add_i32 s36, s27, 12
	s_add_i32 s37, s30, 12
	s_add_i32 s38, s27, 16
	s_add_i32 s40, s27, 20
	s_add_i32 s42, s27, 24
	s_add_i32 s27, s27, 28
	v_or_b32_e32 v126, s31, v11
	v_or_b32_e32 v128, s34, v11
	v_or_b32_e32 v129, s35, v10
	v_lshlrev_b64 v[120:121], 13, v[102:103]
	v_add_u32_e32 v102, s0, v127
	v_mov_b32_e32 v105, v103
	v_mov_b32_e32 v107, v103
	v_mov_b32_e32 v109, v103
	s_add_i32 s39, s30, 16
	v_add_u32_e32 v104, s23, v101
	v_or_b32_e32 v130, s36, v11
	v_or_b32_e32 v131, s37, v10
	v_or_b32_e32 v132, s38, v11
	v_or_b32_e32 v134, s40, v11
	v_or_b32_e32 v137, s42, v11
	v_or_b32_e32 v139, s27, v11
	v_add_u32_e32 v106, s23, v126
	v_add_u32_e32 v108, s23, v128
	v_lshlrev_b64 v[122:123], 13, v[102:103]
	v_add_u32_e32 v102, s0, v129
	v_mov_b32_e32 v111, v103
	v_mov_b32_e32 v113, v103
	v_mov_b32_e32 v115, v103
	v_mov_b32_e32 v117, v103
	v_mov_b32_e32 v119, v103
	s_add_i32 s41, s30, 20
	v_or_b32_e32 v133, s39, v10
	v_lshlrev_b64 v[104:105], 13, v[104:105]
	v_add_u32_e32 v110, s23, v130
	v_add_u32_e32 v112, s23, v132
	v_add_u32_e32 v114, s23, v134
	v_add_u32_e32 v116, s23, v137
	v_add_u32_e32 v118, s23, v139
	v_lshl_add_u64 v[120:121], v[2:3], 0, v[120:121]
	v_lshlrev_b64 v[106:107], 13, v[106:107]
	v_lshlrev_b64 v[108:109], 13, v[108:109]
	v_lshlrev_b64 v[124:125], 13, v[102:103]
	v_add_u32_e32 v102, s0, v131
	s_add_i32 s43, s30, 24
	v_or_b32_e32 v135, s41, v10
	v_lshl_add_u64 v[104:105], v[2:3], 0, v[104:105]
	v_lshlrev_b64 v[110:111], 13, v[110:111]
	v_lshlrev_b64 v[112:113], 13, v[112:113]
	v_lshlrev_b64 v[114:115], 13, v[114:115]
	v_lshlrev_b64 v[116:117], 13, v[116:117]
	v_lshlrev_b64 v[118:119], 13, v[118:119]
	v_lshl_add_u64 v[122:123], v[2:3], 0, v[122:123]
	v_lshl_add_u64 v[106:107], v[2:3], 0, v[106:107]
	v_lshl_add_u64 v[108:109], v[2:3], 0, v[108:109]
	global_load_dword v141, v[120:121], off nt
	global_load_dword v142, v[104:105], off nt
	v_lshlrev_b64 v[120:121], 13, v[102:103]
	v_add_u32_e32 v102, s0, v133
	s_add_i32 s30, s30, 28
	v_or_b32_e32 v138, s43, v10
	v_lshl_add_u64 v[110:111], v[2:3], 0, v[110:111]
	v_lshl_add_u64 v[112:113], v[2:3], 0, v[112:113]
	v_lshl_add_u64 v[114:115], v[2:3], 0, v[114:115]
	v_lshl_add_u64 v[116:117], v[2:3], 0, v[116:117]
	v_lshl_add_u64 v[118:119], v[2:3], 0, v[118:119]
	global_load_dword v143, v[122:123], off nt
	global_load_dword v144, v[106:107], off nt
	global_load_dword v145, v[108:109], off nt
	global_load_dword v146, v[110:111], off nt
	global_load_dword v147, v[112:113], off nt
	global_load_dword v148, v[114:115], off nt
	global_load_dword v149, v[116:117], off nt
	global_load_dword v150, v[118:119], off nt
	v_lshl_add_u64 v[106:107], v[2:3], 0, v[120:121]
	v_lshlrev_b64 v[108:109], 13, v[102:103]
	v_add_u32_e32 v102, s0, v135
	v_or_b32_e32 v140, s30, v10
	v_lshl_add_u64 v[104:105], v[2:3], 0, v[124:125]
	global_load_dword v151, v[106:107], off nt
	global_load_dword v152, v[104:105], off nt
	v_lshlrev_b64 v[106:107], 13, v[102:103]
	v_add_u32_e32 v102, s0, v138
	v_lshl_add_u64 v[104:105], v[2:3], 0, v[108:109]
	v_lshlrev_b64 v[108:109], 13, v[102:103]
	v_add_u32_e32 v102, s0, v140
	v_lshlrev_b64 v[110:111], 13, v[102:103]
	v_lshl_add_u64 v[110:111], v[2:3], 0, v[110:111]
	v_lshl_add_u64 v[106:107], v[2:3], 0, v[106:107]
	v_lshl_add_u64 v[108:109], v[2:3], 0, v[108:109]
	global_load_dword v102, v[110:111], off nt
	global_load_dword v153, v[108:109], off nt
	global_load_dword v154, v[106:107], off nt
	global_load_dword v155, v[104:105], off nt
	s_add_i32 s25, s25, 16
	s_add_i32 s24, s24, 16
	s_add_i32 s26, s26, -16
	s_cmp_lg_u32 s26, 0
	s_lshl_b32 s30, s25, 1
	s_lshl_b32 s27, s24, 1
	v_or_b32_e32 v45, s30, v10
	s_add_i32 s33, s30, 4
	s_add_i32 s31, s27, 4
	s_add_i32 s34, s27, 8
	s_add_i32 s35, s30, 8
	v_add_u32_e32 v0, s0, v45
	v_or_b32_e32 v63, s33, v10
	v_or_b32_e32 v39, s27, v11
	s_add_i32 s36, s27, 12
	s_add_i32 s37, s30, 12
	s_add_i32 s38, s27, 16
	s_add_i32 s40, s27, 20
	s_add_i32 s42, s27, 24
	s_add_i32 s27, s27, 28
	v_or_b32_e32 v62, s31, v11
	v_or_b32_e32 v64, s34, v11
	v_or_b32_e32 v65, s35, v10
	v_lshlrev_b64 v[56:57], 13, v[0:1]
	v_add_u32_e32 v0, s0, v63
	v_mov_b32_e32 v5, v1
	v_mov_b32_e32 v7, v1
	v_mov_b32_e32 v9, v1
	s_add_i32 s39, s30, 16
	v_add_u32_e32 v4, s23, v39
	v_or_b32_e32 v66, s36, v11
	v_or_b32_e32 v67, s37, v10
	v_or_b32_e32 v68, s38, v11
	v_or_b32_e32 v70, s40, v11
	v_or_b32_e32 v72, s42, v11
	v_or_b32_e32 v74, s27, v11
	v_add_u32_e32 v6, s23, v62
	v_add_u32_e32 v8, s23, v64
	v_lshlrev_b64 v[58:59], 13, v[0:1]
	v_add_u32_e32 v0, s0, v65
	v_mov_b32_e32 v47, v1
	v_mov_b32_e32 v49, v1
	v_mov_b32_e32 v51, v1
	v_mov_b32_e32 v53, v1
	v_mov_b32_e32 v55, v1
	s_add_i32 s41, s30, 20
	v_or_b32_e32 v69, s39, v10
	v_lshlrev_b64 v[4:5], 13, v[4:5]
	v_add_u32_e32 v46, s23, v66
	v_add_u32_e32 v48, s23, v68
	v_add_u32_e32 v50, s23, v70
	v_add_u32_e32 v52, s23, v72
	v_add_u32_e32 v54, s23, v74
	v_lshl_add_u64 v[56:57], v[2:3], 0, v[56:57]
	v_lshlrev_b64 v[6:7], 13, v[6:7]
	v_lshlrev_b64 v[8:9], 13, v[8:9]
	v_lshlrev_b64 v[60:61], 13, v[0:1]
	v_add_u32_e32 v0, s0, v67
	s_add_i32 s43, s30, 24
	v_or_b32_e32 v71, s41, v10
	v_lshl_add_u64 v[4:5], v[2:3], 0, v[4:5]
	v_lshlrev_b64 v[46:47], 13, v[46:47]
	v_lshlrev_b64 v[48:49], 13, v[48:49]
	v_lshlrev_b64 v[50:51], 13, v[50:51]
	v_lshlrev_b64 v[52:53], 13, v[52:53]
	v_lshlrev_b64 v[54:55], 13, v[54:55]
	v_lshl_add_u64 v[58:59], v[2:3], 0, v[58:59]
; #define GAS __attribute__((address_space(1)))
; #define LAS __attribute__((address_space(3)))
; #define LDS_WAIT() asm volatile("s_waitcnt lgkmcnt(0)" ::: "memory")
; __device__ __forceinline__ unsigned pk2(float lo, float hi) { unsigned r; asm("v_cvt_pk_bf16_f32 %0, %1, %2" : "=v"(r) : "v"(lo), "v"(hi)); return r; }
; __device__ __forceinline__ void cvt_item(gfp W, int N, bf16* WT, int Kd, int k0, int n0, int drow0, LAS float* scr, int lane, gfp gk) {
; #pragma unroll 8
;     for (int i = 0; i < 32; ++i) { const int kk = 2 * i + (lane >> 5); scr[kk * 33 + (lane & 31)] = W[(size_t)(k0 + kk) * N + n0 + (lane & 31)]; }
;     const int c = lane & 7;
;     f32x4 ga = (f32x4){1.f, 1.f, 1.f, 1.f}, gb = ga;
;     if (gk != nullptr) { ga = *(const GAS f32x4*)(gk + k0 + 8 * c); gb = *(const GAS f32x4*)(gk + k0 + 8 * c + 4); }
;     LDS_WAIT(); asm volatile("" ::: "memory");
; #pragma unroll
;     for (int j = 0; j < 4; ++j) { const int n = (lane >> 3) + 8 * j; const LAS float* s = scr + (8 * c) * 33 + n;
;         v4u o; o.x = pk2(s[0 * 33] * ga[0], s[1 * 33] * ga[1]); o.y = pk2(s[2 * 33] * ga[2], s[3 * 33] * ga[3]); o.z = pk2(s[4 * 33] * gb[0], s[5 * 33] * gb[1]); o.w = pk2(s[6 * 33] * gb[2], s[7 * 33] * gb[3]);
;         *(GAS v4u*)(WT + (size_t)(drow0 + n) * Kd + k0 + 8 * c) = o; }
;     LDS_WAIT(); asm volatile("" ::: "memory");
	v_lshl_add_u64 v[6:7], v[2:3], 0, v[6:7]
	v_lshl_add_u64 v[8:9], v[2:3], 0, v[8:9]
	global_load_dword v76, v[56:57], off nt
	global_load_dword v77, v[4:5], off nt
	v_lshlrev_b64 v[56:57], 13, v[0:1]
	v_add_u32_e32 v0, s0, v69
	s_add_i32 s30, s30, 28
	v_or_b32_e32 v73, s43, v10
	v_lshl_add_u64 v[46:47], v[2:3], 0, v[46:47]
	v_lshl_add_u64 v[48:49], v[2:3], 0, v[48:49]
	v_lshl_add_u64 v[50:51], v[2:3], 0, v[50:51]
	v_lshl_add_u64 v[52:53], v[2:3], 0, v[52:53]
	v_lshl_add_u64 v[54:55], v[2:3], 0, v[54:55]
	global_load_dword v78, v[58:59], off nt
	global_load_dword v79, v[6:7], off nt
	global_load_dword v80, v[8:9], off nt
	global_load_dword v81, v[46:47], off nt
	global_load_dword v82, v[48:49], off nt
	global_load_dword v83, v[50:51], off nt
	global_load_dword v84, v[52:53], off nt
	global_load_dword v85, v[54:55], off nt
	v_lshl_add_u64 v[6:7], v[2:3], 0, v[56:57]
	v_lshlrev_b64 v[8:9], 13, v[0:1]
	v_add_u32_e32 v0, s0, v71
	v_or_b32_e32 v75, s30, v10
	v_lshl_add_u64 v[4:5], v[2:3], 0, v[60:61]
	global_load_dword v86, v[6:7], off nt
	global_load_dword v87, v[4:5], off nt
	v_lshlrev_b64 v[6:7], 13, v[0:1]
	v_add_u32_e32 v0, s0, v73
	v_lshl_add_u64 v[4:5], v[2:3], 0, v[8:9]
	v_lshlrev_b64 v[8:9], 13, v[0:1]
	v_add_u32_e32 v0, s0, v75
	v_lshlrev_b64 v[46:47], 13, v[0:1]
	v_lshl_add_u64 v[46:47], v[2:3], 0, v[46:47]
	v_lshl_add_u64 v[6:7], v[2:3], 0, v[6:7]
	v_lshl_add_u64 v[8:9], v[2:3], 0, v[8:9]
	global_load_dword v0, v[46:47], off nt
	global_load_dword v88, v[8:9], off nt
	global_load_dword v89, v[6:7], off nt
	global_load_dword v90, v[4:5], off nt
	v_mad_u64_u32 v[104:105], s[30:31], v136, s81, v[12:13]
	v_mad_u64_u32 v[106:107], s[30:31], v101, s81, v[12:13]
	v_mad_u64_u32 v[108:109], s[30:31], v127, s81, v[12:13]
	v_mad_u64_u32 v[110:111], s[30:31], v126, s81, v[12:13]
	v_mad_u64_u32 v[112:113], s[30:31], v129, s81, v[12:13]
	v_mad_u64_u32 v[114:115], s[30:31], v128, s81, v[12:13]
	v_mad_u64_u32 v[116:117], s[30:31], v131, s81, v[12:13]
	v_mad_u64_u32 v[118:119], s[30:31], v130, s81, v[12:13]
	v_mad_u64_u32 v[120:121], s[30:31], v133, s81, v[12:13]
	v_mad_u64_u32 v[122:123], s[30:31], v132, s81, v[12:13]
	v_mad_u64_u32 v[124:125], s[30:31], v135, s81, v[12:13]
	v_mad_u64_u32 v[126:127], s[30:31], v134, s81, v[12:13]
	v_mad_u64_u32 v[128:129], s[30:31], v138, s81, v[12:13]
	v_mad_u64_u32 v[130:131], s[30:31], v137, s81, v[12:13]
	v_mad_u64_u32 v[132:133], s[30:31], v140, s81, v[12:13]
	v_mad_u64_u32 v[134:135], s[30:31], v139, s81, v[12:13]
	s_waitcnt vmcnt(31)
	ds_write_b32 v104, v141
	s_waitcnt vmcnt(30)
	ds_write_b32 v106, v142
	s_waitcnt vmcnt(29)
	ds_write_b32 v108, v143
	s_waitcnt vmcnt(28)
	ds_write_b32 v110, v144
	s_waitcnt vmcnt(20)
	ds_write_b32 v112, v152
	ds_write_b32 v114, v145
	ds_write_b32 v116, v151
	ds_write_b32 v118, v146
	s_waitcnt vmcnt(16)
	ds_write_b32 v120, v155
	ds_write_b32 v122, v147
	ds_write_b32 v124, v154
	ds_write_b32 v126, v148
	ds_write_b32 v128, v153
	ds_write_b32 v130, v149
	ds_write_b32 v132, v102
	ds_write_b32 v134, v150
	v_mad_u64_u32 v[4:5], s[30:31], v45, s81, v[12:13]
	v_mad_u64_u32 v[6:7], s[30:31], v39, s81, v[12:13]
	v_mad_u64_u32 v[8:9], s[30:31], v63, s81, v[12:13]
	v_mad_u64_u32 v[46:47], s[30:31], v62, s81, v[12:13]
	v_mad_u64_u32 v[48:49], s[30:31], v65, s81, v[12:13]
	v_mad_u64_u32 v[50:51], s[30:31], v64, s81, v[12:13]
	v_mad_u64_u32 v[52:53], s[30:31], v67, s81, v[12:13]
	v_mad_u64_u32 v[54:55], s[30:31], v66, s81, v[12:13]
	v_mad_u64_u32 v[56:57], s[30:31], v69, s81, v[12:13]
	v_mad_u64_u32 v[58:59], s[30:31], v68, s81, v[12:13]
	v_mad_u64_u32 v[60:61], s[30:31], v71, s81, v[12:13]
	v_mad_u64_u32 v[62:63], s[30:31], v70, s81, v[12:13]
	v_mad_u64_u32 v[64:65], s[30:31], v73, s81, v[12:13]
	v_mad_u64_u32 v[66:67], s[30:31], v72, s81, v[12:13]
	v_mad_u64_u32 v[68:69], s[30:31], v75, s81, v[12:13]
	v_mad_u64_u32 v[70:71], s[30:31], v74, s81, v[12:13]
	s_waitcnt vmcnt(15)
	ds_write_b32 v4, v76
	s_waitcnt vmcnt(14)
	ds_write_b32 v6, v77
	s_waitcnt vmcnt(13)
	ds_write_b32 v8, v78
	s_waitcnt vmcnt(12)
	ds_write_b32 v46, v79
	s_waitcnt vmcnt(4)
	ds_write_b32 v48, v87
	ds_write_b32 v50, v80
	ds_write_b32 v52, v86
	ds_write_b32 v54, v81
	s_waitcnt vmcnt(0)
	ds_write_b32 v56, v90
	ds_write_b32 v58, v82
	ds_write_b32 v60, v89
	ds_write_b32 v62, v83
	ds_write_b32 v64, v88
	ds_write_b32 v66, v84
	ds_write_b32 v68, v0
	ds_write_b32 v70, v85
	s_add_i32 s25, s25, 16
	s_add_i32 s24, s24, 16
	s_add_i32 s26, s26, -16
	s_cmp_lg_u32 s26, 0
	s_waitcnt lgkmcnt(0)
	ds_read2_b32 v[6:7], v41 offset0:33 offset1:41
	ds_read2_b32 v[8:9], v41 offset1:8
	ds_read2_b32 v[46:47], v41 offset0:66 offset1:74
	ds_read2_b32 v[48:49], v41 offset0:99 offset1:107
	ds_read2_b32 v[50:51], v41 offset0:132 offset1:140
	ds_read2_b32 v[52:53], v41 offset0:165 offset1:173
	ds_read2_b32 v[54:55], v41 offset0:198 offset1:206
	ds_read2_b32 v[56:57], v41 offset0:231 offset1:239
	s_and_b32 s22, 0xffff, s22
	s_lshl_b32 s0, s0, 1
	v_or_b32_e32 v0, s22, v40
	v_lshl_add_u64 v[58:59], v[22:23], 0, s[0:1]
	v_lshlrev_b32_e32 v0, 11, v0
	v_lshl_add_u64 v[60:61], v[58:59], 0, v[0:1]
	s_waitcnt lgkmcnt(6)
	v_cvt_pk_bf16_f32 v2, v8, v6
	s_waitcnt lgkmcnt(4)
	v_cvt_pk_bf16_f32 v3, v46, v48
	s_waitcnt lgkmcnt(2)
	v_cvt_pk_bf16_f32 v4, v50, v52
	s_waitcnt lgkmcnt(0)
	v_cvt_pk_bf16_f32 v5, v54, v56
	global_store_dwordx4 v[60:61], v[2:5], off
	v_or_b32_e32 v0, s22, v42
	v_lshlrev_b32_e32 v0, 11, v0
	v_cvt_pk_bf16_f32 v2, v9, v7
	v_cvt_pk_bf16_f32 v3, v47, v49
	v_cvt_pk_bf16_f32 v4, v51, v53
	v_cvt_pk_bf16_f32 v5, v55, v57
	ds_read2_b32 v[8:9], v41 offset0:16 offset1:24
	ds_read2_b32 v[46:47], v41 offset0:49 offset1:57
	ds_read2_b32 v[48:49], v41 offset0:82 offset1:90
	ds_read2_b32 v[50:51], v41 offset0:115 offset1:123
	ds_read2_b32 v[52:53], v41 offset0:148 offset1:156
	ds_read2_b32 v[54:55], v41 offset0:181 offset1:189
	ds_read2_b32 v[56:57], v41 offset0:214 offset1:222
	ds_read2_b32 v[60:61], v41 offset0:247 offset1:255
	v_lshl_add_u64 v[6:7], v[58:59], 0, v[0:1]
	v_or_b32_e32 v0, s22, v43
	v_lshlrev_b32_e32 v0, 11, v0
	global_store_dwordx4 v[6:7], v[2:5], off
	v_lshl_add_u64 v[6:7], v[58:59], 0, v[0:1]
	v_or_b32_e32 v0, s22, v44
	v_lshlrev_b32_e32 v0, 11, v0
	s_waitcnt lgkmcnt(6)
	v_cvt_pk_bf16_f32 v2, v8, v46
	s_waitcnt lgkmcnt(4)
	v_cvt_pk_bf16_f32 v3, v48, v50
	s_waitcnt lgkmcnt(2)
	v_cvt_pk_bf16_f32 v4, v52, v54
	s_waitcnt lgkmcnt(0)
	v_cvt_pk_bf16_f32 v5, v56, v60
	global_store_dwordx4 v[6:7], v[2:5], off
	v_lshl_add_u64 v[6:7], v[58:59], 0, v[0:1]
	s_nop 0
	v_cvt_pk_bf16_f32 v2, v9, v47
	v_cvt_pk_bf16_f32 v3, v49, v51
	v_cvt_pk_bf16_f32 v4, v53, v55
	v_cvt_pk_bf16_f32 v5, v57, v61
	global_store_dwordx4 v[6:7], v[2:5], off
	s_waitcnt lgkmcnt(0)

; __device__ __forceinline__ void cvt_item(gfp W, int N, bf16* WT, int Kd, int k0, int n0, int drow0, LAS float* scr, int lane, gfp gk) {
; #pragma unroll 8
;     for (int i = 0; i < 32; ++i) { const int kk = 2 * i + (lane >> 5); scr[kk * 33 + (lane & 31)] = W[(size_t)(k0 + kk) * N + n0 + (lane & 31)]; }
.LBB0_142:
	v_mov_b32_e32 v103, v1
	s_lshl_b32 s33, s27, 1
	s_lshl_b32 s31, s26, 1
	v_or_b32_e32 v136, s33, v10
	s_add_i32 s35, s33, 4
	s_add_i32 s34, s31, 4
	s_add_i32 s36, s31, 8
	s_add_i32 s37, s33, 8
	v_add_u32_e32 v102, s0, v136
	v_or_b32_e32 v127, s35, v10
	v_or_b32_e32 v101, s31, v11
	s_add_i32 s38, s31, 12
	s_add_i32 s39, s33, 12
	s_add_i32 s40, s31, 16
	s_add_i32 s42, s31, 20
	s_add_i32 s44, s31, 24
	s_add_i32 s31, s31, 28
	v_or_b32_e32 v126, s34, v11
	v_or_b32_e32 v128, s36, v11
	v_or_b32_e32 v129, s37, v10
	v_lshlrev_b64 v[120:121], 13, v[102:103]
	v_add_u32_e32 v102, s0, v127
	v_mov_b32_e32 v105, v103
	v_mov_b32_e32 v107, v103
	v_mov_b32_e32 v109, v103
	s_add_i32 s41, s33, 16
	v_add_u32_e32 v104, s25, v101
	v_or_b32_e32 v130, s38, v11
	v_or_b32_e32 v131, s39, v10
	v_or_b32_e32 v132, s40, v11
	v_or_b32_e32 v134, s42, v11
	v_or_b32_e32 v137, s44, v11
	v_or_b32_e32 v139, s31, v11
	v_add_u32_e32 v106, s25, v126
	v_add_u32_e32 v108, s25, v128
	v_lshlrev_b64 v[122:123], 13, v[102:103]
	v_add_u32_e32 v102, s0, v129
	v_mov_b32_e32 v111, v103
	v_mov_b32_e32 v113, v103
	v_mov_b32_e32 v115, v103
	v_mov_b32_e32 v117, v103
	v_mov_b32_e32 v119, v103
	s_add_i32 s43, s33, 20
	v_or_b32_e32 v133, s41, v10
	v_lshlrev_b64 v[104:105], 13, v[104:105]
	v_add_u32_e32 v110, s25, v130
	v_add_u32_e32 v112, s25, v132
	v_add_u32_e32 v114, s25, v134
	v_add_u32_e32 v116, s25, v137
	v_add_u32_e32 v118, s25, v139
	v_lshl_add_u64 v[120:121], v[2:3], 0, v[120:121]
	v_lshlrev_b64 v[106:107], 13, v[106:107]
	v_lshlrev_b64 v[108:109], 13, v[108:109]
	v_lshlrev_b64 v[124:125], 13, v[102:103]
	v_add_u32_e32 v102, s0, v131
	s_add_i32 s45, s33, 24
	v_or_b32_e32 v135, s43, v10
	v_lshl_add_u64 v[104:105], v[2:3], 0, v[104:105]
	v_lshlrev_b64 v[110:111], 13, v[110:111]
	v_lshlrev_b64 v[112:113], 13, v[112:113]
	v_lshlrev_b64 v[114:115], 13, v[114:115]
	v_lshlrev_b64 v[116:117], 13, v[116:117]
	v_lshlrev_b64 v[118:119], 13, v[118:119]
	v_lshl_add_u64 v[122:123], v[2:3], 0, v[122:123]
	v_lshl_add_u64 v[106:107], v[2:3], 0, v[106:107]
	v_lshl_add_u64 v[108:109], v[2:3], 0, v[108:109]
	global_load_dword v141, v[120:121], off nt
	global_load_dword v142, v[104:105], off nt
	v_lshlrev_b64 v[120:121], 13, v[102:103]
	v_add_u32_e32 v102, s0, v133
	s_add_i32 s33, s33, 28
	v_or_b32_e32 v138, s45, v10
	v_lshl_add_u64 v[110:111], v[2:3], 0, v[110:111]
	v_lshl_add_u64 v[112:113], v[2:3], 0, v[112:113]
	v_lshl_add_u64 v[114:115], v[2:3], 0, v[114:115]
	v_lshl_add_u64 v[116:117], v[2:3], 0, v[116:117]
	v_lshl_add_u64 v[118:119], v[2:3], 0, v[118:119]
	global_load_dword v143, v[122:123], off nt
	global_load_dword v144, v[106:107], off nt
	global_load_dword v145, v[108:109], off nt
	global_load_dword v146, v[110:111], off nt
	global_load_dword v147, v[112:113], off nt
	global_load_dword v148, v[114:115], off nt
	global_load_dword v149, v[116:117], off nt
	global_load_dword v150, v[118:119], off nt
	v_lshl_add_u64 v[106:107], v[2:3], 0, v[120:121]
	v_lshlrev_b64 v[108:109], 13, v[102:103]
	v_add_u32_e32 v102, s0, v135
	v_or_b32_e32 v140, s33, v10
	v_lshl_add_u64 v[104:105], v[2:3], 0, v[124:125]
	global_load_dword v151, v[106:107], off nt
	global_load_dword v152, v[104:105], off nt
	v_lshlrev_b64 v[106:107], 13, v[102:103]
	v_add_u32_e32 v102, s0, v138
	v_lshl_add_u64 v[104:105], v[2:3], 0, v[108:109]
	v_lshlrev_b64 v[108:109], 13, v[102:103]
	v_add_u32_e32 v102, s0, v140
	v_lshlrev_b64 v[110:111], 13, v[102:103]
	v_lshl_add_u64 v[110:111], v[2:3], 0, v[110:111]
	v_lshl_add_u64 v[106:107], v[2:3], 0, v[106:107]
	v_lshl_add_u64 v[108:109], v[2:3], 0, v[108:109]
	global_load_dword v102, v[110:111], off nt
	global_load_dword v153, v[108:109], off nt
	global_load_dword v154, v[106:107], off nt
	global_load_dword v155, v[104:105], off nt
	s_add_i32 s27, s27, 16
	s_add_i32 s26, s26, 16
	s_add_i32 s30, s30, -16
	s_cmp_lg_u32 s30, 0
	s_lshl_b32 s33, s27, 1
	s_lshl_b32 s31, s26, 1
	v_or_b32_e32 v45, s33, v10
	s_add_i32 s35, s33, 4
	s_add_i32 s34, s31, 4
	s_add_i32 s36, s31, 8
	s_add_i32 s37, s33, 8
	v_add_u32_e32 v0, s0, v45
	v_or_b32_e32 v63, s35, v10
	v_or_b32_e32 v39, s31, v11
	s_add_i32 s38, s31, 12
	s_add_i32 s39, s33, 12
	s_add_i32 s40, s31, 16
	s_add_i32 s42, s31, 20
	s_add_i32 s44, s31, 24
	s_add_i32 s31, s31, 28
	v_or_b32_e32 v62, s34, v11
	v_or_b32_e32 v64, s36, v11
	v_or_b32_e32 v65, s37, v10
	v_lshlrev_b64 v[56:57], 13, v[0:1]
	v_add_u32_e32 v0, s0, v63
	v_mov_b32_e32 v5, v1
	v_mov_b32_e32 v7, v1
	v_mov_b32_e32 v9, v1
	s_add_i32 s41, s33, 16
	v_add_u32_e32 v4, s25, v39
	v_or_b32_e32 v66, s38, v11
	v_or_b32_e32 v67, s39, v10
	v_or_b32_e32 v68, s40, v11
	v_or_b32_e32 v70, s42, v11
	v_or_b32_e32 v72, s44, v11
	v_or_b32_e32 v74, s31, v11
	v_add_u32_e32 v6, s25, v62
	v_add_u32_e32 v8, s25, v64
	v_lshlrev_b64 v[58:59], 13, v[0:1]
	v_add_u32_e32 v0, s0, v65
	v_mov_b32_e32 v47, v1
	v_mov_b32_e32 v49, v1
	v_mov_b32_e32 v51, v1
	v_mov_b32_e32 v53, v1
	v_mov_b32_e32 v55, v1
	s_add_i32 s43, s33, 20
	v_or_b32_e32 v69, s41, v10
	v_lshlrev_b64 v[4:5], 13, v[4:5]
	v_add_u32_e32 v46, s25, v66
	v_add_u32_e32 v48, s25, v68
	v_add_u32_e32 v50, s25, v70
	v_add_u32_e32 v52, s25, v72
	v_add_u32_e32 v54, s25, v74
	v_lshl_add_u64 v[56:57], v[2:3], 0, v[56:57]
	v_lshlrev_b64 v[6:7], 13, v[6:7]
; #define GAS __attribute__((address_space(1)))
; __device__ __forceinline__ void cvt_item(gfp W, int N, bf16* WT, int Kd, int k0, int n0, int drow0, LAS float* scr, int lane, gfp gk) {
; #pragma unroll 8
;     for (int i = 0; i < 32; ++i) { const int kk = 2 * i + (lane >> 5); scr[kk * 33 + (lane & 31)] = W[(size_t)(k0 + kk) * N + n0 + (lane & 31)]; }
;     const int c = lane & 7;
;     f32x4 ga = (f32x4){1.f, 1.f, 1.f, 1.f}, gb = ga;
;     if (gk != nullptr) { ga = *(const GAS f32x4*)(gk + k0 + 8 * c); gb = *(const GAS f32x4*)(gk + k0 + 8 * c + 4); }
	v_lshlrev_b64 v[8:9], 13, v[8:9]
	v_lshlrev_b64 v[60:61], 13, v[0:1]
	v_add_u32_e32 v0, s0, v67
	s_add_i32 s45, s33, 24
	v_or_b32_e32 v71, s43, v10
	v_lshl_add_u64 v[4:5], v[2:3], 0, v[4:5]
	v_lshlrev_b64 v[46:47], 13, v[46:47]
	v_lshlrev_b64 v[48:49], 13, v[48:49]
	v_lshlrev_b64 v[50:51], 13, v[50:51]
	v_lshlrev_b64 v[52:53], 13, v[52:53]
	v_lshlrev_b64 v[54:55], 13, v[54:55]
	v_lshl_add_u64 v[58:59], v[2:3], 0, v[58:59]
	v_lshl_add_u64 v[6:7], v[2:3], 0, v[6:7]
	v_lshl_add_u64 v[8:9], v[2:3], 0, v[8:9]
	global_load_dword v76, v[56:57], off nt
	global_load_dword v77, v[4:5], off nt
	v_lshlrev_b64 v[56:57], 13, v[0:1]
	v_add_u32_e32 v0, s0, v69
	s_add_i32 s33, s33, 28
	v_or_b32_e32 v73, s45, v10
	v_lshl_add_u64 v[46:47], v[2:3], 0, v[46:47]
	v_lshl_add_u64 v[48:49], v[2:3], 0, v[48:49]
	v_lshl_add_u64 v[50:51], v[2:3], 0, v[50:51]
	v_lshl_add_u64 v[52:53], v[2:3], 0, v[52:53]
	v_lshl_add_u64 v[54:55], v[2:3], 0, v[54:55]
	global_load_dword v78, v[58:59], off nt
	global_load_dword v79, v[6:7], off nt
	global_load_dword v80, v[8:9], off nt
	global_load_dword v81, v[46:47], off nt
	global_load_dword v82, v[48:49], off nt
	global_load_dword v83, v[50:51], off nt
	global_load_dword v84, v[52:53], off nt
	global_load_dword v85, v[54:55], off nt
	v_lshl_add_u64 v[6:7], v[2:3], 0, v[56:57]
	v_lshlrev_b64 v[8:9], 13, v[0:1]
	v_add_u32_e32 v0, s0, v71
	v_or_b32_e32 v75, s33, v10
	v_lshl_add_u64 v[4:5], v[2:3], 0, v[60:61]
	global_load_dword v86, v[6:7], off nt
	global_load_dword v87, v[4:5], off nt
	v_lshlrev_b64 v[6:7], 13, v[0:1]
	v_add_u32_e32 v0, s0, v73
	v_lshl_add_u64 v[4:5], v[2:3], 0, v[8:9]
	v_lshlrev_b64 v[8:9], 13, v[0:1]
	v_add_u32_e32 v0, s0, v75
	v_lshlrev_b64 v[46:47], 13, v[0:1]
	v_lshl_add_u64 v[46:47], v[2:3], 0, v[46:47]
	v_lshl_add_u64 v[6:7], v[2:3], 0, v[6:7]
	v_lshl_add_u64 v[8:9], v[2:3], 0, v[8:9]
	global_load_dword v0, v[46:47], off nt
	global_load_dword v88, v[8:9], off nt
	global_load_dword v89, v[6:7], off nt
	global_load_dword v90, v[4:5], off nt
	v_mad_u64_u32 v[104:105], s[34:35], v136, s81, v[12:13]
	v_mad_u64_u32 v[106:107], s[34:35], v101, s81, v[12:13]
	v_mad_u64_u32 v[108:109], s[34:35], v127, s81, v[12:13]
	v_mad_u64_u32 v[110:111], s[34:35], v126, s81, v[12:13]
	v_mad_u64_u32 v[112:113], s[34:35], v129, s81, v[12:13]
	v_mad_u64_u32 v[114:115], s[34:35], v128, s81, v[12:13]
	v_mad_u64_u32 v[116:117], s[34:35], v131, s81, v[12:13]
	v_mad_u64_u32 v[118:119], s[34:35], v130, s81, v[12:13]
	v_mad_u64_u32 v[120:121], s[34:35], v133, s81, v[12:13]
	v_mad_u64_u32 v[122:123], s[34:35], v132, s81, v[12:13]
	v_mad_u64_u32 v[124:125], s[34:35], v135, s81, v[12:13]
	v_mad_u64_u32 v[126:127], s[34:35], v134, s81, v[12:13]
	v_mad_u64_u32 v[128:129], s[34:35], v138, s81, v[12:13]
	v_mad_u64_u32 v[130:131], s[34:35], v137, s81, v[12:13]
	v_mad_u64_u32 v[132:133], s[34:35], v140, s81, v[12:13]
	v_mad_u64_u32 v[134:135], s[34:35], v139, s81, v[12:13]
	s_waitcnt vmcnt(31)
	ds_write_b32 v104, v141
	s_waitcnt vmcnt(30)
	ds_write_b32 v106, v142
	s_waitcnt vmcnt(29)
	ds_write_b32 v108, v143
	s_waitcnt vmcnt(28)
	ds_write_b32 v110, v144
	s_waitcnt vmcnt(20)
	ds_write_b32 v112, v152
	ds_write_b32 v114, v145
	ds_write_b32 v116, v151
	ds_write_b32 v118, v146
	s_waitcnt vmcnt(16)
	ds_write_b32 v120, v155
	ds_write_b32 v122, v147
	ds_write_b32 v124, v154
	ds_write_b32 v126, v148
	ds_write_b32 v128, v153
	ds_write_b32 v130, v149
	ds_write_b32 v132, v102
	ds_write_b32 v134, v150
	v_mad_u64_u32 v[4:5], s[34:35], v45, s81, v[12:13]
	v_mad_u64_u32 v[6:7], s[34:35], v39, s81, v[12:13]
	v_mad_u64_u32 v[8:9], s[34:35], v63, s81, v[12:13]
	v_mad_u64_u32 v[46:47], s[34:35], v62, s81, v[12:13]
	v_mad_u64_u32 v[48:49], s[34:35], v65, s81, v[12:13]
	v_mad_u64_u32 v[50:51], s[34:35], v64, s81, v[12:13]
	v_mad_u64_u32 v[52:53], s[34:35], v67, s81, v[12:13]
	v_mad_u64_u32 v[54:55], s[34:35], v66, s81, v[12:13]
	v_mad_u64_u32 v[56:57], s[34:35], v69, s81, v[12:13]
	v_mad_u64_u32 v[58:59], s[34:35], v68, s81, v[12:13]
	v_mad_u64_u32 v[60:61], s[34:35], v71, s81, v[12:13]
	v_mad_u64_u32 v[62:63], s[34:35], v70, s81, v[12:13]
	v_mad_u64_u32 v[64:65], s[34:35], v73, s81, v[12:13]
	v_mad_u64_u32 v[66:67], s[34:35], v72, s81, v[12:13]
	v_mad_u64_u32 v[68:69], s[34:35], v75, s81, v[12:13]
	v_mad_u64_u32 v[70:71], s[34:35], v74, s81, v[12:13]
	s_waitcnt vmcnt(15)
	ds_write_b32 v4, v76
	s_waitcnt vmcnt(14)
	ds_write_b32 v6, v77
	s_waitcnt vmcnt(13)
	ds_write_b32 v8, v78
	s_waitcnt vmcnt(12)
	ds_write_b32 v46, v79
	s_waitcnt vmcnt(4)
	ds_write_b32 v48, v87
	ds_write_b32 v50, v80
	ds_write_b32 v52, v86
	ds_write_b32 v54, v81
	s_waitcnt vmcnt(0)
	ds_write_b32 v56, v90
	ds_write_b32 v58, v82
	ds_write_b32 v60, v89
	ds_write_b32 v62, v83
	ds_write_b32 v64, v88
	ds_write_b32 v66, v84
	ds_write_b32 v68, v0
	ds_write_b32 v70, v85
	s_add_i32 s27, s27, 16
	s_add_i32 s26, s26, 16
	s_add_i32 s30, s30, -16
	s_cmp_lg_u32 s30, 0
	s_lshl_b64 s[26:27], s[6:7], 2
	s_add_u32 s22, s22, s26
	s_addc_u32 s23, s23, s27
	s_cmp_eq_u64 s[22:23], 0
	s_cbranch_scc1 .LBB0_146
	s_lshl_b32 s25, s0, 2
	s_add_u32 s22, s22, s25
	s_addc_u32 s23, s23, 0
	v_lshlrev_b32_e32 v0, 2, v14
	global_load_dwordx4 v[2:5], v0, s[22:23] offset:16
	global_load_dwordx4 v[6:9], v0, s[22:23]
	s_branch .LBB0_147

; __device__ __forceinline__ void cvt_item(gfp W, int N, bf16* WT, int Kd, int k0, int n0, int drow0, LAS float* scr, int lane, gfp gk) {
; #pragma unroll 8
;     for (int i = 0; i < 32; ++i) { const int kk = 2 * i + (lane >> 5); scr[kk * 33 + (lane & 31)] = W[(size_t)(k0 + kk) * N + n0 + (lane & 31)]; }
.LBB0_151:
	s_lshl_b32 s31, s26, 1
	s_lshl_b32 s33, s27, 1
	v_or_b32_e32 v101, s31, v11
	v_or_b32_e32 v134, s33, v10
	s_add_i32 s34, s31, 4
	s_add_i32 s35, s33, 4
	s_add_i32 s36, s31, 8
	s_add_i32 s37, s33, 8
	s_add_i32 s38, s31, 12
	s_add_i32 s39, s33, 12
	s_add_i32 s40, s31, 16
	s_add_i32 s41, s33, 16
	s_add_i32 s42, s31, 20
	s_add_i32 s43, s33, 20
	s_add_i32 s44, s31, 24
	s_add_i32 s45, s33, 24
	s_add_i32 s31, s31, 28
	s_add_i32 s33, s33, 28
	v_add_u32_e32 v102, s0, v134
	v_or_b32_e32 v135, s34, v11
	v_or_b32_e32 v136, s35, v10
	v_or_b32_e32 v137, s36, v11
	v_or_b32_e32 v138, s37, v10
	v_or_b32_e32 v139, s38, v11
	v_or_b32_e32 v140, s39, v10
	v_or_b32_e32 v141, s40, v11
	v_or_b32_e32 v142, s41, v10
	v_or_b32_e32 v143, s42, v11
	v_or_b32_e32 v144, s43, v10
	v_or_b32_e32 v145, s44, v11
	v_or_b32_e32 v146, s45, v10
	v_or_b32_e32 v147, s31, v11
	v_or_b32_e32 v148, s33, v10
	v_add_u32_e32 v104, s25, v101
	v_mad_u64_u32 v[102:103], s[34:35], v102, s47, v[2:3]
	v_add_u32_e32 v108, s25, v135
	v_add_u32_e32 v106, s0, v136
	v_add_u32_e32 v112, s25, v137
	v_add_u32_e32 v110, s0, v138
	v_add_u32_e32 v116, s25, v139
	v_add_u32_e32 v114, s0, v140
	v_add_u32_e32 v120, s25, v141
	v_add_u32_e32 v118, s0, v142
	v_add_u32_e32 v124, s25, v143
	v_add_u32_e32 v122, s0, v144
	v_add_u32_e32 v128, s25, v145
	v_add_u32_e32 v126, s0, v146
	v_add_u32_e32 v132, s25, v147
	v_add_u32_e32 v130, s0, v148
	v_mad_u64_u32 v[104:105], s[34:35], v104, s47, v[2:3]
	v_mad_u64_u32 v[106:107], s[34:35], v106, s47, v[2:3]
	v_mad_u64_u32 v[108:109], s[34:35], v108, s47, v[2:3]
	v_mad_u64_u32 v[110:111], s[34:35], v110, s47, v[2:3]
	v_mad_u64_u32 v[112:113], s[34:35], v112, s47, v[2:3]
	v_mad_u64_u32 v[114:115], s[34:35], v114, s47, v[2:3]
	v_mad_u64_u32 v[116:117], s[34:35], v116, s47, v[2:3]
	v_mad_u64_u32 v[118:119], s[34:35], v118, s47, v[2:3]
	v_mad_u64_u32 v[120:121], s[34:35], v120, s47, v[2:3]
	v_mad_u64_u32 v[122:123], s[34:35], v122, s47, v[2:3]
	v_mad_u64_u32 v[124:125], s[34:35], v124, s47, v[2:3]
	v_mad_u64_u32 v[126:127], s[34:35], v126, s47, v[2:3]
	v_mad_u64_u32 v[128:129], s[34:35], v128, s47, v[2:3]
	v_mad_u64_u32 v[130:131], s[34:35], v130, s47, v[2:3]
	v_mad_u64_u32 v[132:133], s[34:35], v132, s47, v[2:3]
	global_load_dword v149, v[102:103], off nt
	global_load_dword v150, v[104:105], off nt
	global_load_dword v151, v[106:107], off nt
	global_load_dword v152, v[108:109], off nt
	global_load_dword v153, v[110:111], off nt
	global_load_dword v154, v[112:113], off nt
	global_load_dword v155, v[114:115], off nt
	global_load_dword v156, v[116:117], off nt
	global_load_dword v157, v[118:119], off nt
	global_load_dword v158, v[120:121], off nt
	global_load_dword v159, v[122:123], off nt
	global_load_dword v160, v[124:125], off nt
	global_load_dword v161, v[126:127], off nt
	global_load_dword v162, v[128:129], off nt
	global_load_dword v163, v[130:131], off nt
	global_load_dword v164, v[132:133], off nt
	s_add_i32 s27, s27, 16
	s_add_i32 s26, s26, 16
	s_add_i32 s30, s30, -16
	s_cmp_lg_u32 s30, 0
	s_lshl_b32 s31, s26, 1
	s_lshl_b32 s33, s27, 1
	v_or_b32_e32 v0, s31, v11
	v_or_b32_e32 v39, s33, v10
	s_add_i32 s34, s31, 4
	s_add_i32 s35, s33, 4
	s_add_i32 s36, s31, 8
	s_add_i32 s37, s33, 8
	s_add_i32 s38, s31, 12
	s_add_i32 s39, s33, 12
	s_add_i32 s40, s31, 16
	s_add_i32 s41, s33, 16
	s_add_i32 s42, s31, 20
	s_add_i32 s43, s33, 20
	s_add_i32 s44, s31, 24
	s_add_i32 s45, s33, 24
	s_add_i32 s31, s31, 28
	s_add_i32 s33, s33, 28
	v_add_u32_e32 v4, s0, v39
	v_or_b32_e32 v45, s34, v11
	v_or_b32_e32 v72, s35, v10
	v_or_b32_e32 v73, s36, v11
	v_or_b32_e32 v74, s37, v10
	v_or_b32_e32 v75, s38, v11
	v_or_b32_e32 v76, s39, v10
	v_or_b32_e32 v77, s40, v11
	v_or_b32_e32 v78, s41, v10
	v_or_b32_e32 v79, s42, v11
	v_or_b32_e32 v80, s43, v10
	v_or_b32_e32 v81, s44, v11
	v_or_b32_e32 v82, s45, v10
	v_or_b32_e32 v83, s31, v11
	v_or_b32_e32 v84, s33, v10
	v_add_u32_e32 v6, s25, v0
	v_mad_u64_u32 v[4:5], s[34:35], v4, s47, v[2:3]
	v_add_u32_e32 v46, s25, v45
	v_add_u32_e32 v8, s0, v72
	v_add_u32_e32 v50, s25, v73
	v_add_u32_e32 v48, s0, v74
	v_add_u32_e32 v54, s25, v75
	v_add_u32_e32 v52, s0, v76
	v_add_u32_e32 v58, s25, v77
	v_add_u32_e32 v56, s0, v78
	v_add_u32_e32 v62, s25, v79
	v_add_u32_e32 v60, s0, v80
	v_add_u32_e32 v66, s25, v81
	v_add_u32_e32 v64, s0, v82
	v_add_u32_e32 v70, s25, v83
	v_add_u32_e32 v68, s0, v84
	v_mad_u64_u32 v[6:7], s[34:35], v6, s47, v[2:3]
	v_mad_u64_u32 v[8:9], s[34:35], v8, s47, v[2:3]
	v_mad_u64_u32 v[46:47], s[34:35], v46, s47, v[2:3]
	v_mad_u64_u32 v[48:49], s[34:35], v48, s47, v[2:3]
	v_mad_u64_u32 v[50:51], s[34:35], v50, s47, v[2:3]
	v_mad_u64_u32 v[52:53], s[34:35], v52, s47, v[2:3]
	v_mad_u64_u32 v[54:55], s[34:35], v54, s47, v[2:3]
	v_mad_u64_u32 v[56:57], s[34:35], v56, s47, v[2:3]
	v_mad_u64_u32 v[58:59], s[34:35], v58, s47, v[2:3]
	v_mad_u64_u32 v[60:61], s[34:35], v60, s47, v[2:3]
	v_mad_u64_u32 v[62:63], s[34:35], v62, s47, v[2:3]
	v_mad_u64_u32 v[64:65], s[34:35], v64, s47, v[2:3]
	v_mad_u64_u32 v[66:67], s[34:35], v66, s47, v[2:3]
	v_mad_u64_u32 v[68:69], s[34:35], v68, s47, v[2:3]
	v_mad_u64_u32 v[70:71], s[34:35], v70, s47, v[2:3]
	global_load_dword v85, v[4:5], off nt
	global_load_dword v86, v[6:7], off nt
	global_load_dword v87, v[8:9], off nt
	global_load_dword v88, v[46:47], off nt
	global_load_dword v89, v[48:49], off nt
	global_load_dword v90, v[50:51], off nt
	global_load_dword v91, v[52:53], off nt
	global_load_dword v92, v[54:55], off nt
	global_load_dword v93, v[56:57], off nt
	global_load_dword v94, v[58:59], off nt
	global_load_dword v95, v[60:61], off nt
	global_load_dword v96, v[62:63], off nt
	global_load_dword v97, v[64:65], off nt
	global_load_dword v98, v[66:67], off nt
	global_load_dword v99, v[68:69], off nt
	global_load_dword v100, v[70:71], off nt
	v_mad_u64_u32 v[102:103], s[34:35], v134, s81, v[12:13]
	v_mad_u64_u32 v[104:105], s[34:35], v101, s81, v[12:13]
	v_mad_u64_u32 v[106:107], s[34:35], v136, s81, v[12:13]
	v_mad_u64_u32 v[108:109], s[34:35], v135, s81, v[12:13]
	v_mad_u64_u32 v[110:111], s[34:35], v138, s81, v[12:13]
	v_mad_u64_u32 v[112:113], s[34:35], v137, s81, v[12:13]
	v_mad_u64_u32 v[114:115], s[34:35], v140, s81, v[12:13]
	v_mad_u64_u32 v[116:117], s[34:35], v139, s81, v[12:13]
	v_mad_u64_u32 v[118:119], s[34:35], v142, s81, v[12:13]
	v_mad_u64_u32 v[120:121], s[34:35], v141, s81, v[12:13]
	v_mad_u64_u32 v[122:123], s[34:35], v144, s81, v[12:13]
	v_mad_u64_u32 v[124:125], s[34:35], v143, s81, v[12:13]
	v_mad_u64_u32 v[126:127], s[34:35], v146, s81, v[12:13]
	v_mad_u64_u32 v[128:129], s[34:35], v145, s81, v[12:13]
	v_mad_u64_u32 v[130:131], s[34:35], v148, s81, v[12:13]
	v_mad_u64_u32 v[132:133], s[34:35], v147, s81, v[12:13]
	s_waitcnt vmcnt(31)
; #define GAS __attribute__((address_space(1)))
; __device__ __forceinline__ void cvt_item(gfp W, int N, bf16* WT, int Kd, int k0, int n0, int drow0, LAS float* scr, int lane, gfp gk) {
;     ...
;     for (int i = 0; i < 32; ++i) { const int kk = 2 * i + (lane >> 5); scr[kk * 33 + (lane & 31)] = W[(size_t)(k0 + kk) * N + n0 + (lane & 31)]; }
;     const int c = lane & 7;
;     f32x4 ga = (f32x4){1.f, 1.f, 1.f, 1.f}, gb = ga;
;     if (gk != nullptr) { ga = *(const GAS f32x4*)(gk + k0 + 8 * c); gb = *(const GAS f32x4*)(gk + k0 + 8 * c + 4); }
	ds_write_b32 v102, v149
	s_waitcnt vmcnt(30)
	ds_write_b32 v104, v150
	s_waitcnt vmcnt(29)
	ds_write_b32 v106, v151
	s_waitcnt vmcnt(28)
	ds_write_b32 v108, v152
	s_waitcnt vmcnt(27)
	ds_write_b32 v110, v153
	s_waitcnt vmcnt(26)
	ds_write_b32 v112, v154
	s_waitcnt vmcnt(25)
	ds_write_b32 v114, v155
	s_waitcnt vmcnt(24)
	ds_write_b32 v116, v156
	s_waitcnt vmcnt(23)
	ds_write_b32 v118, v157
	s_waitcnt vmcnt(22)
	ds_write_b32 v120, v158
	s_waitcnt vmcnt(21)
	ds_write_b32 v122, v159
	s_waitcnt vmcnt(20)
	ds_write_b32 v124, v160
	s_waitcnt vmcnt(19)
	ds_write_b32 v126, v161
	s_waitcnt vmcnt(18)
	ds_write_b32 v128, v162
	s_waitcnt vmcnt(17)
	ds_write_b32 v130, v163
	s_waitcnt vmcnt(16)
	ds_write_b32 v132, v164
	v_mad_u64_u32 v[4:5], s[34:35], v39, s81, v[12:13]
	v_mad_u64_u32 v[6:7], s[34:35], v0, s81, v[12:13]
	v_mad_u64_u32 v[8:9], s[34:35], v72, s81, v[12:13]
	v_mad_u64_u32 v[46:47], s[34:35], v45, s81, v[12:13]
	v_mad_u64_u32 v[48:49], s[34:35], v74, s81, v[12:13]
	v_mad_u64_u32 v[50:51], s[34:35], v73, s81, v[12:13]
	v_mad_u64_u32 v[52:53], s[34:35], v76, s81, v[12:13]
	v_mad_u64_u32 v[54:55], s[34:35], v75, s81, v[12:13]
	v_mad_u64_u32 v[56:57], s[34:35], v78, s81, v[12:13]
	v_mad_u64_u32 v[58:59], s[34:35], v77, s81, v[12:13]
	v_mad_u64_u32 v[60:61], s[34:35], v80, s81, v[12:13]
	v_mad_u64_u32 v[62:63], s[34:35], v79, s81, v[12:13]
	v_mad_u64_u32 v[64:65], s[34:35], v82, s81, v[12:13]
	v_mad_u64_u32 v[66:67], s[34:35], v81, s81, v[12:13]
	v_mad_u64_u32 v[68:69], s[34:35], v84, s81, v[12:13]
	v_mad_u64_u32 v[70:71], s[34:35], v83, s81, v[12:13]
	s_waitcnt vmcnt(15)
	ds_write_b32 v4, v85
	s_waitcnt vmcnt(14)
	ds_write_b32 v6, v86
	s_waitcnt vmcnt(13)
	ds_write_b32 v8, v87
	s_waitcnt vmcnt(12)
	ds_write_b32 v46, v88
	s_waitcnt vmcnt(11)
	ds_write_b32 v48, v89
	s_waitcnt vmcnt(10)
	ds_write_b32 v50, v90
	s_waitcnt vmcnt(9)
	ds_write_b32 v52, v91
	s_waitcnt vmcnt(8)
	ds_write_b32 v54, v92
	s_waitcnt vmcnt(7)
	ds_write_b32 v56, v93
	s_waitcnt vmcnt(6)
	ds_write_b32 v58, v94
	s_waitcnt vmcnt(5)
	ds_write_b32 v60, v95
	s_waitcnt vmcnt(4)
	ds_write_b32 v62, v96
	s_waitcnt vmcnt(3)
	ds_write_b32 v64, v97
	s_waitcnt vmcnt(2)
	ds_write_b32 v66, v98
	s_waitcnt vmcnt(1)
	ds_write_b32 v68, v99
	s_waitcnt vmcnt(0)
	ds_write_b32 v70, v100
	s_add_i32 s27, s27, 16
	s_add_i32 s26, s26, 16
	s_add_i32 s30, s30, -16
	s_cmp_lg_u32 s30, 0
	s_lshl_b64 s[26:27], s[6:7], 2
	s_add_u32 s22, s22, s26
	s_addc_u32 s23, s23, s27
	s_cmp_eq_u64 s[22:23], 0
	s_cbranch_scc1 .LBB0_154
	s_lshl_b32 s25, s0, 2
	s_add_u32 s22, s22, s25
	s_addc_u32 s23, s23, 0
	v_lshlrev_b32_e32 v0, 2, v14
	global_load_dwordx4 v[2:5], v0, s[22:23] offset:16
	global_load_dwordx4 v[6:9], v0, s[22:23]
	s_branch .LBB0_155

; __device__ __forceinline__ void cvt_item(gfp W, int N, bf16* WT, int Kd, int k0, int n0, int drow0, LAS float* scr, int lane, gfp gk) {
; #pragma unroll 8
;     for (int i = 0; i < 32; ++i) { const int kk = 2 * i + (lane >> 5); scr[kk * 33 + (lane & 31)] = W[(size_t)(k0 + kk) * N + n0 + (lane & 31)]; }
.LBB0_159:
	s_lshl_b32 s31, s26, 1
	s_lshl_b32 s33, s27, 1
	v_or_b32_e32 v101, s31, v11
	v_or_b32_e32 v134, s33, v10
	s_add_i32 s34, s31, 4
	s_add_i32 s35, s33, 4
	s_add_i32 s36, s31, 8
	s_add_i32 s37, s33, 8
	s_add_i32 s38, s31, 12
	s_add_i32 s39, s33, 12
	s_add_i32 s40, s31, 16
	s_add_i32 s41, s33, 16
	s_add_i32 s42, s31, 20
	s_add_i32 s43, s33, 20
	s_add_i32 s44, s31, 24
	s_add_i32 s45, s33, 24
	s_add_i32 s31, s31, 28
	s_add_i32 s33, s33, 28
	v_add_u32_e32 v102, s24, v134
	v_or_b32_e32 v135, s34, v11
	v_or_b32_e32 v136, s35, v10
	v_or_b32_e32 v137, s36, v11
	v_or_b32_e32 v138, s37, v10
	v_or_b32_e32 v139, s38, v11
	v_or_b32_e32 v140, s39, v10
	v_or_b32_e32 v141, s40, v11
	v_or_b32_e32 v142, s41, v10
	v_or_b32_e32 v143, s42, v11
	v_or_b32_e32 v144, s43, v10
	v_or_b32_e32 v145, s44, v11
	v_or_b32_e32 v146, s45, v10
	v_or_b32_e32 v147, s31, v11
	v_or_b32_e32 v148, s33, v10
	v_add_u32_e32 v104, s25, v101
	v_mad_u64_u32 v[102:103], s[34:35], v102, s48, v[2:3]
	v_add_u32_e32 v108, s25, v135
	v_add_u32_e32 v106, s24, v136
	v_add_u32_e32 v112, s25, v137
	v_add_u32_e32 v110, s24, v138
	v_add_u32_e32 v116, s25, v139
	v_add_u32_e32 v114, s24, v140
	v_add_u32_e32 v120, s25, v141
	v_add_u32_e32 v118, s24, v142
	v_add_u32_e32 v124, s25, v143
	v_add_u32_e32 v122, s24, v144
	v_add_u32_e32 v128, s25, v145
	v_add_u32_e32 v126, s24, v146
	v_add_u32_e32 v132, s25, v147
	v_add_u32_e32 v130, s24, v148
	v_mad_u64_u32 v[104:105], s[34:35], v104, s48, v[2:3]
	v_mad_u64_u32 v[106:107], s[34:35], v106, s48, v[2:3]
	v_mad_u64_u32 v[108:109], s[34:35], v108, s48, v[2:3]
	v_mad_u64_u32 v[110:111], s[34:35], v110, s48, v[2:3]
	v_mad_u64_u32 v[112:113], s[34:35], v112, s48, v[2:3]
	v_mad_u64_u32 v[114:115], s[34:35], v114, s48, v[2:3]
	v_mad_u64_u32 v[116:117], s[34:35], v116, s48, v[2:3]
	v_mad_u64_u32 v[118:119], s[34:35], v118, s48, v[2:3]
	v_mad_u64_u32 v[120:121], s[34:35], v120, s48, v[2:3]
	v_mad_u64_u32 v[122:123], s[34:35], v122, s48, v[2:3]
	v_mad_u64_u32 v[124:125], s[34:35], v124, s48, v[2:3]
	v_mad_u64_u32 v[126:127], s[34:35], v126, s48, v[2:3]
	v_mad_u64_u32 v[128:129], s[34:35], v128, s48, v[2:3]
	v_mad_u64_u32 v[130:131], s[34:35], v130, s48, v[2:3]
	v_mad_u64_u32 v[132:133], s[34:35], v132, s48, v[2:3]
	global_load_dword v149, v[102:103], off nt
	global_load_dword v150, v[104:105], off nt
	global_load_dword v151, v[106:107], off nt
	global_load_dword v152, v[108:109], off nt
	global_load_dword v153, v[110:111], off nt
	global_load_dword v154, v[112:113], off nt
	global_load_dword v155, v[114:115], off nt
	global_load_dword v156, v[116:117], off nt
	global_load_dword v157, v[118:119], off nt
	global_load_dword v158, v[120:121], off nt
	global_load_dword v159, v[122:123], off nt
	global_load_dword v160, v[124:125], off nt
	global_load_dword v161, v[126:127], off nt
	global_load_dword v162, v[128:129], off nt
	global_load_dword v163, v[130:131], off nt
	global_load_dword v164, v[132:133], off nt
	s_add_i32 s27, s27, 16
	s_add_i32 s26, s26, 16
	s_add_i32 s30, s30, -16
	s_cmp_lg_u32 s30, 0
	s_lshl_b32 s31, s26, 1
	s_lshl_b32 s33, s27, 1
	v_or_b32_e32 v0, s31, v11
	v_or_b32_e32 v39, s33, v10
	s_add_i32 s34, s31, 4
	s_add_i32 s35, s33, 4
	s_add_i32 s36, s31, 8
	s_add_i32 s37, s33, 8
	s_add_i32 s38, s31, 12
	s_add_i32 s39, s33, 12
	s_add_i32 s40, s31, 16
	s_add_i32 s41, s33, 16
	s_add_i32 s42, s31, 20
	s_add_i32 s43, s33, 20
	s_add_i32 s44, s31, 24
	s_add_i32 s45, s33, 24
	s_add_i32 s31, s31, 28
	s_add_i32 s33, s33, 28
	v_add_u32_e32 v4, s24, v39
	v_or_b32_e32 v45, s34, v11
	v_or_b32_e32 v72, s35, v10
	v_or_b32_e32 v73, s36, v11
	v_or_b32_e32 v74, s37, v10
	v_or_b32_e32 v75, s38, v11
	v_or_b32_e32 v76, s39, v10
	v_or_b32_e32 v77, s40, v11
	v_or_b32_e32 v78, s41, v10
	v_or_b32_e32 v79, s42, v11
	v_or_b32_e32 v80, s43, v10
	v_or_b32_e32 v81, s44, v11
	v_or_b32_e32 v82, s45, v10
	v_or_b32_e32 v83, s31, v11
	v_or_b32_e32 v84, s33, v10
	v_add_u32_e32 v6, s25, v0
	v_mad_u64_u32 v[4:5], s[34:35], v4, s48, v[2:3]
	v_add_u32_e32 v46, s25, v45
	v_add_u32_e32 v8, s24, v72
	v_add_u32_e32 v50, s25, v73
	v_add_u32_e32 v48, s24, v74
	v_add_u32_e32 v54, s25, v75
	v_add_u32_e32 v52, s24, v76
	v_add_u32_e32 v58, s25, v77
	v_add_u32_e32 v56, s24, v78
	v_add_u32_e32 v62, s25, v79
	v_add_u32_e32 v60, s24, v80
	v_add_u32_e32 v66, s25, v81
	v_add_u32_e32 v64, s24, v82
	v_add_u32_e32 v70, s25, v83
	v_add_u32_e32 v68, s24, v84
	v_mad_u64_u32 v[6:7], s[34:35], v6, s48, v[2:3]
	v_mad_u64_u32 v[8:9], s[34:35], v8, s48, v[2:3]
	v_mad_u64_u32 v[46:47], s[34:35], v46, s48, v[2:3]
	v_mad_u64_u32 v[48:49], s[34:35], v48, s48, v[2:3]
	v_mad_u64_u32 v[50:51], s[34:35], v50, s48, v[2:3]
	v_mad_u64_u32 v[52:53], s[34:35], v52, s48, v[2:3]
	v_mad_u64_u32 v[54:55], s[34:35], v54, s48, v[2:3]
	v_mad_u64_u32 v[56:57], s[34:35], v56, s48, v[2:3]
	v_mad_u64_u32 v[58:59], s[34:35], v58, s48, v[2:3]
	v_mad_u64_u32 v[60:61], s[34:35], v60, s48, v[2:3]
	v_mad_u64_u32 v[62:63], s[34:35], v62, s48, v[2:3]
	v_mad_u64_u32 v[64:65], s[34:35], v64, s48, v[2:3]
	v_mad_u64_u32 v[66:67], s[34:35], v66, s48, v[2:3]
	v_mad_u64_u32 v[68:69], s[34:35], v68, s48, v[2:3]
	v_mad_u64_u32 v[70:71], s[34:35], v70, s48, v[2:3]
	global_load_dword v85, v[4:5], off nt
	global_load_dword v86, v[6:7], off nt
	global_load_dword v87, v[8:9], off nt
	global_load_dword v88, v[46:47], off nt
	global_load_dword v89, v[48:49], off nt
	global_load_dword v90, v[50:51], off nt
	global_load_dword v91, v[52:53], off nt
	global_load_dword v92, v[54:55], off nt
	global_load_dword v93, v[56:57], off nt
	global_load_dword v94, v[58:59], off nt
	global_load_dword v95, v[60:61], off nt
	global_load_dword v96, v[62:63], off nt
	global_load_dword v97, v[64:65], off nt
	global_load_dword v98, v[66:67], off nt
	global_load_dword v99, v[68:69], off nt
	global_load_dword v100, v[70:71], off nt
	v_mad_u64_u32 v[102:103], s[34:35], v134, s81, v[12:13]
	v_mad_u64_u32 v[104:105], s[34:35], v101, s81, v[12:13]
	v_mad_u64_u32 v[106:107], s[34:35], v136, s81, v[12:13]
	v_mad_u64_u32 v[108:109], s[34:35], v135, s81, v[12:13]
	v_mad_u64_u32 v[110:111], s[34:35], v138, s81, v[12:13]
	v_mad_u64_u32 v[112:113], s[34:35], v137, s81, v[12:13]
	v_mad_u64_u32 v[114:115], s[34:35], v140, s81, v[12:13]
	v_mad_u64_u32 v[116:117], s[34:35], v139, s81, v[12:13]
	v_mad_u64_u32 v[118:119], s[34:35], v142, s81, v[12:13]
	v_mad_u64_u32 v[120:121], s[34:35], v141, s81, v[12:13]
	v_mad_u64_u32 v[122:123], s[34:35], v144, s81, v[12:13]
	v_mad_u64_u32 v[124:125], s[34:35], v143, s81, v[12:13]
	v_mad_u64_u32 v[126:127], s[34:35], v146, s81, v[12:13]
	v_mad_u64_u32 v[128:129], s[34:35], v145, s81, v[12:13]
	v_mad_u64_u32 v[130:131], s[34:35], v148, s81, v[12:13]
	v_mad_u64_u32 v[132:133], s[34:35], v147, s81, v[12:13]
	s_waitcnt vmcnt(31)
; #define GAS __attribute__((address_space(1)))
; __device__ __forceinline__ void cvt_item(gfp W, int N, bf16* WT, int Kd, int k0, int n0, int drow0, LAS float* scr, int lane, gfp gk) {
;     ...
;     for (int i = 0; i < 32; ++i) { const int kk = 2 * i + (lane >> 5); scr[kk * 33 + (lane & 31)] = W[(size_t)(k0 + kk) * N + n0 + (lane & 31)]; }
;     const int c = lane & 7;
;     f32x4 ga = (f32x4){1.f, 1.f, 1.f, 1.f}, gb = ga;
;     if (gk != nullptr) { ga = *(const GAS f32x4*)(gk + k0 + 8 * c); gb = *(const GAS f32x4*)(gk + k0 + 8 * c + 4); }
	ds_write_b32 v102, v149
	s_waitcnt vmcnt(30)
	ds_write_b32 v104, v150
	s_waitcnt vmcnt(29)
	ds_write_b32 v106, v151
	s_waitcnt vmcnt(28)
	ds_write_b32 v108, v152
	s_waitcnt vmcnt(27)
	ds_write_b32 v110, v153
	s_waitcnt vmcnt(26)
	ds_write_b32 v112, v154
	s_waitcnt vmcnt(25)
	ds_write_b32 v114, v155
	s_waitcnt vmcnt(24)
	ds_write_b32 v116, v156
	s_waitcnt vmcnt(23)
	ds_write_b32 v118, v157
	s_waitcnt vmcnt(22)
	ds_write_b32 v120, v158
	s_waitcnt vmcnt(21)
	ds_write_b32 v122, v159
	s_waitcnt vmcnt(20)
	ds_write_b32 v124, v160
	s_waitcnt vmcnt(19)
	ds_write_b32 v126, v161
	s_waitcnt vmcnt(18)
	ds_write_b32 v128, v162
	s_waitcnt vmcnt(17)
	ds_write_b32 v130, v163
	s_waitcnt vmcnt(16)
	ds_write_b32 v132, v164
	v_mad_u64_u32 v[4:5], s[34:35], v39, s81, v[12:13]
	v_mad_u64_u32 v[6:7], s[34:35], v0, s81, v[12:13]
	v_mad_u64_u32 v[8:9], s[34:35], v72, s81, v[12:13]
	v_mad_u64_u32 v[46:47], s[34:35], v45, s81, v[12:13]
	v_mad_u64_u32 v[48:49], s[34:35], v74, s81, v[12:13]
	v_mad_u64_u32 v[50:51], s[34:35], v73, s81, v[12:13]
	v_mad_u64_u32 v[52:53], s[34:35], v76, s81, v[12:13]
	v_mad_u64_u32 v[54:55], s[34:35], v75, s81, v[12:13]
	v_mad_u64_u32 v[56:57], s[34:35], v78, s81, v[12:13]
	v_mad_u64_u32 v[58:59], s[34:35], v77, s81, v[12:13]
	v_mad_u64_u32 v[60:61], s[34:35], v80, s81, v[12:13]
	v_mad_u64_u32 v[62:63], s[34:35], v79, s81, v[12:13]
	v_mad_u64_u32 v[64:65], s[34:35], v82, s81, v[12:13]
	v_mad_u64_u32 v[66:67], s[34:35], v81, s81, v[12:13]
	v_mad_u64_u32 v[68:69], s[34:35], v84, s81, v[12:13]
	v_mad_u64_u32 v[70:71], s[34:35], v83, s81, v[12:13]
	s_waitcnt vmcnt(15)
	ds_write_b32 v4, v85
	s_waitcnt vmcnt(14)
	ds_write_b32 v6, v86
	s_waitcnt vmcnt(13)
	ds_write_b32 v8, v87
	s_waitcnt vmcnt(12)
	ds_write_b32 v46, v88
	s_waitcnt vmcnt(11)
	ds_write_b32 v48, v89
	s_waitcnt vmcnt(10)
	ds_write_b32 v50, v90
	s_waitcnt vmcnt(9)
	ds_write_b32 v52, v91
	s_waitcnt vmcnt(8)
	ds_write_b32 v54, v92
	s_waitcnt vmcnt(7)
	ds_write_b32 v56, v93
	s_waitcnt vmcnt(6)
	ds_write_b32 v58, v94
	s_waitcnt vmcnt(5)
	ds_write_b32 v60, v95
	s_waitcnt vmcnt(4)
	ds_write_b32 v62, v96
	s_waitcnt vmcnt(3)
	ds_write_b32 v64, v97
	s_waitcnt vmcnt(2)
	ds_write_b32 v66, v98
	s_waitcnt vmcnt(1)
	ds_write_b32 v68, v99
	s_waitcnt vmcnt(0)
	ds_write_b32 v70, v100
	s_add_i32 s27, s27, 16
	s_add_i32 s26, s26, 16
	s_add_i32 s30, s30, -16
	s_cmp_lg_u32 s30, 0
	s_lshl_b64 s[26:27], s[8:9], 2
	s_add_u32 s22, s22, s26
	s_addc_u32 s23, s23, s27
	s_and_b32 s24, s24, 0xffff
	s_cmp_eq_u64 s[22:23], 0
	s_cbranch_scc1 .LBB0_162
	s_lshl_b32 s25, s24, 2
	s_add_u32 s22, s22, s25
	s_addc_u32 s23, s23, 0
	v_lshlrev_b32_e32 v0, 2, v14
	global_load_dwordx4 v[2:5], v0, s[22:23] offset:16
	global_load_dwordx4 v[6:9], v0, s[22:23]
	s_branch .LBB0_163

; __device__ __forceinline__ void cvt_item(gfp W, int N, bf16* WT, int Kd, int k0, int n0, int drow0, LAS float* scr, int lane, gfp gk) {
; #pragma unroll 8
;     for (int i = 0; i < 32; ++i) { const int kk = 2 * i + (lane >> 5); scr[kk * 33 + (lane & 31)] = W[(size_t)(k0 + kk) * N + n0 + (lane & 31)]; }
.LBB0_167:
	v_mov_b32_e32 v103, v1
	s_lshl_b32 s30, s25, 1
	s_lshl_b32 s27, s24, 1
	v_or_b32_e32 v136, s30, v10
	s_add_i32 s33, s30, 4
	s_add_i32 s31, s27, 4
	s_add_i32 s34, s27, 8
	s_add_i32 s35, s30, 8
	v_add_u32_e32 v102, s0, v136
	v_or_b32_e32 v127, s33, v10
	v_or_b32_e32 v101, s27, v11
	s_add_i32 s36, s27, 12
	s_add_i32 s37, s30, 12
	s_add_i32 s38, s27, 16
	s_add_i32 s40, s27, 20
	s_add_i32 s42, s27, 24
	s_add_i32 s27, s27, 28
	v_or_b32_e32 v126, s31, v11
	v_or_b32_e32 v128, s34, v11
	v_or_b32_e32 v129, s35, v10
	v_lshlrev_b64 v[120:121], 13, v[102:103]
	v_add_u32_e32 v102, s0, v127
	v_mov_b32_e32 v105, v103
	v_mov_b32_e32 v107, v103
	v_mov_b32_e32 v109, v103
	s_add_i32 s39, s30, 16
	v_add_u32_e32 v104, s23, v101
	v_or_b32_e32 v130, s36, v11
	v_or_b32_e32 v131, s37, v10
	v_or_b32_e32 v132, s38, v11
	v_or_b32_e32 v134, s40, v11
	v_or_b32_e32 v137, s42, v11
	v_or_b32_e32 v139, s27, v11
	v_add_u32_e32 v106, s23, v126
	v_add_u32_e32 v108, s23, v128
	v_lshlrev_b64 v[122:123], 13, v[102:103]
	v_add_u32_e32 v102, s0, v129
	v_mov_b32_e32 v111, v103
	v_mov_b32_e32 v113, v103
	v_mov_b32_e32 v115, v103
	v_mov_b32_e32 v117, v103
	v_mov_b32_e32 v119, v103
	s_add_i32 s41, s30, 20
	v_or_b32_e32 v133, s39, v10
	v_lshlrev_b64 v[104:105], 13, v[104:105]
	v_add_u32_e32 v110, s23, v130
	v_add_u32_e32 v112, s23, v132
	v_add_u32_e32 v114, s23, v134
	v_add_u32_e32 v116, s23, v137
	v_add_u32_e32 v118, s23, v139
	v_lshl_add_u64 v[120:121], v[2:3], 0, v[120:121]
	v_lshlrev_b64 v[106:107], 13, v[106:107]
	v_lshlrev_b64 v[108:109], 13, v[108:109]
	v_lshlrev_b64 v[124:125], 13, v[102:103]
	v_add_u32_e32 v102, s0, v131
	s_add_i32 s43, s30, 24
	v_or_b32_e32 v135, s41, v10
	v_lshl_add_u64 v[104:105], v[2:3], 0, v[104:105]
	v_lshlrev_b64 v[110:111], 13, v[110:111]
	v_lshlrev_b64 v[112:113], 13, v[112:113]
	v_lshlrev_b64 v[114:115], 13, v[114:115]
	v_lshlrev_b64 v[116:117], 13, v[116:117]
	v_lshlrev_b64 v[118:119], 13, v[118:119]
	v_lshl_add_u64 v[122:123], v[2:3], 0, v[122:123]
	v_lshl_add_u64 v[106:107], v[2:3], 0, v[106:107]
	v_lshl_add_u64 v[108:109], v[2:3], 0, v[108:109]
	global_load_dword v141, v[120:121], off nt
	global_load_dword v142, v[104:105], off nt
	v_lshlrev_b64 v[120:121], 13, v[102:103]
	v_add_u32_e32 v102, s0, v133
	s_add_i32 s30, s30, 28
	v_or_b32_e32 v138, s43, v10
	v_lshl_add_u64 v[110:111], v[2:3], 0, v[110:111]
	v_lshl_add_u64 v[112:113], v[2:3], 0, v[112:113]
	v_lshl_add_u64 v[114:115], v[2:3], 0, v[114:115]
	v_lshl_add_u64 v[116:117], v[2:3], 0, v[116:117]
	v_lshl_add_u64 v[118:119], v[2:3], 0, v[118:119]
	global_load_dword v143, v[122:123], off nt
	global_load_dword v144, v[106:107], off nt
	global_load_dword v145, v[108:109], off nt
	global_load_dword v146, v[110:111], off nt
	global_load_dword v147, v[112:113], off nt
	global_load_dword v148, v[114:115], off nt
	global_load_dword v149, v[116:117], off nt
	global_load_dword v150, v[118:119], off nt
	v_lshl_add_u64 v[106:107], v[2:3], 0, v[120:121]
	v_lshlrev_b64 v[108:109], 13, v[102:103]
	v_add_u32_e32 v102, s0, v135
	v_or_b32_e32 v140, s30, v10
	v_lshl_add_u64 v[104:105], v[2:3], 0, v[124:125]
	global_load_dword v151, v[106:107], off nt
	global_load_dword v152, v[104:105], off nt
	v_lshlrev_b64 v[106:107], 13, v[102:103]
	v_add_u32_e32 v102, s0, v138
	v_lshl_add_u64 v[104:105], v[2:3], 0, v[108:109]
	v_lshlrev_b64 v[108:109], 13, v[102:103]
	v_add_u32_e32 v102, s0, v140
	v_lshlrev_b64 v[110:111], 13, v[102:103]
	v_lshl_add_u64 v[110:111], v[2:3], 0, v[110:111]
	v_lshl_add_u64 v[106:107], v[2:3], 0, v[106:107]
	v_lshl_add_u64 v[108:109], v[2:3], 0, v[108:109]
	global_load_dword v102, v[110:111], off nt
	global_load_dword v153, v[108:109], off nt
	global_load_dword v154, v[106:107], off nt
	global_load_dword v155, v[104:105], off nt
	s_add_i32 s25, s25, 16
	s_add_i32 s24, s24, 16
	s_add_i32 s26, s26, -16
	s_cmp_lg_u32 s26, 0
	s_lshl_b32 s30, s25, 1
	s_lshl_b32 s27, s24, 1
	v_or_b32_e32 v45, s30, v10
	s_add_i32 s33, s30, 4
	s_add_i32 s31, s27, 4
	s_add_i32 s34, s27, 8
	s_add_i32 s35, s30, 8
	v_add_u32_e32 v0, s0, v45
	v_or_b32_e32 v63, s33, v10
	v_or_b32_e32 v39, s27, v11
	s_add_i32 s36, s27, 12
	s_add_i32 s37, s30, 12
	s_add_i32 s38, s27, 16
	s_add_i32 s40, s27, 20
	s_add_i32 s42, s27, 24
	s_add_i32 s27, s27, 28
	v_or_b32_e32 v62, s31, v11
	v_or_b32_e32 v64, s34, v11
	v_or_b32_e32 v65, s35, v10
	v_lshlrev_b64 v[56:57], 13, v[0:1]
	v_add_u32_e32 v0, s0, v63
	v_mov_b32_e32 v5, v1
	v_mov_b32_e32 v7, v1
	v_mov_b32_e32 v9, v1
	s_add_i32 s39, s30, 16
	v_add_u32_e32 v4, s23, v39
	v_or_b32_e32 v66, s36, v11
	v_or_b32_e32 v67, s37, v10
	v_or_b32_e32 v68, s38, v11
	v_or_b32_e32 v70, s40, v11
	v_or_b32_e32 v72, s42, v11
	v_or_b32_e32 v74, s27, v11
	v_add_u32_e32 v6, s23, v62
	v_add_u32_e32 v8, s23, v64
	v_lshlrev_b64 v[58:59], 13, v[0:1]
	v_add_u32_e32 v0, s0, v65
	v_mov_b32_e32 v47, v1
	v_mov_b32_e32 v49, v1
	v_mov_b32_e32 v51, v1
	v_mov_b32_e32 v53, v1
	v_mov_b32_e32 v55, v1
	s_add_i32 s41, s30, 20
	v_or_b32_e32 v69, s39, v10
	v_lshlrev_b64 v[4:5], 13, v[4:5]
	v_add_u32_e32 v46, s23, v66
	v_add_u32_e32 v48, s23, v68
	v_add_u32_e32 v50, s23, v70
	v_add_u32_e32 v52, s23, v72
	v_add_u32_e32 v54, s23, v74
	v_lshl_add_u64 v[56:57], v[2:3], 0, v[56:57]
	v_lshlrev_b64 v[6:7], 13, v[6:7]
	v_lshlrev_b64 v[8:9], 13, v[8:9]
	v_lshlrev_b64 v[60:61], 13, v[0:1]
	v_add_u32_e32 v0, s0, v67
	s_add_i32 s43, s30, 24
	v_or_b32_e32 v71, s41, v10
	v_lshl_add_u64 v[4:5], v[2:3], 0, v[4:5]
	v_lshlrev_b64 v[46:47], 13, v[46:47]
	v_lshlrev_b64 v[48:49], 13, v[48:49]
	v_lshlrev_b64 v[50:51], 13, v[50:51]
	v_lshlrev_b64 v[52:53], 13, v[52:53]
	v_lshlrev_b64 v[54:55], 13, v[54:55]
	v_lshl_add_u64 v[58:59], v[2:3], 0, v[58:59]
; #define GAS __attribute__((address_space(1)))
; #define LAS __attribute__((address_space(3)))
; #define LDS_WAIT() asm volatile("s_waitcnt lgkmcnt(0)" ::: "memory")
; __device__ __forceinline__ unsigned pk2(float lo, float hi) { unsigned r; asm("v_cvt_pk_bf16_f32 %0, %1, %2" : "=v"(r) : "v"(lo), "v"(hi)); return r; }
; __device__ __forceinline__ void cvt_item(gfp W, int N, bf16* WT, int Kd, int k0, int n0, int drow0, LAS float* scr, int lane, gfp gk) {
; #pragma unroll 8
;     for (int i = 0; i < 32; ++i) { const int kk = 2 * i + (lane >> 5); scr[kk * 33 + (lane & 31)] = W[(size_t)(k0 + kk) * N + n0 + (lane & 31)]; }
;     const int c = lane & 7;
;     f32x4 ga = (f32x4){1.f, 1.f, 1.f, 1.f}, gb = ga;
;     if (gk != nullptr) { ga = *(const GAS f32x4*)(gk + k0 + 8 * c); gb = *(const GAS f32x4*)(gk + k0 + 8 * c + 4); }
;     LDS_WAIT(); asm volatile("" ::: "memory");
; #pragma unroll
;     for (int j = 0; j < 4; ++j) { const int n = (lane >> 3) + 8 * j; const LAS float* s = scr + (8 * c) * 33 + n;
;         v4u o; o.x = pk2(s[0 * 33] * ga[0], s[1 * 33] * ga[1]); o.y = pk2(s[2 * 33] * ga[2], s[3 * 33] * ga[3]); o.z = pk2(s[4 * 33] * gb[0], s[5 * 33] * gb[1]); o.w = pk2(s[6 * 33] * gb[2], s[7 * 33] * gb[3]);
;         *(GAS v4u*)(WT + (size_t)(drow0 + n) * Kd + k0 + 8 * c) = o; }
;     LDS_WAIT(); asm volatile("" ::: "memory");
	v_lshl_add_u64 v[6:7], v[2:3], 0, v[6:7]
	v_lshl_add_u64 v[8:9], v[2:3], 0, v[8:9]
	global_load_dword v76, v[56:57], off nt
	global_load_dword v77, v[4:5], off nt
	v_lshlrev_b64 v[56:57], 13, v[0:1]
	v_add_u32_e32 v0, s0, v69
	s_add_i32 s30, s30, 28
	v_or_b32_e32 v73, s43, v10
	v_lshl_add_u64 v[46:47], v[2:3], 0, v[46:47]
	v_lshl_add_u64 v[48:49], v[2:3], 0, v[48:49]
	v_lshl_add_u64 v[50:51], v[2:3], 0, v[50:51]
	v_lshl_add_u64 v[52:53], v[2:3], 0, v[52:53]
	v_lshl_add_u64 v[54:55], v[2:3], 0, v[54:55]
	global_load_dword v78, v[58:59], off nt
	global_load_dword v79, v[6:7], off nt
	global_load_dword v80, v[8:9], off nt
	global_load_dword v81, v[46:47], off nt
	global_load_dword v82, v[48:49], off nt
	global_load_dword v83, v[50:51], off nt
	global_load_dword v84, v[52:53], off nt
	global_load_dword v85, v[54:55], off nt
	v_lshl_add_u64 v[6:7], v[2:3], 0, v[56:57]
	v_lshlrev_b64 v[8:9], 13, v[0:1]
	v_add_u32_e32 v0, s0, v71
	v_or_b32_e32 v75, s30, v10
	v_lshl_add_u64 v[4:5], v[2:3], 0, v[60:61]
	global_load_dword v86, v[6:7], off nt
	global_load_dword v87, v[4:5], off nt
	v_lshlrev_b64 v[6:7], 13, v[0:1]
	v_add_u32_e32 v0, s0, v73
	v_lshl_add_u64 v[4:5], v[2:3], 0, v[8:9]
	v_lshlrev_b64 v[8:9], 13, v[0:1]
	v_add_u32_e32 v0, s0, v75
	v_lshlrev_b64 v[46:47], 13, v[0:1]
	v_lshl_add_u64 v[46:47], v[2:3], 0, v[46:47]
	v_lshl_add_u64 v[6:7], v[2:3], 0, v[6:7]
	v_lshl_add_u64 v[8:9], v[2:3], 0, v[8:9]
	global_load_dword v0, v[46:47], off nt
	global_load_dword v88, v[8:9], off nt
	global_load_dword v89, v[6:7], off nt
	global_load_dword v90, v[4:5], off nt
	v_mad_u64_u32 v[104:105], s[30:31], v136, s81, v[12:13]
	v_mad_u64_u32 v[106:107], s[30:31], v101, s81, v[12:13]
	v_mad_u64_u32 v[108:109], s[30:31], v127, s81, v[12:13]
	v_mad_u64_u32 v[110:111], s[30:31], v126, s81, v[12:13]
	v_mad_u64_u32 v[112:113], s[30:31], v129, s81, v[12:13]
	v_mad_u64_u32 v[114:115], s[30:31], v128, s81, v[12:13]
	v_mad_u64_u32 v[116:117], s[30:31], v131, s81, v[12:13]
	v_mad_u64_u32 v[118:119], s[30:31], v130, s81, v[12:13]
	v_mad_u64_u32 v[120:121], s[30:31], v133, s81, v[12:13]
	v_mad_u64_u32 v[122:123], s[30:31], v132, s81, v[12:13]
	v_mad_u64_u32 v[124:125], s[30:31], v135, s81, v[12:13]
	v_mad_u64_u32 v[126:127], s[30:31], v134, s81, v[12:13]
	v_mad_u64_u32 v[128:129], s[30:31], v138, s81, v[12:13]
	v_mad_u64_u32 v[130:131], s[30:31], v137, s81, v[12:13]
	v_mad_u64_u32 v[132:133], s[30:31], v140, s81, v[12:13]
	v_mad_u64_u32 v[134:135], s[30:31], v139, s81, v[12:13]
	s_waitcnt vmcnt(31)
	ds_write_b32 v104, v141
	s_waitcnt vmcnt(30)
	ds_write_b32 v106, v142
	s_waitcnt vmcnt(29)
	ds_write_b32 v108, v143
	s_waitcnt vmcnt(28)
	ds_write_b32 v110, v144
	s_waitcnt vmcnt(20)
	ds_write_b32 v112, v152
	ds_write_b32 v114, v145
	ds_write_b32 v116, v151
	ds_write_b32 v118, v146
	s_waitcnt vmcnt(16)
	ds_write_b32 v120, v155
	ds_write_b32 v122, v147
	ds_write_b32 v124, v154
	ds_write_b32 v126, v148
	ds_write_b32 v128, v153
	ds_write_b32 v130, v149
	ds_write_b32 v132, v102
	ds_write_b32 v134, v150
	v_mad_u64_u32 v[4:5], s[30:31], v45, s81, v[12:13]
	v_mad_u64_u32 v[6:7], s[30:31], v39, s81, v[12:13]
	v_mad_u64_u32 v[8:9], s[30:31], v63, s81, v[12:13]
	v_mad_u64_u32 v[46:47], s[30:31], v62, s81, v[12:13]
	v_mad_u64_u32 v[48:49], s[30:31], v65, s81, v[12:13]
	v_mad_u64_u32 v[50:51], s[30:31], v64, s81, v[12:13]
	v_mad_u64_u32 v[52:53], s[30:31], v67, s81, v[12:13]
	v_mad_u64_u32 v[54:55], s[30:31], v66, s81, v[12:13]
	v_mad_u64_u32 v[56:57], s[30:31], v69, s81, v[12:13]
	v_mad_u64_u32 v[58:59], s[30:31], v68, s81, v[12:13]
	v_mad_u64_u32 v[60:61], s[30:31], v71, s81, v[12:13]
	v_mad_u64_u32 v[62:63], s[30:31], v70, s81, v[12:13]
	v_mad_u64_u32 v[64:65], s[30:31], v73, s81, v[12:13]
	v_mad_u64_u32 v[66:67], s[30:31], v72, s81, v[12:13]
	v_mad_u64_u32 v[68:69], s[30:31], v75, s81, v[12:13]
	v_mad_u64_u32 v[70:71], s[30:31], v74, s81, v[12:13]
	s_waitcnt vmcnt(15)
	ds_write_b32 v4, v76
	s_waitcnt vmcnt(14)
	ds_write_b32 v6, v77
	s_waitcnt vmcnt(13)
	ds_write_b32 v8, v78
	s_waitcnt vmcnt(12)
	ds_write_b32 v46, v79
	s_waitcnt vmcnt(4)
	ds_write_b32 v48, v87
	ds_write_b32 v50, v80
	ds_write_b32 v52, v86
	ds_write_b32 v54, v81
	s_waitcnt vmcnt(0)
	ds_write_b32 v56, v90
	ds_write_b32 v58, v82
	ds_write_b32 v60, v89
	ds_write_b32 v62, v83
	ds_write_b32 v64, v88
	ds_write_b32 v66, v84
	ds_write_b32 v68, v0
	ds_write_b32 v70, v85
	s_add_i32 s25, s25, 16
	s_add_i32 s24, s24, 16
	s_add_i32 s26, s26, -16
	s_cmp_lg_u32 s26, 0
	s_and_b32 s22, 0xffff, s22
	s_waitcnt lgkmcnt(0)
	v_or_b32_e32 v0, s22, v40
	s_lshl_b32 s0, s0, 1
	ds_read2_b32 v[6:7], v41 offset0:33 offset1:41
	ds_read2_b32 v[8:9], v41 offset1:8
	ds_read2_b32 v[46:47], v41 offset0:66 offset1:74
	ds_read2_b32 v[48:49], v41 offset0:99 offset1:107
	ds_read2_b32 v[50:51], v41 offset0:132 offset1:140
	ds_read2_b32 v[52:53], v41 offset0:165 offset1:173
	ds_read2_b32 v[54:55], v41 offset0:198 offset1:206
	ds_read2_b32 v[56:57], v41 offset0:231 offset1:239
	v_mul_u32_u24_e32 v0, 0x1600, v0
	v_lshl_add_u64 v[58:59], v[24:25], 0, s[0:1]
	v_lshlrev_b32_e32 v0, 1, v0
	v_lshl_add_u64 v[60:61], v[58:59], 0, v[0:1]
	v_or_b32_e32 v0, s22, v42
	v_mul_u32_u24_e32 v0, 0x1600, v0
	s_waitcnt lgkmcnt(6)
	v_cvt_pk_bf16_f32 v2, v8, v6
	v_lshlrev_b32_e32 v0, 1, v0
	s_waitcnt lgkmcnt(4)
	v_cvt_pk_bf16_f32 v3, v46, v48
	s_waitcnt lgkmcnt(2)
	v_cvt_pk_bf16_f32 v4, v50, v52
	s_waitcnt lgkmcnt(0)
	v_cvt_pk_bf16_f32 v5, v54, v56
	global_store_dwordx4 v[60:61], v[2:5], off
	s_nop 1
	v_cvt_pk_bf16_f32 v2, v9, v7
	v_lshl_add_u64 v[6:7], v[58:59], 0, v[0:1]
	v_or_b32_e32 v0, s22, v43
	v_cvt_pk_bf16_f32 v3, v47, v49
	v_cvt_pk_bf16_f32 v4, v51, v53
	v_cvt_pk_bf16_f32 v5, v55, v57
	ds_read2_b32 v[8:9], v41 offset0:16 offset1:24
	ds_read2_b32 v[46:47], v41 offset0:49 offset1:57
	ds_read2_b32 v[48:49], v41 offset0:82 offset1:90
	ds_read2_b32 v[50:51], v41 offset0:115 offset1:123
	ds_read2_b32 v[52:53], v41 offset0:148 offset1:156
	ds_read2_b32 v[54:55], v41 offset0:181 offset1:189
	ds_read2_b32 v[56:57], v41 offset0:214 offset1:222
	ds_read2_b32 v[60:61], v41 offset0:247 offset1:255
	v_mul_u32_u24_e32 v0, 0x1600, v0
	v_lshlrev_b32_e32 v0, 1, v0
	global_store_dwordx4 v[6:7], v[2:5], off
	v_lshl_add_u64 v[6:7], v[58:59], 0, v[0:1]
	v_or_b32_e32 v0, s22, v44
	v_mul_u32_u24_e32 v0, 0x1600, v0
	v_lshlrev_b32_e32 v0, 1, v0
	s_waitcnt lgkmcnt(6)
	v_cvt_pk_bf16_f32 v2, v8, v46
	s_waitcnt lgkmcnt(4)
	v_cvt_pk_bf16_f32 v3, v48, v50
	s_waitcnt lgkmcnt(2)
	v_cvt_pk_bf16_f32 v4, v52, v54
	s_waitcnt lgkmcnt(0)
	v_cvt_pk_bf16_f32 v5, v56, v60
	global_store_dwordx4 v[6:7], v[2:5], off
	v_lshl_add_u64 v[6:7], v[58:59], 0, v[0:1]
	s_nop 0
	v_cvt_pk_bf16_f32 v2, v9, v47
	v_cvt_pk_bf16_f32 v3, v49, v51
	v_cvt_pk_bf16_f32 v4, v53, v55
	v_cvt_pk_bf16_f32 v5, v57, v61
	global_store_dwordx4 v[6:7], v[2:5], off
	s_waitcnt lgkmcnt(0)

; __device__ __forceinline__ void cvt_item(gfp W, int N, bf16* WT, int Kd, int k0, int n0, int drow0, LAS float* scr, int lane, gfp gk) {
; #pragma unroll 8
;     for (int i = 0; i < 32; ++i) { const int kk = 2 * i + (lane >> 5); scr[kk * 33 + (lane & 31)] = W[(size_t)(k0 + kk) * N + n0 + (lane & 31)]; }
.LBB0_172:
	v_mov_b32_e32 v103, v1
	s_lshl_b32 s30, s25, 1
	s_lshl_b32 s27, s24, 1
	v_or_b32_e32 v136, s30, v10
	s_add_i32 s33, s30, 4
	s_add_i32 s31, s27, 4
	s_add_i32 s34, s27, 8
	s_add_i32 s35, s30, 8
	v_add_u32_e32 v102, s0, v136
	v_or_b32_e32 v127, s33, v10
	v_or_b32_e32 v101, s27, v11
	s_add_i32 s36, s27, 12
	s_add_i32 s37, s30, 12
	s_add_i32 s38, s27, 16
	s_add_i32 s40, s27, 20
	s_add_i32 s42, s27, 24
	s_add_i32 s27, s27, 28
	v_or_b32_e32 v126, s31, v11
	v_or_b32_e32 v128, s34, v11
	v_or_b32_e32 v129, s35, v10
	v_lshlrev_b64 v[120:121], 13, v[102:103]
	v_add_u32_e32 v102, s0, v127
	v_mov_b32_e32 v105, v103
	v_mov_b32_e32 v107, v103
	v_mov_b32_e32 v109, v103
	s_add_i32 s39, s30, 16
	v_add_u32_e32 v104, s23, v101
	v_or_b32_e32 v130, s36, v11
	v_or_b32_e32 v131, s37, v10
	v_or_b32_e32 v132, s38, v11
	v_or_b32_e32 v134, s40, v11
	v_or_b32_e32 v137, s42, v11
	v_or_b32_e32 v139, s27, v11
	v_add_u32_e32 v106, s23, v126
	v_add_u32_e32 v108, s23, v128
	v_lshlrev_b64 v[122:123], 13, v[102:103]
	v_add_u32_e32 v102, s0, v129
	v_mov_b32_e32 v111, v103
	v_mov_b32_e32 v113, v103
	v_mov_b32_e32 v115, v103
	v_mov_b32_e32 v117, v103
	v_mov_b32_e32 v119, v103
	s_add_i32 s41, s30, 20
	v_or_b32_e32 v133, s39, v10
	v_lshlrev_b64 v[104:105], 13, v[104:105]
	v_add_u32_e32 v110, s23, v130
	v_add_u32_e32 v112, s23, v132
	v_add_u32_e32 v114, s23, v134
	v_add_u32_e32 v116, s23, v137
	v_add_u32_e32 v118, s23, v139
	v_lshl_add_u64 v[120:121], v[2:3], 0, v[120:121]
	v_lshlrev_b64 v[106:107], 13, v[106:107]
	v_lshlrev_b64 v[108:109], 13, v[108:109]
	v_lshlrev_b64 v[124:125], 13, v[102:103]
	v_add_u32_e32 v102, s0, v131
	s_add_i32 s43, s30, 24
	v_or_b32_e32 v135, s41, v10
	v_lshl_add_u64 v[104:105], v[2:3], 0, v[104:105]
	v_lshlrev_b64 v[110:111], 13, v[110:111]
	v_lshlrev_b64 v[112:113], 13, v[112:113]
	v_lshlrev_b64 v[114:115], 13, v[114:115]
	v_lshlrev_b64 v[116:117], 13, v[116:117]
	v_lshlrev_b64 v[118:119], 13, v[118:119]
	v_lshl_add_u64 v[122:123], v[2:3], 0, v[122:123]
	v_lshl_add_u64 v[106:107], v[2:3], 0, v[106:107]
	v_lshl_add_u64 v[108:109], v[2:3], 0, v[108:109]
	global_load_dword v141, v[120:121], off nt
	global_load_dword v142, v[104:105], off nt
	v_lshlrev_b64 v[120:121], 13, v[102:103]
	v_add_u32_e32 v102, s0, v133
	s_add_i32 s30, s30, 28
	v_or_b32_e32 v138, s43, v10
	v_lshl_add_u64 v[110:111], v[2:3], 0, v[110:111]
	v_lshl_add_u64 v[112:113], v[2:3], 0, v[112:113]
	v_lshl_add_u64 v[114:115], v[2:3], 0, v[114:115]
	v_lshl_add_u64 v[116:117], v[2:3], 0, v[116:117]
	v_lshl_add_u64 v[118:119], v[2:3], 0, v[118:119]
	global_load_dword v143, v[122:123], off nt
	global_load_dword v144, v[106:107], off nt
	global_load_dword v145, v[108:109], off nt
	global_load_dword v146, v[110:111], off nt
	global_load_dword v147, v[112:113], off nt
	global_load_dword v148, v[114:115], off nt
	global_load_dword v149, v[116:117], off nt
	global_load_dword v150, v[118:119], off nt
	v_lshl_add_u64 v[106:107], v[2:3], 0, v[120:121]
	v_lshlrev_b64 v[108:109], 13, v[102:103]
	v_add_u32_e32 v102, s0, v135
	v_or_b32_e32 v140, s30, v10
	v_lshl_add_u64 v[104:105], v[2:3], 0, v[124:125]
	global_load_dword v151, v[106:107], off nt
	global_load_dword v152, v[104:105], off nt
	v_lshlrev_b64 v[106:107], 13, v[102:103]
	v_add_u32_e32 v102, s0, v138
	v_lshl_add_u64 v[104:105], v[2:3], 0, v[108:109]
	v_lshlrev_b64 v[108:109], 13, v[102:103]
	v_add_u32_e32 v102, s0, v140
	v_lshlrev_b64 v[110:111], 13, v[102:103]
	v_lshl_add_u64 v[110:111], v[2:3], 0, v[110:111]
	v_lshl_add_u64 v[106:107], v[2:3], 0, v[106:107]
	v_lshl_add_u64 v[108:109], v[2:3], 0, v[108:109]
	global_load_dword v102, v[110:111], off nt
	global_load_dword v153, v[108:109], off nt
	global_load_dword v154, v[106:107], off nt
	global_load_dword v155, v[104:105], off nt
	s_add_i32 s25, s25, 16
	s_add_i32 s24, s24, 16
	s_add_i32 s26, s26, -16
	s_cmp_lg_u32 s26, 0
	s_lshl_b32 s30, s25, 1
	s_lshl_b32 s27, s24, 1
	v_or_b32_e32 v45, s30, v10
	s_add_i32 s33, s30, 4
	s_add_i32 s31, s27, 4
	s_add_i32 s34, s27, 8
	s_add_i32 s35, s30, 8
	v_add_u32_e32 v0, s0, v45
	v_or_b32_e32 v63, s33, v10
	v_or_b32_e32 v39, s27, v11
	s_add_i32 s36, s27, 12
	s_add_i32 s37, s30, 12
	s_add_i32 s38, s27, 16
	s_add_i32 s40, s27, 20
	s_add_i32 s42, s27, 24
	s_add_i32 s27, s27, 28
	v_or_b32_e32 v62, s31, v11
	v_or_b32_e32 v64, s34, v11
	v_or_b32_e32 v65, s35, v10
	v_lshlrev_b64 v[56:57], 13, v[0:1]
	v_add_u32_e32 v0, s0, v63
	v_mov_b32_e32 v5, v1
	v_mov_b32_e32 v7, v1
	v_mov_b32_e32 v9, v1
	s_add_i32 s39, s30, 16
	v_add_u32_e32 v4, s23, v39
	v_or_b32_e32 v66, s36, v11
	v_or_b32_e32 v67, s37, v10
	v_or_b32_e32 v68, s38, v11
	v_or_b32_e32 v70, s40, v11
	v_or_b32_e32 v72, s42, v11
	v_or_b32_e32 v74, s27, v11
	v_add_u32_e32 v6, s23, v62
	v_add_u32_e32 v8, s23, v64
	v_lshlrev_b64 v[58:59], 13, v[0:1]
	v_add_u32_e32 v0, s0, v65
	v_mov_b32_e32 v47, v1
	v_mov_b32_e32 v49, v1
	v_mov_b32_e32 v51, v1
	v_mov_b32_e32 v53, v1
	v_mov_b32_e32 v55, v1
	s_add_i32 s41, s30, 20
	v_or_b32_e32 v69, s39, v10
	v_lshlrev_b64 v[4:5], 13, v[4:5]
	v_add_u32_e32 v46, s23, v66
	v_add_u32_e32 v48, s23, v68
	v_add_u32_e32 v50, s23, v70
	v_add_u32_e32 v52, s23, v72
	v_add_u32_e32 v54, s23, v74
	v_lshl_add_u64 v[56:57], v[2:3], 0, v[56:57]
	v_lshlrev_b64 v[6:7], 13, v[6:7]
	v_lshlrev_b64 v[8:9], 13, v[8:9]
	v_lshlrev_b64 v[60:61], 13, v[0:1]
	v_add_u32_e32 v0, s0, v67
	s_add_i32 s43, s30, 24
	v_or_b32_e32 v71, s41, v10
	v_lshl_add_u64 v[4:5], v[2:3], 0, v[4:5]
	v_lshlrev_b64 v[46:47], 13, v[46:47]
	v_lshlrev_b64 v[48:49], 13, v[48:49]
	v_lshlrev_b64 v[50:51], 13, v[50:51]
	v_lshlrev_b64 v[52:53], 13, v[52:53]
	v_lshlrev_b64 v[54:55], 13, v[54:55]
	v_lshl_add_u64 v[58:59], v[2:3], 0, v[58:59]
; #define GAS __attribute__((address_space(1)))
; #define LAS __attribute__((address_space(3)))
; #define LDS_WAIT() asm volatile("s_waitcnt lgkmcnt(0)" ::: "memory")
; __device__ __forceinline__ unsigned pk2(float lo, float hi) { unsigned r; asm("v_cvt_pk_bf16_f32 %0, %1, %2" : "=v"(r) : "v"(lo), "v"(hi)); return r; }
; __device__ __forceinline__ void cvt_item(gfp W, int N, bf16* WT, int Kd, int k0, int n0, int drow0, LAS float* scr, int lane, gfp gk) {
; #pragma unroll 8
;     for (int i = 0; i < 32; ++i) { const int kk = 2 * i + (lane >> 5); scr[kk * 33 + (lane & 31)] = W[(size_t)(k0 + kk) * N + n0 + (lane & 31)]; }
;     const int c = lane & 7;
;     f32x4 ga = (f32x4){1.f, 1.f, 1.f, 1.f}, gb = ga;
;     if (gk != nullptr) { ga = *(const GAS f32x4*)(gk + k0 + 8 * c); gb = *(const GAS f32x4*)(gk + k0 + 8 * c + 4); }
;     LDS_WAIT(); asm volatile("" ::: "memory");
; #pragma unroll
;     for (int j = 0; j < 4; ++j) { const int n = (lane >> 3) + 8 * j; const LAS float* s = scr + (8 * c) * 33 + n;
;         v4u o; o.x = pk2(s[0 * 33] * ga[0], s[1 * 33] * ga[1]); o.y = pk2(s[2 * 33] * ga[2], s[3 * 33] * ga[3]); o.z = pk2(s[4 * 33] * gb[0], s[5 * 33] * gb[1]); o.w = pk2(s[6 * 33] * gb[2], s[7 * 33] * gb[3]);
;         *(GAS v4u*)(WT + (size_t)(drow0 + n) * Kd + k0 + 8 * c) = o; }
;     LDS_WAIT(); asm volatile("" ::: "memory");
	v_lshl_add_u64 v[6:7], v[2:3], 0, v[6:7]
	v_lshl_add_u64 v[8:9], v[2:3], 0, v[8:9]
	global_load_dword v76, v[56:57], off nt
	global_load_dword v77, v[4:5], off nt
	v_lshlrev_b64 v[56:57], 13, v[0:1]
	v_add_u32_e32 v0, s0, v69
	s_add_i32 s30, s30, 28
	v_or_b32_e32 v73, s43, v10
	v_lshl_add_u64 v[46:47], v[2:3], 0, v[46:47]
	v_lshl_add_u64 v[48:49], v[2:3], 0, v[48:49]
	v_lshl_add_u64 v[50:51], v[2:3], 0, v[50:51]
	v_lshl_add_u64 v[52:53], v[2:3], 0, v[52:53]
	v_lshl_add_u64 v[54:55], v[2:3], 0, v[54:55]
	global_load_dword v78, v[58:59], off nt
	global_load_dword v79, v[6:7], off nt
	global_load_dword v80, v[8:9], off nt
	global_load_dword v81, v[46:47], off nt
	global_load_dword v82, v[48:49], off nt
	global_load_dword v83, v[50:51], off nt
	global_load_dword v84, v[52:53], off nt
	global_load_dword v85, v[54:55], off nt
	v_lshl_add_u64 v[6:7], v[2:3], 0, v[56:57]
	v_lshlrev_b64 v[8:9], 13, v[0:1]
	v_add_u32_e32 v0, s0, v71
	v_or_b32_e32 v75, s30, v10
	v_lshl_add_u64 v[4:5], v[2:3], 0, v[60:61]
	global_load_dword v86, v[6:7], off nt
	global_load_dword v87, v[4:5], off nt
	v_lshlrev_b64 v[6:7], 13, v[0:1]
	v_add_u32_e32 v0, s0, v73
	v_lshl_add_u64 v[4:5], v[2:3], 0, v[8:9]
	v_lshlrev_b64 v[8:9], 13, v[0:1]
	v_add_u32_e32 v0, s0, v75
	v_lshlrev_b64 v[46:47], 13, v[0:1]
	v_lshl_add_u64 v[46:47], v[2:3], 0, v[46:47]
	v_lshl_add_u64 v[6:7], v[2:3], 0, v[6:7]
	v_lshl_add_u64 v[8:9], v[2:3], 0, v[8:9]
	global_load_dword v0, v[46:47], off nt
	global_load_dword v88, v[8:9], off nt
	global_load_dword v89, v[6:7], off nt
	global_load_dword v90, v[4:5], off nt
	v_mad_u64_u32 v[104:105], s[30:31], v136, s81, v[12:13]
	v_mad_u64_u32 v[106:107], s[30:31], v101, s81, v[12:13]
	v_mad_u64_u32 v[108:109], s[30:31], v127, s81, v[12:13]
	v_mad_u64_u32 v[110:111], s[30:31], v126, s81, v[12:13]
	v_mad_u64_u32 v[112:113], s[30:31], v129, s81, v[12:13]
	v_mad_u64_u32 v[114:115], s[30:31], v128, s81, v[12:13]
	v_mad_u64_u32 v[116:117], s[30:31], v131, s81, v[12:13]
	v_mad_u64_u32 v[118:119], s[30:31], v130, s81, v[12:13]
	v_mad_u64_u32 v[120:121], s[30:31], v133, s81, v[12:13]
	v_mad_u64_u32 v[122:123], s[30:31], v132, s81, v[12:13]
	v_mad_u64_u32 v[124:125], s[30:31], v135, s81, v[12:13]
	v_mad_u64_u32 v[126:127], s[30:31], v134, s81, v[12:13]
	v_mad_u64_u32 v[128:129], s[30:31], v138, s81, v[12:13]
	v_mad_u64_u32 v[130:131], s[30:31], v137, s81, v[12:13]
	v_mad_u64_u32 v[132:133], s[30:31], v140, s81, v[12:13]
	v_mad_u64_u32 v[134:135], s[30:31], v139, s81, v[12:13]
	s_waitcnt vmcnt(31)
	ds_write_b32 v104, v141
	s_waitcnt vmcnt(30)
	ds_write_b32 v106, v142
	s_waitcnt vmcnt(29)
	ds_write_b32 v108, v143
	s_waitcnt vmcnt(28)
	ds_write_b32 v110, v144
	s_waitcnt vmcnt(20)
	ds_write_b32 v112, v152
	ds_write_b32 v114, v145
	ds_write_b32 v116, v151
	ds_write_b32 v118, v146
	s_waitcnt vmcnt(16)
	ds_write_b32 v120, v155
	ds_write_b32 v122, v147
	ds_write_b32 v124, v154
	ds_write_b32 v126, v148
	ds_write_b32 v128, v153
	ds_write_b32 v130, v149
	ds_write_b32 v132, v102
	ds_write_b32 v134, v150
	v_mad_u64_u32 v[4:5], s[30:31], v45, s81, v[12:13]
	v_mad_u64_u32 v[6:7], s[30:31], v39, s81, v[12:13]
	v_mad_u64_u32 v[8:9], s[30:31], v63, s81, v[12:13]
	v_mad_u64_u32 v[46:47], s[30:31], v62, s81, v[12:13]
	v_mad_u64_u32 v[48:49], s[30:31], v65, s81, v[12:13]
	v_mad_u64_u32 v[50:51], s[30:31], v64, s81, v[12:13]
	v_mad_u64_u32 v[52:53], s[30:31], v67, s81, v[12:13]
	v_mad_u64_u32 v[54:55], s[30:31], v66, s81, v[12:13]
	v_mad_u64_u32 v[56:57], s[30:31], v69, s81, v[12:13]
	v_mad_u64_u32 v[58:59], s[30:31], v68, s81, v[12:13]
	v_mad_u64_u32 v[60:61], s[30:31], v71, s81, v[12:13]
	v_mad_u64_u32 v[62:63], s[30:31], v70, s81, v[12:13]
	v_mad_u64_u32 v[64:65], s[30:31], v73, s81, v[12:13]
	v_mad_u64_u32 v[66:67], s[30:31], v72, s81, v[12:13]
	v_mad_u64_u32 v[68:69], s[30:31], v75, s81, v[12:13]
	v_mad_u64_u32 v[70:71], s[30:31], v74, s81, v[12:13]
	s_waitcnt vmcnt(15)
	ds_write_b32 v4, v76
	s_waitcnt vmcnt(14)
	ds_write_b32 v6, v77
	s_waitcnt vmcnt(13)
	ds_write_b32 v8, v78
	s_waitcnt vmcnt(12)
	ds_write_b32 v46, v79
	s_waitcnt vmcnt(4)
	ds_write_b32 v48, v87
	ds_write_b32 v50, v80
	ds_write_b32 v52, v86
	ds_write_b32 v54, v81
	s_waitcnt vmcnt(0)
	ds_write_b32 v56, v90
	ds_write_b32 v58, v82
	ds_write_b32 v60, v89
	ds_write_b32 v62, v83
	ds_write_b32 v64, v88
	ds_write_b32 v66, v84
	ds_write_b32 v68, v0
	ds_write_b32 v70, v85
	s_add_i32 s25, s25, 16
	s_add_i32 s24, s24, 16
	s_add_i32 s26, s26, -16
	s_cmp_lg_u32 s26, 0
	s_and_b32 s22, 0xffff, s22
	s_waitcnt lgkmcnt(0)
	v_or_b32_e32 v0, s22, v40
	s_lshl_b32 s0, s0, 1
	ds_read2_b32 v[6:7], v41 offset0:33 offset1:41
	ds_read2_b32 v[8:9], v41 offset1:8
	ds_read2_b32 v[46:47], v41 offset0:66 offset1:74
	ds_read2_b32 v[48:49], v41 offset0:99 offset1:107
	ds_read2_b32 v[50:51], v41 offset0:132 offset1:140
	ds_read2_b32 v[52:53], v41 offset0:165 offset1:173
	ds_read2_b32 v[54:55], v41 offset0:198 offset1:206
	ds_read2_b32 v[56:57], v41 offset0:231 offset1:239
	v_mul_u32_u24_e32 v0, 0x1600, v0
	v_lshl_add_u64 v[58:59], v[26:27], 0, s[0:1]
	v_lshlrev_b32_e32 v0, 1, v0
	v_lshl_add_u64 v[60:61], v[58:59], 0, v[0:1]
	v_or_b32_e32 v0, s22, v42
	v_mul_u32_u24_e32 v0, 0x1600, v0
	s_waitcnt lgkmcnt(6)
	v_cvt_pk_bf16_f32 v2, v8, v6
	v_lshlrev_b32_e32 v0, 1, v0
	s_waitcnt lgkmcnt(4)
	v_cvt_pk_bf16_f32 v3, v46, v48
	s_waitcnt lgkmcnt(2)
	v_cvt_pk_bf16_f32 v4, v50, v52
	s_waitcnt lgkmcnt(0)
	v_cvt_pk_bf16_f32 v5, v54, v56
	global_store_dwordx4 v[60:61], v[2:5], off
	s_nop 1
	v_cvt_pk_bf16_f32 v2, v9, v7
	v_lshl_add_u64 v[6:7], v[58:59], 0, v[0:1]
	v_or_b32_e32 v0, s22, v43
	v_cvt_pk_bf16_f32 v3, v47, v49
	v_cvt_pk_bf16_f32 v4, v51, v53
	v_cvt_pk_bf16_f32 v5, v55, v57
	ds_read2_b32 v[8:9], v41 offset0:16 offset1:24
	ds_read2_b32 v[46:47], v41 offset0:49 offset1:57
	ds_read2_b32 v[48:49], v41 offset0:82 offset1:90
	ds_read2_b32 v[50:51], v41 offset0:115 offset1:123
	ds_read2_b32 v[52:53], v41 offset0:148 offset1:156
	ds_read2_b32 v[54:55], v41 offset0:181 offset1:189
	ds_read2_b32 v[56:57], v41 offset0:214 offset1:222
	ds_read2_b32 v[60:61], v41 offset0:247 offset1:255
	v_mul_u32_u24_e32 v0, 0x1600, v0
	v_lshlrev_b32_e32 v0, 1, v0
	global_store_dwordx4 v[6:7], v[2:5], off
	v_lshl_add_u64 v[6:7], v[58:59], 0, v[0:1]
	v_or_b32_e32 v0, s22, v44
	v_mul_u32_u24_e32 v0, 0x1600, v0
	v_lshlrev_b32_e32 v0, 1, v0
	s_waitcnt lgkmcnt(6)
	v_cvt_pk_bf16_f32 v2, v8, v46
	s_waitcnt lgkmcnt(4)
	v_cvt_pk_bf16_f32 v3, v48, v50
	s_waitcnt lgkmcnt(2)
	v_cvt_pk_bf16_f32 v4, v52, v54
	s_waitcnt lgkmcnt(0)
	v_cvt_pk_bf16_f32 v5, v56, v60
	global_store_dwordx4 v[6:7], v[2:5], off
	v_lshl_add_u64 v[6:7], v[58:59], 0, v[0:1]
	s_nop 0
	v_cvt_pk_bf16_f32 v2, v9, v47
	v_cvt_pk_bf16_f32 v3, v49, v51
	v_cvt_pk_bf16_f32 v4, v53, v55
	v_cvt_pk_bf16_f32 v5, v57, v61
	global_store_dwordx4 v[6:7], v[2:5], off
	s_waitcnt lgkmcnt(0)

; __device__ __forceinline__ void cvt_item(gfp W, int N, bf16* WT, int Kd, int k0, int n0, int drow0, LAS float* scr, int lane, gfp gk) {
; #pragma unroll 8
;     for (int i = 0; i < 32; ++i) { const int kk = 2 * i + (lane >> 5); scr[kk * 33 + (lane & 31)] = W[(size_t)(k0 + kk) * N + n0 + (lane & 31)]; }
.LBB0_177:
	s_lshl_b32 s33, s27, 1
	s_lshl_b32 s34, s30, 1
	v_or_b32_e32 v101, s33, v11
	v_or_b32_e32 v134, s34, v10
	s_add_i32 s35, s33, 4
	s_add_i32 s36, s34, 4
	s_add_i32 s37, s33, 8
	s_add_i32 s38, s34, 8
	s_add_i32 s39, s33, 12
	s_add_i32 s40, s34, 12
	s_add_i32 s41, s33, 16
	s_add_i32 s42, s34, 16
	s_add_i32 s43, s33, 20
	s_add_i32 s44, s34, 20
	s_add_i32 s45, s33, 24
	s_add_i32 s46, s34, 24
	s_add_i32 s33, s33, 28
	s_add_i32 s34, s34, 28
	v_add_u32_e32 v102, s25, v134
	v_or_b32_e32 v135, s35, v11
	v_or_b32_e32 v136, s36, v10
	v_or_b32_e32 v137, s37, v11
	v_or_b32_e32 v138, s38, v10
	v_or_b32_e32 v139, s39, v11
	v_or_b32_e32 v140, s40, v10
	v_or_b32_e32 v141, s41, v11
	v_or_b32_e32 v142, s42, v10
	v_or_b32_e32 v143, s43, v11
	v_or_b32_e32 v144, s44, v10
	v_or_b32_e32 v145, s45, v11
	v_or_b32_e32 v146, s46, v10
	v_or_b32_e32 v147, s33, v11
	v_or_b32_e32 v148, s34, v10
	v_add_u32_e32 v104, s26, v101
	v_mad_u64_u32 v[102:103], s[34:35], v102, s74, v[2:3]
	v_add_u32_e32 v108, s26, v135
	v_add_u32_e32 v106, s25, v136
	v_add_u32_e32 v112, s26, v137
	v_add_u32_e32 v110, s25, v138
	v_add_u32_e32 v116, s26, v139
	v_add_u32_e32 v114, s25, v140
	v_add_u32_e32 v120, s26, v141
	v_add_u32_e32 v118, s25, v142
	v_add_u32_e32 v124, s26, v143
	v_add_u32_e32 v122, s25, v144
	v_add_u32_e32 v128, s26, v145
	v_add_u32_e32 v126, s25, v146
	v_add_u32_e32 v132, s26, v147
	v_add_u32_e32 v130, s25, v148
	v_mad_u64_u32 v[104:105], s[34:35], v104, s74, v[2:3]
	v_mad_u64_u32 v[106:107], s[34:35], v106, s74, v[2:3]
	v_mad_u64_u32 v[108:109], s[34:35], v108, s74, v[2:3]
	v_mad_u64_u32 v[110:111], s[34:35], v110, s74, v[2:3]
	v_mad_u64_u32 v[112:113], s[34:35], v112, s74, v[2:3]
	v_mad_u64_u32 v[114:115], s[34:35], v114, s74, v[2:3]
	v_mad_u64_u32 v[116:117], s[34:35], v116, s74, v[2:3]
	v_mad_u64_u32 v[118:119], s[34:35], v118, s74, v[2:3]
	v_mad_u64_u32 v[120:121], s[34:35], v120, s74, v[2:3]
	v_mad_u64_u32 v[122:123], s[34:35], v122, s74, v[2:3]
	v_mad_u64_u32 v[124:125], s[34:35], v124, s74, v[2:3]
	v_mad_u64_u32 v[126:127], s[34:35], v126, s74, v[2:3]
	v_mad_u64_u32 v[128:129], s[34:35], v128, s74, v[2:3]
	v_mad_u64_u32 v[130:131], s[34:35], v130, s74, v[2:3]
	v_mad_u64_u32 v[132:133], s[34:35], v132, s74, v[2:3]
	global_load_dword v149, v[102:103], off nt
	global_load_dword v150, v[104:105], off nt
	global_load_dword v151, v[106:107], off nt
	global_load_dword v152, v[108:109], off nt
	global_load_dword v153, v[110:111], off nt
	global_load_dword v154, v[112:113], off nt
	global_load_dword v155, v[114:115], off nt
	global_load_dword v156, v[116:117], off nt
	global_load_dword v157, v[118:119], off nt
	global_load_dword v158, v[120:121], off nt
	global_load_dword v159, v[122:123], off nt
	global_load_dword v160, v[124:125], off nt
	global_load_dword v161, v[126:127], off nt
	global_load_dword v162, v[128:129], off nt
	global_load_dword v163, v[130:131], off nt
	global_load_dword v164, v[132:133], off nt
	s_add_i32 s30, s30, 16
	s_add_i32 s27, s27, 16
	s_add_i32 s31, s31, -16
	s_cmp_lg_u32 s31, 0
	s_lshl_b32 s33, s27, 1
	s_lshl_b32 s34, s30, 1
	v_or_b32_e32 v0, s33, v11
	v_or_b32_e32 v39, s34, v10
	s_add_i32 s35, s33, 4
	s_add_i32 s36, s34, 4
	s_add_i32 s37, s33, 8
	s_add_i32 s38, s34, 8
	s_add_i32 s39, s33, 12
	s_add_i32 s40, s34, 12
	s_add_i32 s41, s33, 16
	s_add_i32 s42, s34, 16
	s_add_i32 s43, s33, 20
	s_add_i32 s44, s34, 20
	s_add_i32 s45, s33, 24
	s_add_i32 s46, s34, 24
	s_add_i32 s33, s33, 28
	s_add_i32 s34, s34, 28
	v_add_u32_e32 v4, s25, v39
	v_or_b32_e32 v45, s35, v11
	v_or_b32_e32 v72, s36, v10
	v_or_b32_e32 v73, s37, v11
	v_or_b32_e32 v74, s38, v10
	v_or_b32_e32 v75, s39, v11
	v_or_b32_e32 v76, s40, v10
	v_or_b32_e32 v77, s41, v11
	v_or_b32_e32 v78, s42, v10
	v_or_b32_e32 v79, s43, v11
	v_or_b32_e32 v80, s44, v10
	v_or_b32_e32 v81, s45, v11
	v_or_b32_e32 v82, s46, v10
	v_or_b32_e32 v83, s33, v11
	v_or_b32_e32 v84, s34, v10
	v_add_u32_e32 v6, s26, v0
	v_mad_u64_u32 v[4:5], s[34:35], v4, s74, v[2:3]
	v_add_u32_e32 v46, s26, v45
	v_add_u32_e32 v8, s25, v72
	v_add_u32_e32 v50, s26, v73
	v_add_u32_e32 v48, s25, v74
	v_add_u32_e32 v54, s26, v75
	v_add_u32_e32 v52, s25, v76
	v_add_u32_e32 v58, s26, v77
	v_add_u32_e32 v56, s25, v78
	v_add_u32_e32 v62, s26, v79
	v_add_u32_e32 v60, s25, v80
	v_add_u32_e32 v66, s26, v81
	v_add_u32_e32 v64, s25, v82
	v_add_u32_e32 v70, s26, v83
	v_add_u32_e32 v68, s25, v84
	v_mad_u64_u32 v[6:7], s[34:35], v6, s74, v[2:3]
	v_mad_u64_u32 v[8:9], s[34:35], v8, s74, v[2:3]
	v_mad_u64_u32 v[46:47], s[34:35], v46, s74, v[2:3]
	v_mad_u64_u32 v[48:49], s[34:35], v48, s74, v[2:3]
	v_mad_u64_u32 v[50:51], s[34:35], v50, s74, v[2:3]
	v_mad_u64_u32 v[52:53], s[34:35], v52, s74, v[2:3]
	v_mad_u64_u32 v[54:55], s[34:35], v54, s74, v[2:3]
	v_mad_u64_u32 v[56:57], s[34:35], v56, s74, v[2:3]
	v_mad_u64_u32 v[58:59], s[34:35], v58, s74, v[2:3]
	v_mad_u64_u32 v[60:61], s[34:35], v60, s74, v[2:3]
	v_mad_u64_u32 v[62:63], s[34:35], v62, s74, v[2:3]
	v_mad_u64_u32 v[64:65], s[34:35], v64, s74, v[2:3]
	v_mad_u64_u32 v[66:67], s[34:35], v66, s74, v[2:3]
	v_mad_u64_u32 v[68:69], s[34:35], v68, s74, v[2:3]
	v_mad_u64_u32 v[70:71], s[34:35], v70, s74, v[2:3]
	global_load_dword v85, v[4:5], off nt
	global_load_dword v86, v[6:7], off nt
	global_load_dword v87, v[8:9], off nt
	global_load_dword v88, v[46:47], off nt
	global_load_dword v89, v[48:49], off nt
	global_load_dword v90, v[50:51], off nt
	global_load_dword v91, v[52:53], off nt
	global_load_dword v92, v[54:55], off nt
	global_load_dword v93, v[56:57], off nt
	global_load_dword v94, v[58:59], off nt
	global_load_dword v95, v[60:61], off nt
	global_load_dword v96, v[62:63], off nt
	global_load_dword v97, v[64:65], off nt
	global_load_dword v98, v[66:67], off nt
	global_load_dword v99, v[68:69], off nt
	global_load_dword v100, v[70:71], off nt
	v_mad_u64_u32 v[102:103], s[34:35], v134, s81, v[12:13]
	v_mad_u64_u32 v[104:105], s[34:35], v101, s81, v[12:13]
	v_mad_u64_u32 v[106:107], s[34:35], v136, s81, v[12:13]
	v_mad_u64_u32 v[108:109], s[34:35], v135, s81, v[12:13]
	v_mad_u64_u32 v[110:111], s[34:35], v138, s81, v[12:13]
	v_mad_u64_u32 v[112:113], s[34:35], v137, s81, v[12:13]
	v_mad_u64_u32 v[114:115], s[34:35], v140, s81, v[12:13]
	v_mad_u64_u32 v[116:117], s[34:35], v139, s81, v[12:13]
	v_mad_u64_u32 v[118:119], s[34:35], v142, s81, v[12:13]
	v_mad_u64_u32 v[120:121], s[34:35], v141, s81, v[12:13]
	v_mad_u64_u32 v[122:123], s[34:35], v144, s81, v[12:13]
	v_mad_u64_u32 v[124:125], s[34:35], v143, s81, v[12:13]
	v_mad_u64_u32 v[126:127], s[34:35], v146, s81, v[12:13]
	v_mad_u64_u32 v[128:129], s[34:35], v145, s81, v[12:13]
	v_mad_u64_u32 v[130:131], s[34:35], v148, s81, v[12:13]
	v_mad_u64_u32 v[132:133], s[34:35], v147, s81, v[12:13]
	s_waitcnt vmcnt(31)
; #define GAS __attribute__((address_space(1)))
; __device__ __forceinline__ void cvt_item(gfp W, int N, bf16* WT, int Kd, int k0, int n0, int drow0, LAS float* scr, int lane, gfp gk) {
;     ...
;     for (int i = 0; i < 32; ++i) { const int kk = 2 * i + (lane >> 5); scr[kk * 33 + (lane & 31)] = W[(size_t)(k0 + kk) * N + n0 + (lane & 31)]; }
;     const int c = lane & 7;
;     f32x4 ga = (f32x4){1.f, 1.f, 1.f, 1.f}, gb = ga;
;     if (gk != nullptr) { ga = *(const GAS f32x4*)(gk + k0 + 8 * c); gb = *(const GAS f32x4*)(gk + k0 + 8 * c + 4); }
	ds_write_b32 v102, v149
	s_waitcnt vmcnt(30)
	ds_write_b32 v104, v150
	s_waitcnt vmcnt(29)
	ds_write_b32 v106, v151
	s_waitcnt vmcnt(28)
	ds_write_b32 v108, v152
	s_waitcnt vmcnt(27)
	ds_write_b32 v110, v153
	s_waitcnt vmcnt(26)
	ds_write_b32 v112, v154
	s_waitcnt vmcnt(25)
	ds_write_b32 v114, v155
	s_waitcnt vmcnt(24)
	ds_write_b32 v116, v156
	s_waitcnt vmcnt(23)
	ds_write_b32 v118, v157
	s_waitcnt vmcnt(22)
	ds_write_b32 v120, v158
	s_waitcnt vmcnt(21)
	ds_write_b32 v122, v159
	s_waitcnt vmcnt(20)
	ds_write_b32 v124, v160
	s_waitcnt vmcnt(19)
	ds_write_b32 v126, v161
	s_waitcnt vmcnt(18)
	ds_write_b32 v128, v162
	s_waitcnt vmcnt(17)
	ds_write_b32 v130, v163
	s_waitcnt vmcnt(16)
	ds_write_b32 v132, v164
	v_mad_u64_u32 v[4:5], s[34:35], v39, s81, v[12:13]
	v_mad_u64_u32 v[6:7], s[34:35], v0, s81, v[12:13]
	v_mad_u64_u32 v[8:9], s[34:35], v72, s81, v[12:13]
	v_mad_u64_u32 v[46:47], s[34:35], v45, s81, v[12:13]
	v_mad_u64_u32 v[48:49], s[34:35], v74, s81, v[12:13]
	v_mad_u64_u32 v[50:51], s[34:35], v73, s81, v[12:13]
	v_mad_u64_u32 v[52:53], s[34:35], v76, s81, v[12:13]
	v_mad_u64_u32 v[54:55], s[34:35], v75, s81, v[12:13]
	v_mad_u64_u32 v[56:57], s[34:35], v78, s81, v[12:13]
	v_mad_u64_u32 v[58:59], s[34:35], v77, s81, v[12:13]
	v_mad_u64_u32 v[60:61], s[34:35], v80, s81, v[12:13]
	v_mad_u64_u32 v[62:63], s[34:35], v79, s81, v[12:13]
	v_mad_u64_u32 v[64:65], s[34:35], v82, s81, v[12:13]
	v_mad_u64_u32 v[66:67], s[34:35], v81, s81, v[12:13]
	v_mad_u64_u32 v[68:69], s[34:35], v84, s81, v[12:13]
	v_mad_u64_u32 v[70:71], s[34:35], v83, s81, v[12:13]
	s_waitcnt vmcnt(15)
	ds_write_b32 v4, v85
	s_waitcnt vmcnt(14)
	ds_write_b32 v6, v86
	s_waitcnt vmcnt(13)
	ds_write_b32 v8, v87
	s_waitcnt vmcnt(12)
	ds_write_b32 v46, v88
	s_waitcnt vmcnt(11)
	ds_write_b32 v48, v89
	s_waitcnt vmcnt(10)
	ds_write_b32 v50, v90
	s_waitcnt vmcnt(9)
	ds_write_b32 v52, v91
	s_waitcnt vmcnt(8)
	ds_write_b32 v54, v92
	s_waitcnt vmcnt(7)
	ds_write_b32 v56, v93
	s_waitcnt vmcnt(6)
	ds_write_b32 v58, v94
	s_waitcnt vmcnt(5)
	ds_write_b32 v60, v95
	s_waitcnt vmcnt(4)
	ds_write_b32 v62, v96
	s_waitcnt vmcnt(3)
	ds_write_b32 v64, v97
	s_waitcnt vmcnt(2)
	ds_write_b32 v66, v98
	s_waitcnt vmcnt(1)
	ds_write_b32 v68, v99
	s_waitcnt vmcnt(0)
	ds_write_b32 v70, v100
	s_add_i32 s30, s30, 16
	s_add_i32 s27, s27, 16
	s_add_i32 s31, s31, -16
	s_cmp_lg_u32 s31, 0
	s_lshl_b64 s[26:27], s[8:9], 2
	s_add_u32 s22, s22, s26
	s_addc_u32 s23, s23, s27
	s_and_b32 s25, s25, 0xffff
	s_cmp_eq_u64 s[22:23], 0
	s_cbranch_scc1 .LBB0_180
	s_lshl_b32 s26, s25, 2
	s_add_u32 s22, s22, s26
	s_addc_u32 s23, s23, 0
	v_lshlrev_b32_e32 v0, 2, v14
	global_load_dwordx4 v[2:5], v0, s[22:23] offset:16
	global_load_dwordx4 v[6:9], v0, s[22:23]
	s_branch .LBB0_181

; __device__ __forceinline__ void cvt_item(gfp W, int N, bf16* WT, int Kd, int k0, int n0, int drow0, LAS float* scr, int lane, gfp gk) {
; #pragma unroll 8
;     for (int i = 0; i < 32; ++i) { const int kk = 2 * i + (lane >> 5); scr[kk * 33 + (lane & 31)] = W[(size_t)(k0 + kk) * N + n0 + (lane & 31)]; }
.LBB0_200:
	s_lshl_b32 s33, s26, 1
	s_lshl_b32 s34, s30, 1
	v_or_b32_e32 v101, s33, v11
	v_or_b32_e32 v134, s34, v10
	s_add_i32 s35, s33, 4
	s_add_i32 s36, s34, 4
	s_add_i32 s37, s33, 8
	s_add_i32 s38, s34, 8
	s_add_i32 s39, s33, 12
	s_add_i32 s40, s34, 12
	s_add_i32 s41, s33, 16
	s_add_i32 s42, s34, 16
	s_add_i32 s43, s33, 20
	s_add_i32 s44, s34, 20
	s_add_i32 s45, s33, 24
	s_add_i32 s46, s34, 24
	s_add_i32 s33, s33, 28
	s_add_i32 s34, s34, 28
	v_add_u32_e32 v102, s22, v134
	v_or_b32_e32 v135, s35, v11
	v_or_b32_e32 v136, s36, v10
	v_or_b32_e32 v137, s37, v11
	v_or_b32_e32 v138, s38, v10
	v_or_b32_e32 v139, s39, v11
	v_or_b32_e32 v140, s40, v10
	v_or_b32_e32 v141, s41, v11
	v_or_b32_e32 v142, s42, v10
	v_or_b32_e32 v143, s43, v11
	v_or_b32_e32 v144, s44, v10
	v_or_b32_e32 v145, s45, v11
	v_or_b32_e32 v146, s46, v10
	v_or_b32_e32 v147, s33, v11
	v_or_b32_e32 v148, s34, v10
	v_add_u32_e32 v104, s25, v101
	v_mad_i64_i32 v[102:103], s[34:35], v102, s74, v[2:3]
	v_add_u32_e32 v108, s25, v135
	v_add_u32_e32 v106, s22, v136
	v_add_u32_e32 v112, s25, v137
	v_add_u32_e32 v110, s22, v138
	v_add_u32_e32 v116, s25, v139
	v_add_u32_e32 v114, s22, v140
	v_add_u32_e32 v120, s25, v141
	v_add_u32_e32 v118, s22, v142
	v_add_u32_e32 v124, s25, v143
	v_add_u32_e32 v122, s22, v144
	v_add_u32_e32 v128, s25, v145
	v_add_u32_e32 v126, s22, v146
	v_add_u32_e32 v132, s25, v147
	v_add_u32_e32 v130, s22, v148
	v_mad_i64_i32 v[104:105], s[34:35], v104, s74, v[2:3]
	v_mad_i64_i32 v[106:107], s[34:35], v106, s74, v[2:3]
	v_mad_i64_i32 v[108:109], s[34:35], v108, s74, v[2:3]
	v_mad_i64_i32 v[110:111], s[34:35], v110, s74, v[2:3]
	v_mad_i64_i32 v[112:113], s[34:35], v112, s74, v[2:3]
	v_mad_i64_i32 v[114:115], s[34:35], v114, s74, v[2:3]
	v_mad_i64_i32 v[116:117], s[34:35], v116, s74, v[2:3]
	v_mad_i64_i32 v[118:119], s[34:35], v118, s74, v[2:3]
	v_mad_i64_i32 v[120:121], s[34:35], v120, s74, v[2:3]
	v_mad_i64_i32 v[122:123], s[34:35], v122, s74, v[2:3]
	v_mad_i64_i32 v[124:125], s[34:35], v124, s74, v[2:3]
	v_mad_i64_i32 v[126:127], s[34:35], v126, s74, v[2:3]
	v_mad_i64_i32 v[128:129], s[34:35], v128, s74, v[2:3]
	v_mad_i64_i32 v[130:131], s[34:35], v130, s74, v[2:3]
	v_mad_i64_i32 v[132:133], s[34:35], v132, s74, v[2:3]
	global_load_dword v149, v[102:103], off nt
	global_load_dword v150, v[104:105], off nt
	global_load_dword v151, v[106:107], off nt
	global_load_dword v152, v[108:109], off nt
	global_load_dword v153, v[110:111], off nt
	global_load_dword v154, v[112:113], off nt
	global_load_dword v155, v[114:115], off nt
	global_load_dword v156, v[116:117], off nt
	global_load_dword v157, v[118:119], off nt
	global_load_dword v158, v[120:121], off nt
	global_load_dword v159, v[122:123], off nt
	global_load_dword v160, v[124:125], off nt
	global_load_dword v161, v[126:127], off nt
	global_load_dword v162, v[128:129], off nt
	global_load_dword v163, v[130:131], off nt
	global_load_dword v164, v[132:133], off nt
	s_add_i32 s30, s30, 16
	s_add_i32 s26, s26, 16
	s_add_i32 s31, s31, -16
	s_cmp_lg_u32 s31, 0
	s_lshl_b32 s33, s26, 1
	s_lshl_b32 s34, s30, 1
	v_or_b32_e32 v0, s33, v11
	v_or_b32_e32 v39, s34, v10
	s_add_i32 s35, s33, 4
	s_add_i32 s36, s34, 4
	s_add_i32 s37, s33, 8
	s_add_i32 s38, s34, 8
	s_add_i32 s39, s33, 12
	s_add_i32 s40, s34, 12
	s_add_i32 s41, s33, 16
	s_add_i32 s42, s34, 16
	s_add_i32 s43, s33, 20
	s_add_i32 s44, s34, 20
	s_add_i32 s45, s33, 24
	s_add_i32 s46, s34, 24
	s_add_i32 s33, s33, 28
	s_add_i32 s34, s34, 28
	v_add_u32_e32 v4, s22, v39
	v_or_b32_e32 v45, s35, v11
	v_or_b32_e32 v72, s36, v10
	v_or_b32_e32 v73, s37, v11
	v_or_b32_e32 v74, s38, v10
	v_or_b32_e32 v75, s39, v11
	v_or_b32_e32 v76, s40, v10
	v_or_b32_e32 v77, s41, v11
	v_or_b32_e32 v78, s42, v10
	v_or_b32_e32 v79, s43, v11
	v_or_b32_e32 v80, s44, v10
	v_or_b32_e32 v81, s45, v11
	v_or_b32_e32 v82, s46, v10
	v_or_b32_e32 v83, s33, v11
	v_or_b32_e32 v84, s34, v10
	v_add_u32_e32 v6, s25, v0
	v_mad_i64_i32 v[4:5], s[34:35], v4, s74, v[2:3]
	v_add_u32_e32 v46, s25, v45
	v_add_u32_e32 v8, s22, v72
	v_add_u32_e32 v50, s25, v73
	v_add_u32_e32 v48, s22, v74
	v_add_u32_e32 v54, s25, v75
	v_add_u32_e32 v52, s22, v76
	v_add_u32_e32 v58, s25, v77
	v_add_u32_e32 v56, s22, v78
	v_add_u32_e32 v62, s25, v79
	v_add_u32_e32 v60, s22, v80
	v_add_u32_e32 v66, s25, v81
	v_add_u32_e32 v64, s22, v82
	v_add_u32_e32 v70, s25, v83
	v_add_u32_e32 v68, s22, v84
	v_mad_i64_i32 v[6:7], s[34:35], v6, s74, v[2:3]
	v_mad_i64_i32 v[8:9], s[34:35], v8, s74, v[2:3]
	v_mad_i64_i32 v[46:47], s[34:35], v46, s74, v[2:3]
	v_mad_i64_i32 v[48:49], s[34:35], v48, s74, v[2:3]
	v_mad_i64_i32 v[50:51], s[34:35], v50, s74, v[2:3]
	v_mad_i64_i32 v[52:53], s[34:35], v52, s74, v[2:3]
	v_mad_i64_i32 v[54:55], s[34:35], v54, s74, v[2:3]
	v_mad_i64_i32 v[56:57], s[34:35], v56, s74, v[2:3]
	v_mad_i64_i32 v[58:59], s[34:35], v58, s74, v[2:3]
	v_mad_i64_i32 v[60:61], s[34:35], v60, s74, v[2:3]
	v_mad_i64_i32 v[62:63], s[34:35], v62, s74, v[2:3]
	v_mad_i64_i32 v[64:65], s[34:35], v64, s74, v[2:3]
	v_mad_i64_i32 v[66:67], s[34:35], v66, s74, v[2:3]
	v_mad_i64_i32 v[68:69], s[34:35], v68, s74, v[2:3]
	v_mad_i64_i32 v[70:71], s[34:35], v70, s74, v[2:3]
	global_load_dword v85, v[4:5], off nt
	global_load_dword v86, v[6:7], off nt
	global_load_dword v87, v[8:9], off nt
	global_load_dword v88, v[46:47], off nt
	global_load_dword v89, v[48:49], off nt
	global_load_dword v90, v[50:51], off nt
	global_load_dword v91, v[52:53], off nt
	global_load_dword v92, v[54:55], off nt
	global_load_dword v93, v[56:57], off nt
	global_load_dword v94, v[58:59], off nt
	global_load_dword v95, v[60:61], off nt
	global_load_dword v96, v[62:63], off nt
	global_load_dword v97, v[64:65], off nt
	global_load_dword v98, v[66:67], off nt
	global_load_dword v99, v[68:69], off nt
	global_load_dword v100, v[70:71], off nt
	v_mad_u64_u32 v[102:103], s[34:35], v134, s81, v[12:13]
	v_mad_u64_u32 v[104:105], s[34:35], v101, s81, v[12:13]
	v_mad_u64_u32 v[106:107], s[34:35], v136, s81, v[12:13]
	v_mad_u64_u32 v[108:109], s[34:35], v135, s81, v[12:13]
	v_mad_u64_u32 v[110:111], s[34:35], v138, s81, v[12:13]
	v_mad_u64_u32 v[112:113], s[34:35], v137, s81, v[12:13]
	v_mad_u64_u32 v[114:115], s[34:35], v140, s81, v[12:13]
	v_mad_u64_u32 v[116:117], s[34:35], v139, s81, v[12:13]
	v_mad_u64_u32 v[118:119], s[34:35], v142, s81, v[12:13]
	v_mad_u64_u32 v[120:121], s[34:35], v141, s81, v[12:13]
	v_mad_u64_u32 v[122:123], s[34:35], v144, s81, v[12:13]
	v_mad_u64_u32 v[124:125], s[34:35], v143, s81, v[12:13]
	v_mad_u64_u32 v[126:127], s[34:35], v146, s81, v[12:13]
	v_mad_u64_u32 v[128:129], s[34:35], v145, s81, v[12:13]
	v_mad_u64_u32 v[130:131], s[34:35], v148, s81, v[12:13]
	v_mad_u64_u32 v[132:133], s[34:35], v147, s81, v[12:13]
	s_waitcnt vmcnt(31)
; #define GAS __attribute__((address_space(1)))
; __device__ __forceinline__ void cvt_item(gfp W, int N, bf16* WT, int Kd, int k0, int n0, int drow0, LAS float* scr, int lane, gfp gk) {
;     ...
;     for (int i = 0; i < 32; ++i) { const int kk = 2 * i + (lane >> 5); scr[kk * 33 + (lane & 31)] = W[(size_t)(k0 + kk) * N + n0 + (lane & 31)]; }
;     const int c = lane & 7;
;     f32x4 ga = (f32x4){1.f, 1.f, 1.f, 1.f}, gb = ga;
;     if (gk != nullptr) { ga = *(const GAS f32x4*)(gk + k0 + 8 * c); gb = *(const GAS f32x4*)(gk + k0 + 8 * c + 4); }
	ds_write_b32 v102, v149
	s_waitcnt vmcnt(30)
	ds_write_b32 v104, v150
	s_waitcnt vmcnt(29)
	ds_write_b32 v106, v151
	s_waitcnt vmcnt(28)
	ds_write_b32 v108, v152
	s_waitcnt vmcnt(27)
	ds_write_b32 v110, v153
	s_waitcnt vmcnt(26)
	ds_write_b32 v112, v154
	s_waitcnt vmcnt(25)
	ds_write_b32 v114, v155
	s_waitcnt vmcnt(24)
	ds_write_b32 v116, v156
	s_waitcnt vmcnt(23)
	ds_write_b32 v118, v157
	s_waitcnt vmcnt(22)
	ds_write_b32 v120, v158
	s_waitcnt vmcnt(21)
	ds_write_b32 v122, v159
	s_waitcnt vmcnt(20)
	ds_write_b32 v124, v160
	s_waitcnt vmcnt(19)
	ds_write_b32 v126, v161
	s_waitcnt vmcnt(18)
	ds_write_b32 v128, v162
	s_waitcnt vmcnt(17)
	ds_write_b32 v130, v163
	s_waitcnt vmcnt(16)
	ds_write_b32 v132, v164
	v_mad_u64_u32 v[4:5], s[34:35], v39, s81, v[12:13]
	v_mad_u64_u32 v[6:7], s[34:35], v0, s81, v[12:13]
	v_mad_u64_u32 v[8:9], s[34:35], v72, s81, v[12:13]
	v_mad_u64_u32 v[46:47], s[34:35], v45, s81, v[12:13]
	v_mad_u64_u32 v[48:49], s[34:35], v74, s81, v[12:13]
	v_mad_u64_u32 v[50:51], s[34:35], v73, s81, v[12:13]
	v_mad_u64_u32 v[52:53], s[34:35], v76, s81, v[12:13]
	v_mad_u64_u32 v[54:55], s[34:35], v75, s81, v[12:13]
	v_mad_u64_u32 v[56:57], s[34:35], v78, s81, v[12:13]
	v_mad_u64_u32 v[58:59], s[34:35], v77, s81, v[12:13]
	v_mad_u64_u32 v[60:61], s[34:35], v80, s81, v[12:13]
	v_mad_u64_u32 v[62:63], s[34:35], v79, s81, v[12:13]
	v_mad_u64_u32 v[64:65], s[34:35], v82, s81, v[12:13]
	v_mad_u64_u32 v[66:67], s[34:35], v81, s81, v[12:13]
	v_mad_u64_u32 v[68:69], s[34:35], v84, s81, v[12:13]
	v_mad_u64_u32 v[70:71], s[34:35], v83, s81, v[12:13]
	s_waitcnt vmcnt(15)
	ds_write_b32 v4, v85
	s_waitcnt vmcnt(14)
	ds_write_b32 v6, v86
	s_waitcnt vmcnt(13)
	ds_write_b32 v8, v87
	s_waitcnt vmcnt(12)
	ds_write_b32 v46, v88
	s_waitcnt vmcnt(11)
	ds_write_b32 v48, v89
	s_waitcnt vmcnt(10)
	ds_write_b32 v50, v90
	s_waitcnt vmcnt(9)
	ds_write_b32 v52, v91
	s_waitcnt vmcnt(8)
	ds_write_b32 v54, v92
	s_waitcnt vmcnt(7)
	ds_write_b32 v56, v93
	s_waitcnt vmcnt(6)
	ds_write_b32 v58, v94
	s_waitcnt vmcnt(5)
	ds_write_b32 v60, v95
	s_waitcnt vmcnt(4)
	ds_write_b32 v62, v96
	s_waitcnt vmcnt(3)
	ds_write_b32 v64, v97
	s_waitcnt vmcnt(2)
	ds_write_b32 v66, v98
	s_waitcnt vmcnt(1)
	ds_write_b32 v68, v99
	s_waitcnt vmcnt(0)
	ds_write_b32 v70, v100
	s_add_i32 s30, s30, 16
	s_add_i32 s26, s26, 16
	s_add_i32 s31, s31, -16
	s_cmp_lg_u32 s31, 0
	s_lshl_b64 s[30:31], s[8:9], 2
	s_add_u32 s26, s23, s30
	s_addc_u32 s27, s27, s31
	s_ashr_i32 s23, s22, 31
	s_cmp_eq_u64 s[26:27], 0
	s_cbranch_scc0 .LBB0_107
	v_mov_b32_e32 v2, 1.0
	v_mov_b32_e32 v3, 1.0
	v_mov_b32_e32 v4, 1.0
	v_mov_b32_e32 v5, 1.0
	v_mov_b32_e32 v6, 1.0
	v_mov_b32_e32 v7, 1.0
	v_mov_b32_e32 v8, 1.0
	v_mov_b32_e32 v9, 1.0
	s_branch .LBB0_108
